# speedup vs baseline: 1.0093x; 1.0093x over previous
; DI unsigned cvt_pk_bf16(float lo, float hi) { unsigned r; asm volatile("v_cvt_pk_bf16_f32 %0, %1, %2" : "=v"(r) : "v"(lo), "v"(hi)); return r; }
; DI void sample_fix(const float* base, float* hs, bf16_t* Uo, int ldo, float* ss, const float* PARTp, int S, float sc) {
;     const int lane = threadIdx.x & 63, gw = blockIdx.x * 8 + (threadIdx.x >> 6);
;     if (gw < RS) {
;         const float* pr = PARTp + (size_t)gw * DM + lane * 4; float q = 0.f;
; #pragma unroll
;         for (int i = 0; i < 8; ++i) {
;             f32x4 a = {0.f, 0.f, 0.f, 0.f};
;             for (int ks = 0; ks < S; ++ks) a += *(const f32x4*)(pr + (size_t)ks * 256 * DM + i * 256);
;             const f32x4 v = *(const f32x4*)(base + (size_t)gw * DM + i * 256 + lane * 4) + a * sc;
;             *(f32x4*)(hs + (size_t)gw * DM + i * 256 + lane * 4) = v;
;             u32x2 w; w.x = cvt_pk_bf16(v[0], v[1]); w.y = cvt_pk_bf16(v[2], v[3]); *(u32x2*)(Uo + (size_t)(RP + gw) * ldo + i * 256 + lane * 4) = w;
;             q += v[0] * v[0] + v[1] * v[1] + v[2] * v[2] + v[3] * v[3];
;         }
;         q = wave_sum(q); if (lane == 0) ss[RP + gw] = q;
;     }
; }
.LBB0_451:
	v_lshrrev_b32_e32 v0, 6, v184
	s_add_u32 s8, s22, 0x122400
	v_lshl_add_u32 v24, s2, 3, v0
	s_movk_i32 s0, 0x100
	s_addc_u32 s9, s23, 0
	v_cmp_gt_i32_e32 vcc, s0, v24
	s_and_saveexec_b64 s[10:11], vcc
	s_cbranch_execz .LBB0_454
	v_ashrrev_i32_e32 v25, 31, v24
	v_lshlrev_b64 v[10:11], 13, v[24:25]
	v_lshl_add_u64 v[0:1], s[22:23], 0, v[10:11]
	v_lshlrev_b32_e32 v14, 4, v186
	v_mov_b32_e32 v15, 0
	v_lshl_add_u64 v[4:5], v[0:1], 0, v[14:15]
	s_mov_b32 s0, 0x3c40c000
	v_add_co_u32_e32 v26, vcc, s0, v4
	s_mov_b32 s0, 0x3c60c000
	s_nop 0
	v_addc_co_u32_e32 v27, vcc, 0, v5, vcc
	v_add_co_u32_e32 v28, vcc, s0, v4
	s_mov_b32 s0, 0x3c80c000
	s_nop 0
	v_addc_co_u32_e32 v29, vcc, 0, v5, vcc
	v_add_co_u32_e32 v30, vcc, s0, v4
	s_mov_b32 s0, 0x3ca0c000
	s_nop 0
	v_addc_co_u32_e32 v31, vcc, 0, v5, vcc
	global_load_dwordx4 v[0:3], v[26:27], off offset:-4096
	global_load_dwordx4 v[6:9], v[28:29], off offset:-4096
	v_add_co_u32_e32 v32, vcc, s0, v4
	s_mov_b32 s0, 0x3cc0c000
	s_nop 0
	v_addc_co_u32_e32 v33, vcc, 0, v5, vcc
	global_load_dwordx4 v[20:23], v[30:31], off offset:-4096
	global_load_dwordx4 v[50:53], v[32:33], off offset:-4096
	v_add_co_u32_e32 v34, vcc, s0, v4
	s_mov_b32 s0, 0x3ce0c000
	s_nop 0
	v_addc_co_u32_e32 v35, vcc, 0, v5, vcc
	v_add_co_u32_e32 v36, vcc, s0, v4
	s_mov_b32 s0, 0x3d00c000
	s_nop 0
	v_addc_co_u32_e32 v37, vcc, 0, v5, vcc
	global_load_dwordx4 v[54:57], v[34:35], off offset:-4096
	global_load_dwordx4 v[58:61], v[36:37], off offset:-4096
	v_add_co_u32_e32 v40, vcc, s0, v4
	s_mov_b32 s0, 0x3d20c000
	s_nop 0
	v_addc_co_u32_e32 v41, vcc, 0, v5, vcc
	v_add_co_u32_e32 v42, vcc, s0, v4
	s_mov_b32 s0, 0x3d40c000
	s_nop 0
	v_addc_co_u32_e32 v43, vcc, 0, v5, vcc
	v_add_co_u32_e32 v44, vcc, s0, v4
	s_mov_b32 s0, 0x3d60c000
	s_nop 0
	v_addc_co_u32_e32 v45, vcc, 0, v5, vcc
	v_add_co_u32_e32 v46, vcc, s0, v4
	global_load_dwordx4 v[62:65], v[40:41], off offset:-4096
	global_load_dwordx4 v[66:69], v[42:43], off offset:-4096
	v_addc_co_u32_e32 v47, vcc, 0, v5, vcc
	s_mov_b32 s0, 0x3d80c000
	v_add_co_u32_e32 v48, vcc, s0, v4
	v_lshl_add_u64 v[12:13], s[30:31], 0, v[10:11]
	global_load_dwordx4 v[70:73], v[44:45], off offset:-4096
	global_load_dwordx4 v[74:77], v[46:47], off offset:-4096
	v_addc_co_u32_e32 v49, vcc, 0, v5, vcc
	global_load_dwordx4 v[78:81], v[48:49], off offset:-4096
	v_lshl_add_u64 v[16:17], v[12:13], 0, v[14:15]
	global_load_dwordx4 v[82:85], v[16:17], off
	s_mov_b64 s[0:1], 0x3c40b000
	v_lshlrev_b64 v[12:13], 12, v[24:25]
	v_lshl_add_u64 v[10:11], s[20:21], 0, v[10:11]
	v_lshl_add_u64 v[18:19], s[22:23], 0, v[12:13]
	v_lshl_add_u64 v[10:11], v[10:11], 0, v[14:15]
	v_lshlrev_b32_e32 v14, 3, v186
	v_lshl_add_u64 v[12:13], v[4:5], 0, s[0:1]
	s_mov_b32 s0, 0x3c60b000
	v_lshl_add_u64 v[108:109], v[18:19], 0, v[14:15]
	v_add_co_u32_e32 v14, vcc, s0, v4
	s_mov_b32 s0, 0x3c80b000
	s_nop 0
	v_addc_co_u32_e32 v15, vcc, 0, v5, vcc
	v_add_co_u32_e32 v18, vcc, s0, v4
	s_mov_b32 s0, 0x3ca0b000
	s_nop 0
	v_addc_co_u32_e32 v19, vcc, 0, v5, vcc
	s_waitcnt vmcnt(0)
	v_pk_add_f32 v[0:1], v[0:1], 0 op_sel_hi:[1,0]
	s_nop 0
	v_pk_add_f32 v[0:1], v[0:1], v[6:7]
	v_pk_add_f32 v[2:3], v[2:3], 0 op_sel_hi:[1,0]
	v_pk_add_f32 v[0:1], v[0:1], v[20:21]
	v_add_co_u32_e32 v20, vcc, s0, v4
	v_pk_add_f32 v[2:3], v[2:3], v[8:9]
	s_nop 0
	v_addc_co_u32_e32 v21, vcc, 0, v5, vcc
	s_mov_b32 s0, 0x3cc0b000
	v_pk_add_f32 v[2:3], v[2:3], v[22:23]
	v_add_co_u32_e32 v22, vcc, s0, v4
	v_pk_add_f32 v[0:1], v[0:1], v[50:51]
	s_nop 0
	v_addc_co_u32_e32 v23, vcc, 0, v5, vcc
	s_mov_b32 s0, 0x3ce0b000
	v_pk_add_f32 v[0:1], v[0:1], v[54:55]
	v_add_co_u32_e32 v54, vcc, s0, v4
	s_mov_b32 s0, 0x3d00b000
	s_nop 0
	v_addc_co_u32_e32 v55, vcc, 0, v5, vcc
	v_pk_add_f32 v[2:3], v[2:3], v[52:53]
	v_add_co_u32_e32 v52, vcc, s0, v4
	s_mov_b32 s0, 0x3d20b000
	s_nop 0
	v_addc_co_u32_e32 v53, vcc, 0, v5, vcc
	v_pk_add_f32 v[2:3], v[2:3], v[56:57]
	v_add_co_u32_e32 v56, vcc, s0, v4
	v_pk_add_f32 v[2:3], v[2:3], v[60:61]
	v_pk_add_f32 v[0:1], v[0:1], v[58:59]
	v_addc_co_u32_e32 v57, vcc, 0, v5, vcc
	s_mov_b32 s0, 0x3d40b000
	v_pk_add_f32 v[2:3], v[2:3], v[64:65]
	v_pk_add_f32 v[0:1], v[0:1], v[62:63]
	v_add_co_u32_e32 v58, vcc, s0, v4
	v_pk_add_f32 v[2:3], v[2:3], v[68:69]
	v_pk_add_f32 v[0:1], v[0:1], v[66:67]
	v_addc_co_u32_e32 v59, vcc, 0, v5, vcc
	s_mov_b32 s0, 0x10001000
	v_pk_add_f32 v[2:3], v[2:3], v[72:73]
	v_pk_add_f32 v[0:1], v[0:1], v[70:71]
	v_add_co_u32_e32 v38, vcc, s0, v10
	v_pk_add_f32 v[2:3], v[2:3], v[76:77]
	v_pk_add_f32 v[0:1], v[0:1], v[74:75]
	v_addc_co_u32_e32 v39, vcc, 0, v11, vcc
	s_mov_b32 s0, 0x106c3000
	v_pk_add_f32 v[2:3], v[2:3], v[80:81]
	v_pk_add_f32 v[0:1], v[0:1], v[78:79]
	v_add_co_u32_e32 v8, vcc, s0, v108
	v_pk_fma_f32 v[2:3], v[2:3], 0.5, v[84:85] op_sel_hi:[1,0,1]
	v_pk_fma_f32 v[0:1], v[0:1], 0.5, v[82:83] op_sel_hi:[1,0,1]
	v_addc_co_u32_e32 v9, vcc, 0, v109, vcc
	global_store_dwordx4 v[38:39], v[0:3], off offset:-4096
	v_cvt_pk_bf16_f32 v6, v0, v1
	v_cvt_pk_bf16_f32 v7, v2, v3
	global_store_dwordx2 v[8:9], v[6:7], off
	global_load_dwordx4 v[6:9], v[12:13], off offset:1024
	s_nop 0
	global_load_dwordx4 v[64:67], v[14:15], off offset:1024
	global_load_dwordx4 v[68:71], v[18:19], off offset:1024
	global_load_dwordx4 v[72:75], v[20:21], off offset:1024
	global_load_dwordx4 v[76:79], v[22:23], off offset:1024
	global_load_dwordx4 v[80:83], v[54:55], off offset:1024
	s_mov_b32 s0, 0x3d60b000
	v_add_co_u32_e32 v60, vcc, s0, v4
	s_mov_b32 s0, 0x3d80b000
	s_nop 0
	v_addc_co_u32_e32 v61, vcc, 0, v5, vcc
	global_load_dwordx4 v[84:87], v[52:53], off offset:1024
	global_load_dwordx4 v[88:91], v[56:57], off offset:1024
	global_load_dwordx4 v[92:95], v[58:59], off offset:1024
	global_load_dwordx4 v[96:99], v[60:61], off offset:1024
	v_add_co_u32_e32 v112, vcc, s0, v4
	s_mov_b64 s[0:1], 0x10000000
	s_nop 0
	v_addc_co_u32_e32 v113, vcc, 0, v5, vcc
	global_load_dwordx4 v[100:103], v[112:113], off offset:1024
	global_load_dwordx4 v[104:107], v[16:17], off offset:1024
	v_lshl_add_u64 v[62:63], v[10:11], 0, s[0:1]
	s_mov_b64 s[0:1], 0x106c3000
	v_lshl_add_u64 v[50:51], v[108:109], 0, s[0:1]
	s_movk_i32 s0, 0x1000
	v_mul_f32_e32 v1, v1, v1
	v_fmac_f32_e32 v1, v0, v0
	v_fmac_f32_e32 v1, v2, v2
	v_fmac_f32_e32 v1, v3, v3
	s_waitcnt vmcnt(11)
; DI unsigned cvt_pk_bf16(float lo, float hi) { unsigned r; asm volatile("v_cvt_pk_bf16_f32 %0, %1, %2" : "=v"(r) : "v"(lo), "v"(hi)); return r; }
; DI void sample_fix(const float* base, float* hs, bf16_t* Uo, int ldo, float* ss, const float* PARTp, int S, float sc) {
;     const int lane = threadIdx.x & 63, gw = blockIdx.x * 8 + (threadIdx.x >> 6);
;     if (gw < RS) {
;         const float* pr = PARTp + (size_t)gw * DM + lane * 4; float q = 0.f;
; #pragma unroll
;         for (int i = 0; i < 8; ++i) {
;             f32x4 a = {0.f, 0.f, 0.f, 0.f};
;             for (int ks = 0; ks < S; ++ks) a += *(const f32x4*)(pr + (size_t)ks * 256 * DM + i * 256);
;             const f32x4 v = *(const f32x4*)(base + (size_t)gw * DM + i * 256 + lane * 4) + a * sc;
;             *(f32x4*)(hs + (size_t)gw * DM + i * 256 + lane * 4) = v;
;             u32x2 w; w.x = cvt_pk_bf16(v[0], v[1]); w.y = cvt_pk_bf16(v[2], v[3]); *(u32x2*)(Uo + (size_t)(RP + gw) * ldo + i * 256 + lane * 4) = w;
;             q += v[0] * v[0] + v[1] * v[1] + v[2] * v[2] + v[3] * v[3];
;         }
;         q = wave_sum(q); if (lane == 0) ss[RP + gw] = q;
;     }
; }
	v_pk_add_f32 v[4:5], v[8:9], 0 op_sel_hi:[1,0]
	v_pk_add_f32 v[6:7], v[6:7], 0 op_sel_hi:[1,0]
	s_waitcnt vmcnt(10)
	v_pk_add_f32 v[4:5], v[4:5], v[66:67]
	v_pk_add_f32 v[6:7], v[6:7], v[64:65]
	s_waitcnt vmcnt(9)
	v_pk_add_f32 v[4:5], v[4:5], v[70:71]
	v_pk_add_f32 v[6:7], v[6:7], v[68:69]
	s_waitcnt vmcnt(8)
	v_pk_add_f32 v[4:5], v[4:5], v[74:75]
	v_pk_add_f32 v[6:7], v[6:7], v[72:73]
	s_waitcnt vmcnt(7)
	v_pk_add_f32 v[4:5], v[4:5], v[78:79]
	v_pk_add_f32 v[6:7], v[6:7], v[76:77]
	s_waitcnt vmcnt(6)
	v_pk_add_f32 v[4:5], v[4:5], v[82:83]
	v_pk_add_f32 v[6:7], v[6:7], v[80:81]
	s_waitcnt vmcnt(5)
	v_pk_add_f32 v[4:5], v[4:5], v[86:87]
	v_pk_add_f32 v[6:7], v[6:7], v[84:85]
	s_waitcnt vmcnt(4)
	v_pk_add_f32 v[4:5], v[4:5], v[90:91]
	v_pk_add_f32 v[6:7], v[6:7], v[88:89]
	s_waitcnt vmcnt(3)
	v_pk_add_f32 v[4:5], v[4:5], v[94:95]
	v_pk_add_f32 v[6:7], v[6:7], v[92:93]
	s_waitcnt vmcnt(2)
	v_pk_add_f32 v[4:5], v[4:5], v[98:99]
	v_pk_add_f32 v[6:7], v[6:7], v[96:97]
	s_waitcnt vmcnt(1)
	v_pk_add_f32 v[4:5], v[4:5], v[102:103]
	v_pk_add_f32 v[8:9], v[6:7], v[100:101]
	s_waitcnt vmcnt(0)
	v_pk_fma_f32 v[6:7], v[4:5], 0.5, v[106:107] op_sel_hi:[1,0,1]
	v_pk_fma_f32 v[4:5], v[8:9], 0.5, v[104:105] op_sel_hi:[1,0,1]
	global_store_dwordx4 v[62:63], v[4:7], off offset:1024
	v_cvt_pk_bf16_f32 v8, v4, v5
	v_cvt_pk_bf16_f32 v9, v6, v7
	global_store_dwordx2 v[50:51], v[8:9], off offset:512
	global_load_dwordx4 v[8:11], v[12:13], off offset:2048
	s_nop 0
	global_load_dwordx4 v[64:67], v[14:15], off offset:2048
	global_load_dwordx4 v[68:71], v[18:19], off offset:2048
	global_load_dwordx4 v[72:75], v[20:21], off offset:2048
	global_load_dwordx4 v[76:79], v[22:23], off offset:2048
	global_load_dwordx4 v[80:83], v[54:55], off offset:2048
	global_load_dwordx4 v[84:87], v[52:53], off offset:2048
	global_load_dwordx4 v[88:91], v[56:57], off offset:2048
	global_load_dwordx4 v[92:95], v[58:59], off offset:2048
	global_load_dwordx4 v[96:99], v[60:61], off offset:2048
	global_load_dwordx4 v[100:103], v[112:113], off offset:2048
	global_load_dwordx4 v[104:107], v[16:17], off offset:2048
	v_mul_f32_e32 v0, v5, v5
	v_fmac_f32_e32 v0, v4, v4
	v_fmac_f32_e32 v0, v6, v6
	v_fmac_f32_e32 v0, v7, v7
	v_add_f32_e32 v0, v1, v0
	s_waitcnt vmcnt(11)
	v_pk_add_f32 v[10:11], v[10:11], 0 op_sel_hi:[1,0]
	v_pk_add_f32 v[8:9], v[8:9], 0 op_sel_hi:[1,0]
	s_waitcnt vmcnt(10)
	v_pk_add_f32 v[10:11], v[10:11], v[66:67]
	v_pk_add_f32 v[8:9], v[8:9], v[64:65]
	s_waitcnt vmcnt(9)
	v_pk_add_f32 v[10:11], v[10:11], v[70:71]
	v_pk_add_f32 v[8:9], v[8:9], v[68:69]
	s_waitcnt vmcnt(8)
	v_pk_add_f32 v[10:11], v[10:11], v[74:75]
	v_pk_add_f32 v[8:9], v[8:9], v[72:73]
	s_waitcnt vmcnt(7)
	v_pk_add_f32 v[10:11], v[10:11], v[78:79]
	v_pk_add_f32 v[8:9], v[8:9], v[76:77]
	s_waitcnt vmcnt(6)
	v_pk_add_f32 v[10:11], v[10:11], v[82:83]
	v_pk_add_f32 v[8:9], v[8:9], v[80:81]
	s_waitcnt vmcnt(5)
	v_pk_add_f32 v[10:11], v[10:11], v[86:87]
	v_pk_add_f32 v[8:9], v[8:9], v[84:85]
	s_waitcnt vmcnt(4)
	v_pk_add_f32 v[10:11], v[10:11], v[90:91]
	v_pk_add_f32 v[8:9], v[8:9], v[88:89]
	s_waitcnt vmcnt(3)
	v_pk_add_f32 v[10:11], v[10:11], v[94:95]
	v_pk_add_f32 v[8:9], v[8:9], v[92:93]
	s_waitcnt vmcnt(2)
	v_pk_add_f32 v[10:11], v[10:11], v[98:99]
	v_pk_add_f32 v[8:9], v[8:9], v[96:97]
	s_waitcnt vmcnt(1)
	v_pk_add_f32 v[10:11], v[10:11], v[102:103]
	v_pk_add_f32 v[8:9], v[8:9], v[100:101]
	s_waitcnt vmcnt(0)
	v_pk_fma_f32 v[10:11], v[10:11], 0.5, v[106:107] op_sel_hi:[1,0,1]
	v_pk_fma_f32 v[8:9], v[8:9], 0.5, v[104:105] op_sel_hi:[1,0,1]
	global_store_dwordx4 v[62:63], v[8:11], off offset:2048
	v_cvt_pk_bf16_f32 v64, v8, v9
	v_cvt_pk_bf16_f32 v65, v10, v11
	global_store_dwordx2 v[50:51], v[64:65], off offset:1024
	global_load_dwordx4 v[64:67], v[12:13], off offset:3072
	s_nop 0
	global_load_dwordx4 v[68:71], v[14:15], off offset:3072
	global_load_dwordx4 v[72:75], v[18:19], off offset:3072
	global_load_dwordx4 v[76:79], v[20:21], off offset:3072
	global_load_dwordx4 v[80:83], v[22:23], off offset:3072
	global_load_dwordx4 v[84:87], v[54:55], off offset:3072
	global_load_dwordx4 v[88:91], v[52:53], off offset:3072
	global_load_dwordx4 v[92:95], v[56:57], off offset:3072
	global_load_dwordx4 v[96:99], v[58:59], off offset:3072
	global_load_dwordx4 v[100:103], v[60:61], off offset:3072
	global_load_dwordx4 v[104:107], v[112:113], off offset:3072
	global_load_dwordx4 v[108:111], v[16:17], off offset:3072
	v_add_co_u32_e32 v52, vcc, s0, v16
	v_mul_f32_e32 v1, v9, v9
	s_nop 0
	v_addc_co_u32_e32 v53, vcc, 0, v17, vcc
	v_fmac_f32_e32 v1, v8, v8
	v_fmac_f32_e32 v1, v10, v10
	v_fmac_f32_e32 v1, v11, v11
	v_add_f32_e32 v0, v0, v1
	s_waitcnt vmcnt(11)
	v_pk_add_f32 v[12:13], v[66:67], 0 op_sel_hi:[1,0]
	v_pk_add_f32 v[14:15], v[64:65], 0 op_sel_hi:[1,0]
	s_waitcnt vmcnt(10)
	v_pk_add_f32 v[12:13], v[12:13], v[70:71]
	v_pk_add_f32 v[14:15], v[14:15], v[68:69]
	s_waitcnt vmcnt(9)
	v_pk_add_f32 v[12:13], v[12:13], v[74:75]
	v_pk_add_f32 v[14:15], v[14:15], v[72:73]
	s_waitcnt vmcnt(8)
	v_pk_add_f32 v[12:13], v[12:13], v[78:79]
	v_pk_add_f32 v[14:15], v[14:15], v[76:77]
	s_waitcnt vmcnt(7)
	v_pk_add_f32 v[12:13], v[12:13], v[82:83]
	v_pk_add_f32 v[14:15], v[14:15], v[80:81]
	s_waitcnt vmcnt(6)
	v_pk_add_f32 v[12:13], v[12:13], v[86:87]
	v_pk_add_f32 v[14:15], v[14:15], v[84:85]
	s_waitcnt vmcnt(5)
	v_pk_add_f32 v[12:13], v[12:13], v[90:91]
	v_pk_add_f32 v[14:15], v[14:15], v[88:89]
	s_waitcnt vmcnt(4)
	v_pk_add_f32 v[12:13], v[12:13], v[94:95]
	v_pk_add_f32 v[14:15], v[14:15], v[92:93]
	s_waitcnt vmcnt(3)
	v_pk_add_f32 v[12:13], v[12:13], v[98:99]
	v_pk_add_f32 v[14:15], v[14:15], v[96:97]
	s_waitcnt vmcnt(2)
; DI unsigned cvt_pk_bf16(float lo, float hi) { unsigned r; asm volatile("v_cvt_pk_bf16_f32 %0, %1, %2" : "=v"(r) : "v"(lo), "v"(hi)); return r; }
; DI void sample_fix(const float* base, float* hs, bf16_t* Uo, int ldo, float* ss, const float* PARTp, int S, float sc) {
;     const int lane = threadIdx.x & 63, gw = blockIdx.x * 8 + (threadIdx.x >> 6);
;     if (gw < RS) {
;         const float* pr = PARTp + (size_t)gw * DM + lane * 4; float q = 0.f;
; #pragma unroll
;         for (int i = 0; i < 8; ++i) {
;             f32x4 a = {0.f, 0.f, 0.f, 0.f};
;             for (int ks = 0; ks < S; ++ks) a += *(const f32x4*)(pr + (size_t)ks * 256 * DM + i * 256);
;             const f32x4 v = *(const f32x4*)(base + (size_t)gw * DM + i * 256 + lane * 4) + a * sc;
;             *(f32x4*)(hs + (size_t)gw * DM + i * 256 + lane * 4) = v;
;             u32x2 w; w.x = cvt_pk_bf16(v[0], v[1]); w.y = cvt_pk_bf16(v[2], v[3]); *(u32x2*)(Uo + (size_t)(RP + gw) * ldo + i * 256 + lane * 4) = w;
;             q += v[0] * v[0] + v[1] * v[1] + v[2] * v[2] + v[3] * v[3];
;         }
;         q = wave_sum(q); if (lane == 0) ss[RP + gw] = q;
;     }
; }
	v_pk_add_f32 v[12:13], v[12:13], v[102:103]
	v_pk_add_f32 v[14:15], v[14:15], v[100:101]
	s_waitcnt vmcnt(1)
	v_pk_add_f32 v[12:13], v[12:13], v[106:107]
	v_pk_add_f32 v[18:19], v[14:15], v[104:105]
	s_waitcnt vmcnt(0)
	v_pk_fma_f32 v[14:15], v[12:13], 0.5, v[110:111] op_sel_hi:[1,0,1]
	v_pk_fma_f32 v[12:13], v[18:19], 0.5, v[108:109] op_sel_hi:[1,0,1]
	global_store_dwordx4 v[62:63], v[12:15], off offset:3072
	v_cvt_pk_bf16_f32 v18, v12, v13
	v_cvt_pk_bf16_f32 v19, v14, v15
	global_store_dwordx2 v[50:51], v[18:19], off offset:1536
	global_load_dwordx4 v[18:21], v[26:27], off
	s_nop 0
	global_load_dwordx4 v[54:57], v[28:29], off
	global_load_dwordx4 v[58:61], v[30:31], off
	global_load_dwordx4 v[62:65], v[32:33], off
	global_load_dwordx4 v[66:69], v[34:35], off
	global_load_dwordx4 v[70:73], v[36:37], off
	global_load_dwordx4 v[74:77], v[40:41], off
	global_load_dwordx4 v[78:81], v[42:43], off
	global_load_dwordx4 v[82:85], v[44:45], off
	global_load_dwordx4 v[86:89], v[46:47], off
	global_load_dwordx4 v[90:93], v[48:49], off
	global_load_dwordx4 v[94:97], v[52:53], off
	v_mul_f32_e32 v1, v13, v13
	v_fmac_f32_e32 v1, v12, v12
	v_fmac_f32_e32 v1, v14, v14
	v_fmac_f32_e32 v1, v15, v15
	v_add_f32_e32 v0, v0, v1
	s_waitcnt vmcnt(11)
	v_pk_add_f32 v[16:17], v[20:21], 0 op_sel_hi:[1,0]
	v_pk_add_f32 v[18:19], v[18:19], 0 op_sel_hi:[1,0]
	s_waitcnt vmcnt(10)
	v_pk_add_f32 v[16:17], v[16:17], v[56:57]
	v_pk_add_f32 v[18:19], v[18:19], v[54:55]
	s_waitcnt vmcnt(9)
	v_pk_add_f32 v[16:17], v[16:17], v[60:61]
	v_pk_add_f32 v[18:19], v[18:19], v[58:59]
	s_waitcnt vmcnt(8)
	v_pk_add_f32 v[16:17], v[16:17], v[64:65]
	v_pk_add_f32 v[18:19], v[18:19], v[62:63]
	s_waitcnt vmcnt(7)
	v_pk_add_f32 v[16:17], v[16:17], v[68:69]
	v_pk_add_f32 v[18:19], v[18:19], v[66:67]
	s_waitcnt vmcnt(6)
	v_pk_add_f32 v[16:17], v[16:17], v[72:73]
	v_pk_add_f32 v[18:19], v[18:19], v[70:71]
	s_waitcnt vmcnt(5)
	v_pk_add_f32 v[16:17], v[16:17], v[76:77]
	v_pk_add_f32 v[18:19], v[18:19], v[74:75]
	s_waitcnt vmcnt(4)
	v_pk_add_f32 v[16:17], v[16:17], v[80:81]
	v_pk_add_f32 v[18:19], v[18:19], v[78:79]
	s_waitcnt vmcnt(3)
	v_pk_add_f32 v[16:17], v[16:17], v[84:85]
	v_pk_add_f32 v[18:19], v[18:19], v[82:83]
	s_waitcnt vmcnt(2)
	v_pk_add_f32 v[16:17], v[16:17], v[88:89]
	v_pk_add_f32 v[18:19], v[18:19], v[86:87]
	s_waitcnt vmcnt(1)
	v_pk_add_f32 v[16:17], v[16:17], v[92:93]
	v_pk_add_f32 v[20:21], v[18:19], v[90:91]
	s_waitcnt vmcnt(0)
	v_pk_fma_f32 v[18:19], v[16:17], 0.5, v[96:97] op_sel_hi:[1,0,1]
	v_pk_fma_f32 v[16:17], v[20:21], 0.5, v[94:95] op_sel_hi:[1,0,1]
	global_store_dwordx4 v[38:39], v[16:19], off
	v_cvt_pk_bf16_f32 v20, v16, v17
	v_cvt_pk_bf16_f32 v21, v18, v19
	global_store_dwordx2 v[50:51], v[20:21], off offset:2048
	global_load_dwordx4 v[20:23], v[26:27], off offset:1024
	s_nop 0
	global_load_dwordx4 v[54:57], v[28:29], off offset:1024
	global_load_dwordx4 v[58:61], v[30:31], off offset:1024
	global_load_dwordx4 v[62:65], v[32:33], off offset:1024
	global_load_dwordx4 v[66:69], v[34:35], off offset:1024
	global_load_dwordx4 v[70:73], v[36:37], off offset:1024
	global_load_dwordx4 v[74:77], v[40:41], off offset:1024
	global_load_dwordx4 v[78:81], v[42:43], off offset:1024
	global_load_dwordx4 v[82:85], v[44:45], off offset:1024
	global_load_dwordx4 v[86:89], v[46:47], off offset:1024
	global_load_dwordx4 v[90:93], v[48:49], off offset:1024
	global_load_dwordx4 v[94:97], v[52:53], off offset:1024
	v_mul_f32_e32 v1, v17, v17
	v_fmac_f32_e32 v1, v16, v16
	v_fmac_f32_e32 v1, v18, v18
	v_fmac_f32_e32 v1, v19, v19
	v_add_f32_e32 v0, v0, v1
	s_waitcnt vmcnt(11)
	v_pk_add_f32 v[22:23], v[22:23], 0 op_sel_hi:[1,0]
	v_pk_add_f32 v[20:21], v[20:21], 0 op_sel_hi:[1,0]
	s_waitcnt vmcnt(10)
	v_pk_add_f32 v[22:23], v[22:23], v[56:57]
	v_pk_add_f32 v[20:21], v[20:21], v[54:55]
	s_waitcnt vmcnt(9)
	v_pk_add_f32 v[22:23], v[22:23], v[60:61]
	v_pk_add_f32 v[20:21], v[20:21], v[58:59]
	s_waitcnt vmcnt(8)
	v_pk_add_f32 v[22:23], v[22:23], v[64:65]
	v_pk_add_f32 v[20:21], v[20:21], v[62:63]
	s_waitcnt vmcnt(7)
	v_pk_add_f32 v[22:23], v[22:23], v[68:69]
	v_pk_add_f32 v[20:21], v[20:21], v[66:67]
	s_waitcnt vmcnt(6)
	v_pk_add_f32 v[22:23], v[22:23], v[72:73]
	v_pk_add_f32 v[20:21], v[20:21], v[70:71]
	s_waitcnt vmcnt(5)
	v_pk_add_f32 v[22:23], v[22:23], v[76:77]
	v_pk_add_f32 v[20:21], v[20:21], v[74:75]
	s_waitcnt vmcnt(4)
	v_pk_add_f32 v[22:23], v[22:23], v[80:81]
	v_pk_add_f32 v[20:21], v[20:21], v[78:79]
	s_waitcnt vmcnt(3)
	v_pk_add_f32 v[22:23], v[22:23], v[84:85]
	v_pk_add_f32 v[20:21], v[20:21], v[82:83]
	s_waitcnt vmcnt(2)
	v_pk_add_f32 v[22:23], v[22:23], v[88:89]
	v_pk_add_f32 v[20:21], v[20:21], v[86:87]
	s_waitcnt vmcnt(1)
	v_pk_add_f32 v[22:23], v[22:23], v[92:93]
	v_pk_add_f32 v[20:21], v[20:21], v[90:91]
	s_waitcnt vmcnt(0)
	v_pk_fma_f32 v[22:23], v[22:23], 0.5, v[96:97] op_sel_hi:[1,0,1]
	v_pk_fma_f32 v[20:21], v[20:21], 0.5, v[94:95] op_sel_hi:[1,0,1]
	global_store_dwordx4 v[38:39], v[20:23], off offset:1024
	v_cvt_pk_bf16_f32 v54, v20, v21
	v_cvt_pk_bf16_f32 v55, v22, v23
	global_store_dwordx2 v[50:51], v[54:55], off offset:2560
	global_load_dwordx4 v[54:57], v[26:27], off offset:2048
	s_nop 0
	global_load_dwordx4 v[58:61], v[28:29], off offset:2048
	global_load_dwordx4 v[62:65], v[30:31], off offset:2048
	global_load_dwordx4 v[66:69], v[32:33], off offset:2048
	global_load_dwordx4 v[70:73], v[34:35], off offset:2048
	global_load_dwordx4 v[74:77], v[36:37], off offset:2048
	global_load_dwordx4 v[78:81], v[40:41], off offset:2048
	global_load_dwordx4 v[82:85], v[42:43], off offset:2048
	global_load_dwordx4 v[86:89], v[44:45], off offset:2048
	global_load_dwordx4 v[90:93], v[46:47], off offset:2048
	global_load_dwordx4 v[94:97], v[48:49], off offset:2048
	global_load_dwordx4 v[98:101], v[52:53], off offset:2048
	v_mul_f32_e32 v1, v21, v21
	v_fmac_f32_e32 v1, v20, v20
	v_fmac_f32_e32 v1, v22, v22
	v_fmac_f32_e32 v1, v23, v23
	v_add_f32_e32 v0, v0, v1
	s_waitcnt vmcnt(11)
; DI unsigned cvt_pk_bf16(float lo, float hi) { unsigned r; asm volatile("v_cvt_pk_bf16_f32 %0, %1, %2" : "=v"(r) : "v"(lo), "v"(hi)); return r; }
; DI float rs_of(const float* ss, int row) { return 1.0f / sqrtf(ss[row] * (1.0f / DM) + EPS); }
; DI void sample_fix(const float* base, float* hs, bf16_t* Uo, int ldo, float* ss, const float* PARTp, int S, float sc) {
;     const int lane = threadIdx.x & 63, gw = blockIdx.x * 8 + (threadIdx.x >> 6);
;     if (gw < RS) {
;         const float* pr = PARTp + (size_t)gw * DM + lane * 4; float q = 0.f;
; #pragma unroll
;         for (int i = 0; i < 8; ++i) {
;             f32x4 a = {0.f, 0.f, 0.f, 0.f};
;             for (int ks = 0; ks < S; ++ks) a += *(const f32x4*)(pr + (size_t)ks * 256 * DM + i * 256);
;             const f32x4 v = *(const f32x4*)(base + (size_t)gw * DM + i * 256 + lane * 4) + a * sc;
;             *(f32x4*)(hs + (size_t)gw * DM + i * 256 + lane * 4) = v;
;             u32x2 w; w.x = cvt_pk_bf16(v[0], v[1]); w.y = cvt_pk_bf16(v[2], v[3]); *(u32x2*)(Uo + (size_t)(RP + gw) * ldo + i * 256 + lane * 4) = w;
;             q += v[0] * v[0] + v[1] * v[1] + v[2] * v[2] + v[3] * v[3];
;         }
;         q = wave_sum(q); if (lane == 0) ss[RP + gw] = q;
;     }
; }
	v_pk_add_f32 v[56:57], v[56:57], 0 op_sel_hi:[1,0]
	v_pk_add_f32 v[54:55], v[54:55], 0 op_sel_hi:[1,0]
	s_waitcnt vmcnt(10)
	v_pk_add_f32 v[56:57], v[56:57], v[60:61]
	v_pk_add_f32 v[54:55], v[54:55], v[58:59]
	s_waitcnt vmcnt(9)
	v_pk_add_f32 v[56:57], v[56:57], v[64:65]
	v_pk_add_f32 v[54:55], v[54:55], v[62:63]
	s_waitcnt vmcnt(8)
	v_pk_add_f32 v[56:57], v[56:57], v[68:69]
	v_pk_add_f32 v[54:55], v[54:55], v[66:67]
	s_waitcnt vmcnt(7)
	v_pk_add_f32 v[56:57], v[56:57], v[72:73]
	v_pk_add_f32 v[54:55], v[54:55], v[70:71]
	s_waitcnt vmcnt(6)
	v_pk_add_f32 v[56:57], v[56:57], v[76:77]
	v_pk_add_f32 v[54:55], v[54:55], v[74:75]
	s_waitcnt vmcnt(5)
	v_pk_add_f32 v[56:57], v[56:57], v[80:81]
	v_pk_add_f32 v[54:55], v[54:55], v[78:79]
	s_waitcnt vmcnt(4)
	v_pk_add_f32 v[56:57], v[56:57], v[84:85]
	v_pk_add_f32 v[54:55], v[54:55], v[82:83]
	s_waitcnt vmcnt(3)
	v_pk_add_f32 v[56:57], v[56:57], v[88:89]
	v_pk_add_f32 v[54:55], v[54:55], v[86:87]
	s_waitcnt vmcnt(2)
	v_pk_add_f32 v[56:57], v[56:57], v[92:93]
	v_pk_add_f32 v[54:55], v[54:55], v[90:91]
	s_waitcnt vmcnt(1)
	v_pk_add_f32 v[56:57], v[56:57], v[96:97]
	v_pk_add_f32 v[54:55], v[54:55], v[94:95]
	s_waitcnt vmcnt(0)
	v_pk_fma_f32 v[56:57], v[56:57], 0.5, v[100:101] op_sel_hi:[1,0,1]
	v_pk_fma_f32 v[54:55], v[54:55], 0.5, v[98:99] op_sel_hi:[1,0,1]
	global_store_dwordx4 v[38:39], v[54:57], off offset:2048
	v_cvt_pk_bf16_f32 v58, v54, v55
	v_cvt_pk_bf16_f32 v59, v56, v57
	global_store_dwordx2 v[50:51], v[58:59], off offset:3072
	global_load_dwordx4 v[58:61], v[26:27], off offset:3072
	s_nop 0
	global_load_dwordx4 v[62:65], v[28:29], off offset:3072
	global_load_dwordx4 v[66:69], v[30:31], off offset:3072
	global_load_dwordx4 v[70:73], v[32:33], off offset:3072
	global_load_dwordx4 v[74:77], v[34:35], off offset:3072
	global_load_dwordx4 v[78:81], v[36:37], off offset:3072
	global_load_dwordx4 v[82:85], v[40:41], off offset:3072
	global_load_dwordx4 v[86:89], v[42:43], off offset:3072
	global_load_dwordx4 v[90:93], v[44:45], off offset:3072
	global_load_dwordx4 v[94:97], v[46:47], off offset:3072
	global_load_dwordx4 v[98:101], v[48:49], off offset:3072
	global_load_dwordx4 v[102:105], v[52:53], off offset:3072
	v_mul_f32_e32 v1, v55, v55
	v_fmac_f32_e32 v1, v54, v54
	v_fmac_f32_e32 v1, v56, v56
	v_fmac_f32_e32 v1, v57, v57
	v_add_f32_e32 v6, v0, v1
	v_mbcnt_lo_u32_b32 v26, -1, 0
	v_mbcnt_hi_u32_b32 v26, -1, v26
	v_and_b32_e32 v27, 64, v26
	v_xor_b32_e32 v28, 32, v26
	v_add_u32_e32 v27, 64, v27
	v_cmp_lt_i32_e32 vcc, v28, v27
	s_waitcnt vmcnt(11)
	v_pk_add_f32 v[2:3], v[58:59], 0 op_sel_hi:[1,0]
	v_pk_add_f32 v[0:1], v[60:61], 0 op_sel_hi:[1,0]
	s_waitcnt vmcnt(10)
	v_pk_add_f32 v[2:3], v[2:3], v[62:63]
	v_pk_add_f32 v[0:1], v[0:1], v[64:65]
	s_waitcnt vmcnt(9)
	v_pk_add_f32 v[2:3], v[2:3], v[66:67]
	v_pk_add_f32 v[0:1], v[0:1], v[68:69]
	s_waitcnt vmcnt(8)
	v_pk_add_f32 v[2:3], v[2:3], v[70:71]
	v_pk_add_f32 v[0:1], v[0:1], v[72:73]
	s_waitcnt vmcnt(7)
	v_pk_add_f32 v[2:3], v[2:3], v[74:75]
	v_pk_add_f32 v[0:1], v[0:1], v[76:77]
	s_waitcnt vmcnt(6)
	v_pk_add_f32 v[2:3], v[2:3], v[78:79]
	v_pk_add_f32 v[0:1], v[0:1], v[80:81]
	s_waitcnt vmcnt(5)
	v_pk_add_f32 v[2:3], v[2:3], v[82:83]
	v_pk_add_f32 v[0:1], v[0:1], v[84:85]
	s_waitcnt vmcnt(4)
	v_pk_add_f32 v[2:3], v[2:3], v[86:87]
	v_pk_add_f32 v[0:1], v[0:1], v[88:89]
	s_waitcnt vmcnt(3)
	v_pk_add_f32 v[2:3], v[2:3], v[90:91]
	v_pk_add_f32 v[0:1], v[0:1], v[92:93]
	s_waitcnt vmcnt(2)
	v_pk_add_f32 v[2:3], v[2:3], v[94:95]
	v_pk_add_f32 v[0:1], v[0:1], v[96:97]
	s_waitcnt vmcnt(1)
	v_pk_add_f32 v[2:3], v[2:3], v[98:99]
	v_pk_add_f32 v[0:1], v[0:1], v[100:101]
	s_waitcnt vmcnt(0)
	v_pk_fma_f32 v[2:3], v[2:3], 0.5, v[102:103] op_sel_hi:[1,0,1]
	v_pk_fma_f32 v[4:5], v[0:1], 0.5, v[104:105] op_sel_hi:[1,0,1]
	v_mul_f32_e32 v0, v3, v3
	v_fmac_f32_e32 v0, v2, v2
	v_fmac_f32_e32 v0, v4, v4
	v_cndmask_b32_e32 v28, v26, v28, vcc
	v_fmac_f32_e32 v0, v5, v5
	v_lshlrev_b32_e32 v28, 2, v28
	v_add_f32_e32 v0, v6, v0
	ds_bpermute_b32 v1, v28, v0
	v_xor_b32_e32 v6, 16, v26
	v_cmp_lt_i32_e32 vcc, v6, v27
	global_store_dwordx4 v[38:39], v[2:5], off offset:3072
	s_waitcnt lgkmcnt(0)
	v_add_f32_e32 v0, v0, v1
	v_cndmask_b32_e32 v6, v26, v6, vcc
	v_lshlrev_b32_e32 v6, 2, v6
	ds_bpermute_b32 v1, v6, v0
	v_xor_b32_e32 v6, 8, v26
	v_cmp_lt_i32_e32 vcc, v6, v27
	v_cvt_pk_bf16_f32 v2, v2, v3
	v_cvt_pk_bf16_f32 v3, v4, v5
	s_waitcnt lgkmcnt(0)
	v_add_f32_e32 v0, v0, v1
	global_store_dwordx2 v[50:51], v[2:3], off offset:3584
	v_cndmask_b32_e32 v6, v26, v6, vcc
	v_lshlrev_b32_e32 v6, 2, v6
	ds_bpermute_b32 v1, v6, v0
	v_xor_b32_e32 v6, 4, v26
	v_cmp_lt_i32_e32 vcc, v6, v27
	s_waitcnt lgkmcnt(0)
	v_add_f32_e32 v0, v0, v1
	v_cndmask_b32_e32 v6, v26, v6, vcc
	v_lshlrev_b32_e32 v6, 2, v6
	ds_bpermute_b32 v1, v6, v0
	v_xor_b32_e32 v6, 2, v26
	v_cmp_lt_i32_e32 vcc, v6, v27
	s_waitcnt lgkmcnt(0)
	v_add_f32_e32 v0, v0, v1
	v_cndmask_b32_e32 v6, v26, v6, vcc
	v_lshlrev_b32_e32 v6, 2, v6
	ds_bpermute_b32 v1, v6, v0
	v_xor_b32_e32 v6, 1, v26
	v_cmp_lt_i32_e64 s[6:7], v6, v27
	v_cmp_eq_u32_e32 vcc, 0, v186
	s_waitcnt lgkmcnt(0)
	v_add_f32_e32 v0, v0, v1
	v_cndmask_b32_e64 v6, v26, v6, s[6:7]
	v_lshlrev_b32_e32 v1, 2, v6
	ds_bpermute_b32 v1, v1, v0
	s_and_b64 exec, exec, vcc
	s_cbranch_execz .LBB0_454
	v_lshl_add_u64 v[2:3], v[24:25], 2, s[8:9]
	s_waitcnt lgkmcnt(0)
	v_add_f32_e32 v4, v0, v1
	v_add_co_u32_e32 v0, vcc, 0x20000, v2
	s_nop 1
	v_addc_co_u32_e32 v1, vcc, 0, v3, vcc
	v_mov_b32_e32 v230, 0x358637bd
	v_mov_b32_e32 v231, 0x260
	v_fmamk_f32 v224, v4, 0x3a000000, v230
	v_mul_f32_e32 v225, 0x4f800000, v224
	v_cmp_gt_f32_e32 vcc, 0xf800000, v224
	s_nop 1
	v_cndmask_b32_e32 v224, v224, v225, vcc
	v_sqrt_f32_e32 v225, v224
	s_nop 0
	v_add_u32_e32 v226, -1, v225
	v_add_u32_e32 v227, 1, v225
	v_fma_f32 v228, -v226, v225, v224
	v_fma_f32 v229, -v227, v225, v224
	v_cmp_ge_f32_e64 s[46:47], 0, v228
	s_nop 1
	v_cndmask_b32_e64 v225, v225, v226, s[46:47]
	v_cmp_lt_f32_e64 s[46:47], 0, v229
	s_nop 1
	v_cndmask_b32_e64 v225, v225, v227, s[46:47]
	v_mul_f32_e32 v226, 0x37800000, v225
	v_cndmask_b32_e32 v225, v225, v226, vcc
	v_cmp_class_f32_e32 vcc, v224, v231
	s_nop 1
	v_cndmask_b32_e32 v224, v225, v224, vcc
	v_div_scale_f32 v225, s[46:47], v224, v224, 1.0
	v_rcp_f32_e32 v226, v225
	v_div_scale_f32 v227, vcc, 1.0, v224, 1.0
	v_fma_f32 v228, -v225, v226, 1.0
	v_fmac_f32_e32 v226, v228, v226
	v_mul_f32_e32 v228, v227, v226
	v_fma_f32 v229, -v225, v228, v227
	v_fmac_f32_e32 v228, v229, v226
	v_fma_f32 v225, -v225, v228, v227
	v_div_fmas_f32 v225, v225, v226, v228
	v_div_fixup_f32 v4, v225, v224, 1.0
	s_nop 0
	global_store_dword v[0:1], v4, off

; DI float rs_of(const float* ss, int row) { return 1.0f / sqrtf(ss[row] * (1.0f / DM) + EPS); }
; DI void ss_reduce(const float* ssp, float* ss) {
;     for (int row = blockIdx.x * 512 + threadIdx.x; row < RP; row += gridDim.x * 512) {
;         const f32x4* p = (const f32x4*)(ssp + (size_t)row * 32); f32x4 a = p[0];
; #pragma unroll
;         for (int i = 1; i < 8; ++i) a += p[i];
;         ss[row] = (a[0] + a[1]) + (a[2] + a[3]);
;     }
; }
.LBB0_456:
	s_waitcnt lgkmcnt(0)
	v_ashrrev_i32_e32 v1, 31, v0
	v_lshlrev_b64 v[2:3], 7, v[0:1]
	v_lshl_add_u64 v[34:35], s[10:11], 0, v[2:3]
	global_load_dwordx4 v[2:5], v[34:35], off
	global_load_dwordx4 v[6:9], v[34:35], off offset:16
	global_load_dwordx4 v[10:13], v[34:35], off offset:32
	global_load_dwordx4 v[14:17], v[34:35], off offset:48
	global_load_dwordx4 v[18:21], v[34:35], off offset:64
	global_load_dwordx4 v[22:25], v[34:35], off offset:80
	global_load_dwordx4 v[26:29], v[34:35], off offset:96
	global_load_dwordx4 v[30:33], v[34:35], off offset:112
	v_lshl_add_u64 v[34:35], v[0:1], 2, s[8:9]
	v_add_u32_e32 v0, s0, v0
	v_cmp_lt_i32_e32 vcc, s1, v0
	s_or_b64 s[14:15], vcc, s[14:15]
	s_waitcnt vmcnt(0)
	v_pk_add_f32 v[4:5], v[4:5], v[8:9]
	v_pk_add_f32 v[2:3], v[2:3], v[6:7]
	v_pk_add_f32 v[4:5], v[4:5], v[12:13]
	v_pk_add_f32 v[2:3], v[2:3], v[10:11]
	v_pk_add_f32 v[4:5], v[4:5], v[16:17]
	v_pk_add_f32 v[2:3], v[2:3], v[14:15]
	v_pk_add_f32 v[4:5], v[4:5], v[20:21]
	v_pk_add_f32 v[2:3], v[2:3], v[18:19]
	v_pk_add_f32 v[4:5], v[4:5], v[24:25]
	v_pk_add_f32 v[2:3], v[2:3], v[22:23]
	v_pk_add_f32 v[4:5], v[4:5], v[28:29]
	v_pk_add_f32 v[2:3], v[2:3], v[26:27]
	v_pk_add_f32 v[4:5], v[4:5], v[32:33]
	v_pk_add_f32 v[2:3], v[2:3], v[30:31]
	s_nop 0
	v_pk_mov_b32 v[6:7], v[2:3], v[4:5] op_sel:[1,0]
	v_mov_b32_e32 v3, v5
	v_pk_add_f32 v[2:3], v[6:7], v[2:3]
	s_nop 0
	v_add_f32_e32 v1, v2, v3
	v_mov_b32_e32 v230, 0x358637bd
	v_mov_b32_e32 v231, 0x260
	v_fmamk_f32 v224, v1, 0x3a000000, v230
	v_mul_f32_e32 v225, 0x4f800000, v224
	v_cmp_gt_f32_e32 vcc, 0xf800000, v224
	s_nop 1
	v_cndmask_b32_e32 v224, v224, v225, vcc
	v_sqrt_f32_e32 v225, v224
	s_nop 0
	v_add_u32_e32 v226, -1, v225
	v_add_u32_e32 v227, 1, v225
	v_fma_f32 v228, -v226, v225, v224
	v_fma_f32 v229, -v227, v225, v224
	v_cmp_ge_f32_e64 s[46:47], 0, v228
	s_nop 1
	v_cndmask_b32_e64 v225, v225, v226, s[46:47]
	v_cmp_lt_f32_e64 s[46:47], 0, v229
	s_nop 1
	v_cndmask_b32_e64 v225, v225, v227, s[46:47]
	v_mul_f32_e32 v226, 0x37800000, v225
	v_cndmask_b32_e32 v225, v225, v226, vcc
	v_cmp_class_f32_e32 vcc, v224, v231
	s_nop 1
	v_cndmask_b32_e32 v224, v225, v224, vcc
	v_div_scale_f32 v225, s[46:47], v224, v224, 1.0
	v_rcp_f32_e32 v226, v225
	v_div_scale_f32 v227, vcc, 1.0, v224, 1.0
	v_fma_f32 v228, -v225, v226, 1.0
	v_fmac_f32_e32 v226, v228, v226
	v_mul_f32_e32 v228, v227, v226
	v_fma_f32 v229, -v225, v228, v227
	v_fmac_f32_e32 v228, v229, v226
	v_fma_f32 v225, -v225, v228, v227
	v_div_fmas_f32 v225, v225, v226, v228
	v_div_fixup_f32 v1, v225, v224, 1.0
	s_nop 0
	global_store_dword v[34:35], v1, off
	s_andn2_b64 exec, exec, s[14:15]
	s_cbranch_execnz .LBB0_456

; #define PG8_STAGE(bufoff, gbase, voff) do { _Pragma("unroll") for (int _i = 0; _i < 2; ++_i) \
;         __builtin_amdgcn_global_load_lds((const unsigned*)((const char*)(gbase) + (voff)[_i]), (LAS unsigned*)(lds + (bufoff) + ldsw + _i * 8192), 16, 0, 0); } while (0)
; #define PG8_LDA(dst, b, h) do { _Pragma("unroll") for (int m = 0; m < 4; ++m) _Pragma("unroll") for (int k = 0; k < 2; ++k) dst[m][k] = *(const LAS bf16x8*)(lds + PG8_SA(b, h) + aoff + m * 2048 + k * 1024); } while (0)
; #define PG8_LDB(dst, b, h) do { _Pragma("unroll") for (int n = 0; n < 2; ++n) _Pragma("unroll") for (int k = 0; k < 2; ++k) dst[n][k] = *(const LAS bf16x8*)(lds + PG8_SB(b, h) + boff + n * 2048 + k * 1024); } while (0)
; #define PG8_WAIT_V(n) asm volatile("s_waitcnt vmcnt(" #n ")" ::: "memory")
; #define PG8_WAIT_L(n) asm volatile("s_waitcnt lgkmcnt(" #n ")" ::: "memory")
; #define PG8_BAR __builtin_amdgcn_s_barrier()
; #define PG8_SCHED __builtin_amdgcn_sched_barrier(0)
; template <class Epi, class Sched>
; DI void gemm_phase(LAS unsigned char* lds, const Gemm g, const Sched& S, const Epi& E) {
;     ...
;             PG8_LDB(B0, 0, 0); PG8_SCHED; PG8_LDA(At, 0, 0); PG8_STAGE(PG8_SA(1, 1), a1 + hstep, voffA);
;             PG8_WAIT_L(8); PG8_BAR; PG8_WAIT_L(0); PG8_MMA(0, 0, At, B0); PG8_BAR; PG8_SCHED;
;             PG8_LDB(B1, 0, 1); PG8_STAGE(PG8_SB(0, 0), b2, voffB);
;             PG8_BAR; PG8_WAIT_L(0); PG8_MMA(0, 1, At, B1); PG8_BAR;
;             PG8_LDA(At, 0, 1); PG8_STAGE(PG8_SA(0, 0), a2, voffA);
;             PG8_BAR; PG8_WAIT_L(0); PG8_MMA(1, 0, At, B0); PG8_BAR; PG8_SCHED;
;             PG8_STAGE(PG8_SB(0, 1), b2 + hstep, voffB);
;             PG8_WAIT_V(6); PG8_BAR; PG8_MMA(1, 1, At, B1); PG8_BAR;
;             PG8_LDB(B0, 1, 0); PG8_SCHED; PG8_LDA(At, 1, 0); PG8_STAGE(PG8_SA(0, 1), a2 + hstep, voffA);
;             PG8_WAIT_L(8); PG8_BAR; PG8_WAIT_L(0); PG8_MMA(0, 0, At, B0); PG8_BAR; PG8_SCHED;
;             PG8_LDB(B1, 1, 1); PG8_STAGE(PG8_SB(1, 0), b3, voffB);
;             PG8_BAR; PG8_WAIT_L(0); PG8_MMA(0, 1, At, B1); PG8_BAR;
;             PG8_LDA(At, 1, 1); PG8_STAGE(PG8_SA(1, 0), a3, voffA);
;             PG8_BAR; PG8_WAIT_L(0); PG8_MMA(1, 0, At, B0); PG8_BAR; PG8_SCHED;
;             PG8_STAGE(PG8_SB(1, 1), b3 + hstep, voffB);
;             PG8_WAIT_V(6); PG8_BAR; PG8_MMA(1, 1, At, B1); PG8_BAR;
.LBB0_527:
	ds_read_b128 v[146:149], v164
	ds_read_b128 v[150:153], v164 offset:1024
	ds_read_b128 v[154:157], v164 offset:2048
	ds_read_b128 v[170:173], v164 offset:3072
	s_add_u32 s0, s8, 0xfff80080
	s_addc_u32 s1, s9, -1
	s_cmp_eq_u32 s35, 28
	s_cselect_b32 s13, s14, s1
	s_cselect_b32 s12, s15, s0
	s_cselect_b32 s11, s16, s34
	s_cselect_b32 s10, s17, s28
	v_lshl_add_u64 v[158:159], s[8:9], 0, v[138:139]
	s_add_i32 m0, s59, 0xc000
	ds_read_b128 v[174:177], v165
	ds_read_b128 v[178:181], v165 offset:1024
	ds_read_b128 v[188:191], v165 offset:2048
	ds_read_b128 v[194:197], v165 offset:3072
	ds_read_b128 v[198:201], v165 offset:4096
	ds_read_b128 v[202:205], v165 offset:5120
	ds_read_b128 v[206:209], v165 offset:6144
	ds_read_b128 v[210:213], v165 offset:7168
	global_load_lds_dwordx4 v[158:159], off
	v_lshl_add_u64 v[158:159], s[8:9], 0, v[140:141]
	s_add_i32 m0, s59, 0xe000
	s_nop 0
	global_load_lds_dwordx4 v[158:159], off
	s_waitcnt lgkmcnt(8)
	s_barrier
	s_waitcnt lgkmcnt(0)
	s_setprio 1
	s_waitcnt lgkmcnt(0)
	v_mfma_f32_16x16x32_bf16 v[124:127], v[146:149], v[174:177], v[124:127]
	v_mfma_f32_16x16x32_bf16 v[120:123], v[154:157], v[174:177], v[120:123]
	v_mfma_f32_16x16x32_bf16 v[108:111], v[146:149], v[188:191], v[108:111]
	v_mfma_f32_16x16x32_bf16 v[104:107], v[154:157], v[188:191], v[104:107]
	v_mfma_f32_16x16x32_bf16 v[92:95], v[146:149], v[198:201], v[92:95]
	v_mfma_f32_16x16x32_bf16 v[88:91], v[154:157], v[198:201], v[88:91]
	v_mfma_f32_16x16x32_bf16 v[76:79], v[146:149], v[206:209], v[76:79]
	v_mfma_f32_16x16x32_bf16 v[72:75], v[154:157], v[206:209], v[72:75]
	v_mfma_f32_16x16x32_bf16 v[124:127], v[150:153], v[178:181], v[124:127]
	v_mfma_f32_16x16x32_bf16 v[120:123], v[170:173], v[178:181], v[120:123]
	v_mfma_f32_16x16x32_bf16 v[108:111], v[150:153], v[194:197], v[108:111]
	v_mfma_f32_16x16x32_bf16 v[104:107], v[170:173], v[194:197], v[104:107]
	v_mfma_f32_16x16x32_bf16 v[92:95], v[150:153], v[202:205], v[92:95]
	v_mfma_f32_16x16x32_bf16 v[88:91], v[170:173], v[202:205], v[88:91]
	v_mfma_f32_16x16x32_bf16 v[76:79], v[150:153], v[210:213], v[76:79]
	v_mfma_f32_16x16x32_bf16 v[72:75], v[170:173], v[210:213], v[72:75]
	s_setprio 0
	s_barrier
	s_add_i32 s0, s47, s74
	v_lshl_add_u64 v[158:159], s[10:11], 0, v[130:131]
	s_mov_b32 m0, s0
	ds_read_b128 v[214:217], v166
	ds_read_b128 v[218:221], v166 offset:1024
	ds_read_b128 v[222:225], v166 offset:2048
	ds_read_b128 v[226:229], v166 offset:3072
	global_load_lds_dwordx4 v[158:159], off
	v_lshl_add_u64 v[182:183], s[10:11], 0, v[134:135]
	s_add_i32 m0, s0, 0x2000
	s_nop 0
	global_load_lds_dwordx4 v[182:183], off
	s_barrier
	s_waitcnt lgkmcnt(0)
	s_setprio 1
	s_waitcnt lgkmcnt(0)
	v_mfma_f32_16x16x32_bf16 v[116:119], v[214:217], v[174:177], v[116:119]
	v_mfma_f32_16x16x32_bf16 v[112:115], v[222:225], v[174:177], v[112:115]
	v_mfma_f32_16x16x32_bf16 v[100:103], v[214:217], v[188:191], v[100:103]
	v_mfma_f32_16x16x32_bf16 v[96:99], v[222:225], v[188:191], v[96:99]
	v_mfma_f32_16x16x32_bf16 v[84:87], v[214:217], v[198:201], v[84:87]
	v_mfma_f32_16x16x32_bf16 v[80:83], v[222:225], v[198:201], v[80:83]
	v_mfma_f32_16x16x32_bf16 v[68:71], v[214:217], v[206:209], v[68:71]
	v_mfma_f32_16x16x32_bf16 v[64:67], v[222:225], v[206:209], v[64:67]
	v_mfma_f32_16x16x32_bf16 v[116:119], v[218:221], v[178:181], v[116:119]
	v_mfma_f32_16x16x32_bf16 v[112:115], v[226:229], v[178:181], v[112:115]
	v_mfma_f32_16x16x32_bf16 v[100:103], v[218:221], v[194:197], v[100:103]
	v_mfma_f32_16x16x32_bf16 v[96:99], v[226:229], v[194:197], v[96:99]
	v_mfma_f32_16x16x32_bf16 v[84:87], v[218:221], v[202:205], v[84:87]
	v_mfma_f32_16x16x32_bf16 v[80:83], v[226:229], v[202:205], v[80:83]
	v_mfma_f32_16x16x32_bf16 v[68:71], v[218:221], v[210:213], v[68:71]
	v_mfma_f32_16x16x32_bf16 v[64:67], v[226:229], v[210:213], v[64:67]
	s_setprio 0
	s_mov_b32 m0, s59
	v_lshl_add_u64 v[230:231], s[12:13], 0, v[128:129]
	s_barrier
	ds_read_b128 v[174:177], v165 offset:16384
	ds_read_b128 v[178:181], v165 offset:17408
	ds_read_b128 v[188:191], v165 offset:18432
	ds_read_b128 v[194:197], v165 offset:19456
	ds_read_b128 v[198:201], v165 offset:20480
	ds_read_b128 v[202:205], v165 offset:21504
	ds_read_b128 v[206:209], v165 offset:22528
	ds_read_b128 v[210:213], v165 offset:23552
	global_load_lds_dwordx4 v[230:231], off
	v_lshl_add_u64 v[232:233], s[12:13], 0, v[132:133]
	s_mov_b32 m0, s75
	s_nop 0
	global_load_lds_dwordx4 v[232:233], off
	s_barrier
	s_waitcnt lgkmcnt(0)
	s_setprio 1
	s_waitcnt lgkmcnt(0)
	v_mfma_f32_16x16x32_bf16 v[60:63], v[146:149], v[174:177], v[60:63]
	v_mfma_f32_16x16x32_bf16 v[56:59], v[154:157], v[174:177], v[56:59]
	v_mfma_f32_16x16x32_bf16 v[44:47], v[146:149], v[188:191], v[44:47]
	v_mfma_f32_16x16x32_bf16 v[40:43], v[154:157], v[188:191], v[40:43]
	v_mfma_f32_16x16x32_bf16 v[28:31], v[146:149], v[198:201], v[28:31]
	v_mfma_f32_16x16x32_bf16 v[24:27], v[154:157], v[198:201], v[24:27]
	v_mfma_f32_16x16x32_bf16 v[12:15], v[146:149], v[206:209], v[12:15]
	v_mfma_f32_16x16x32_bf16 v[8:11], v[154:157], v[206:209], v[8:11]
	v_mfma_f32_16x16x32_bf16 v[60:63], v[150:153], v[178:181], v[60:63]
	v_mfma_f32_16x16x32_bf16 v[56:59], v[170:173], v[178:181], v[56:59]
	v_mfma_f32_16x16x32_bf16 v[44:47], v[150:153], v[194:197], v[44:47]
	v_mfma_f32_16x16x32_bf16 v[40:43], v[170:173], v[194:197], v[40:43]
	v_mfma_f32_16x16x32_bf16 v[28:31], v[150:153], v[202:205], v[28:31]
	v_mfma_f32_16x16x32_bf16 v[24:27], v[170:173], v[202:205], v[24:27]
	v_mfma_f32_16x16x32_bf16 v[12:15], v[150:153], v[210:213], v[12:15]
	v_mfma_f32_16x16x32_bf16 v[8:11], v[170:173], v[210:213], v[8:11]
	s_setprio 0
	s_barrier
; #define PG8_STAGE(bufoff, gbase, voff) do { _Pragma("unroll") for (int _i = 0; _i < 2; ++_i) \
;         __builtin_amdgcn_global_load_lds((const unsigned*)((const char*)(gbase) + (voff)[_i]), (LAS unsigned*)(lds + (bufoff) + ldsw + _i * 8192), 16, 0, 0); } while (0)
; #define PG8_LDA(dst, b, h) do { _Pragma("unroll") for (int m = 0; m < 4; ++m) _Pragma("unroll") for (int k = 0; k < 2; ++k) dst[m][k] = *(const LAS bf16x8*)(lds + PG8_SA(b, h) + aoff + m * 2048 + k * 1024); } while (0)
; #define PG8_LDB(dst, b, h) do { _Pragma("unroll") for (int n = 0; n < 2; ++n) _Pragma("unroll") for (int k = 0; k < 2; ++k) dst[n][k] = *(const LAS bf16x8*)(lds + PG8_SB(b, h) + boff + n * 2048 + k * 1024); } while (0)
; #define PG8_WAIT_V(n) asm volatile("s_waitcnt vmcnt(" #n ")" ::: "memory")
; #define PG8_WAIT_L(n) asm volatile("s_waitcnt lgkmcnt(" #n ")" ::: "memory")
; #define PG8_BAR __builtin_amdgcn_s_barrier()
; #define PG8_SCHED __builtin_amdgcn_sched_barrier(0)
; template <class Epi, class Sched>
; DI void gemm_phase(LAS unsigned char* lds, const Gemm g, const Sched& S, const Epi& E) {
;     ...
;             PG8_LDB(B0, 0, 0); PG8_SCHED; PG8_LDA(At, 0, 0); PG8_STAGE(PG8_SA(1, 1), a1 + hstep, voffA);
;             PG8_WAIT_L(8); PG8_BAR; PG8_WAIT_L(0); PG8_MMA(0, 0, At, B0); PG8_BAR; PG8_SCHED;
;             PG8_LDB(B1, 0, 1); PG8_STAGE(PG8_SB(0, 0), b2, voffB);
;             PG8_BAR; PG8_WAIT_L(0); PG8_MMA(0, 1, At, B1); PG8_BAR;
;             PG8_LDA(At, 0, 1); PG8_STAGE(PG8_SA(0, 0), a2, voffA);
;             PG8_BAR; PG8_WAIT_L(0); PG8_MMA(1, 0, At, B0); PG8_BAR; PG8_SCHED;
;             PG8_STAGE(PG8_SB(0, 1), b2 + hstep, voffB);
;             PG8_WAIT_V(6); PG8_BAR; PG8_MMA(1, 1, At, B1); PG8_BAR;
;             PG8_LDB(B0, 1, 0); PG8_SCHED; PG8_LDA(At, 1, 0); PG8_STAGE(PG8_SA(0, 1), a2 + hstep, voffA);
;             PG8_WAIT_L(8); PG8_BAR; PG8_WAIT_L(0); PG8_MMA(0, 0, At, B0); PG8_BAR; PG8_SCHED;
;             PG8_LDB(B1, 1, 1); PG8_STAGE(PG8_SB(1, 0), b3, voffB);
;             PG8_BAR; PG8_WAIT_L(0); PG8_MMA(0, 1, At, B1); PG8_BAR;
;             PG8_LDA(At, 1, 1); PG8_STAGE(PG8_SA(1, 0), a3, voffA);
;             PG8_BAR; PG8_WAIT_L(0); PG8_MMA(1, 0, At, B0); PG8_BAR; PG8_SCHED;
;             PG8_STAGE(PG8_SB(1, 1), b3 + hstep, voffB);
;             PG8_WAIT_V(6); PG8_BAR; PG8_MMA(1, 1, At, B1); PG8_BAR;
	s_add_u32 s0, s10, 0x80000
	s_addc_u32 s1, s11, 0
	s_add_i32 s4, s87, s74
	v_lshl_add_u64 v[146:147], s[0:1], 0, v[130:131]
	s_mov_b32 m0, s4
	s_nop 0
	global_load_lds_dwordx4 v[146:147], off
	v_lshl_add_u64 v[146:147], s[0:1], 0, v[134:135]
	s_add_i32 m0, s4, 0x2000
	s_nop 0
	global_load_lds_dwordx4 v[146:147], off
	s_waitcnt vmcnt(6)
	s_barrier
	s_setprio 1
	v_mfma_f32_16x16x32_bf16 v[52:55], v[214:217], v[174:177], v[52:55]
	v_mfma_f32_16x16x32_bf16 v[48:51], v[222:225], v[174:177], v[48:51]
	v_mfma_f32_16x16x32_bf16 v[36:39], v[214:217], v[188:191], v[36:39]
	v_mfma_f32_16x16x32_bf16 v[32:35], v[222:225], v[188:191], v[32:35]
	v_mfma_f32_16x16x32_bf16 v[20:23], v[214:217], v[198:201], v[20:23]
	v_mfma_f32_16x16x32_bf16 v[16:19], v[222:225], v[198:201], v[16:19]
	v_mfma_f32_16x16x32_bf16 v[4:7], v[214:217], v[206:209], v[4:7]
	v_mfma_f32_16x16x32_bf16 v[0:3], v[222:225], v[206:209], v[0:3]
	v_mfma_f32_16x16x32_bf16 v[52:55], v[218:221], v[178:181], v[52:55]
	v_mfma_f32_16x16x32_bf16 v[48:51], v[226:229], v[178:181], v[48:51]
	v_mfma_f32_16x16x32_bf16 v[36:39], v[218:221], v[194:197], v[36:39]
	v_mfma_f32_16x16x32_bf16 v[32:35], v[226:229], v[194:197], v[32:35]
	v_mfma_f32_16x16x32_bf16 v[20:23], v[218:221], v[202:205], v[20:23]
	v_mfma_f32_16x16x32_bf16 v[16:19], v[226:229], v[202:205], v[16:19]
	v_mfma_f32_16x16x32_bf16 v[4:7], v[218:221], v[210:213], v[4:7]
	v_mfma_f32_16x16x32_bf16 v[0:3], v[226:229], v[210:213], v[0:3]
	s_setprio 0
	s_add_i32 s4, 0, 0x18000
	v_add_u32_e32 v137, s4, v163
	s_barrier
	ds_read_b128 v[146:149], v137
	ds_read_b128 v[150:153], v137 offset:1024
	ds_read_b128 v[154:157], v137 offset:2048
	ds_read_b128 v[170:173], v137 offset:3072
	s_add_u32 s0, s12, 0x80000
	s_addc_u32 s1, s13, 0
	s_mov_b32 m0, s76
	v_lshl_add_u64 v[214:215], s[0:1], 0, v[128:129]
	ds_read_b128 v[174:177], v165 offset:32768
	ds_read_b128 v[178:181], v165 offset:33792
	ds_read_b128 v[188:191], v165 offset:34816
	ds_read_b128 v[194:197], v165 offset:35840
	ds_read_b128 v[198:201], v165 offset:36864
	ds_read_b128 v[202:205], v165 offset:37888
	ds_read_b128 v[206:209], v165 offset:38912
	ds_read_b128 v[210:213], v165 offset:39936
	global_load_lds_dwordx4 v[214:215], off
	v_lshl_add_u64 v[214:215], s[0:1], 0, v[132:133]
	s_mov_b32 m0, s77
	s_nop 0
	global_load_lds_dwordx4 v[214:215], off
	s_waitcnt lgkmcnt(8)
	s_barrier
	s_waitcnt lgkmcnt(0)
	s_setprio 1
	s_waitcnt lgkmcnt(0)
	v_mfma_f32_16x16x32_bf16 v[124:127], v[146:149], v[174:177], v[124:127]
	v_mfma_f32_16x16x32_bf16 v[120:123], v[154:157], v[174:177], v[120:123]
	v_mfma_f32_16x16x32_bf16 v[108:111], v[146:149], v[188:191], v[108:111]
	v_mfma_f32_16x16x32_bf16 v[104:107], v[154:157], v[188:191], v[104:107]
	v_mfma_f32_16x16x32_bf16 v[92:95], v[146:149], v[198:201], v[92:95]
	v_mfma_f32_16x16x32_bf16 v[88:91], v[154:157], v[198:201], v[88:91]
	v_mfma_f32_16x16x32_bf16 v[76:79], v[146:149], v[206:209], v[76:79]
	v_mfma_f32_16x16x32_bf16 v[72:75], v[154:157], v[206:209], v[72:75]
	v_mfma_f32_16x16x32_bf16 v[124:127], v[150:153], v[178:181], v[124:127]
	v_mfma_f32_16x16x32_bf16 v[120:123], v[170:173], v[178:181], v[120:123]
	v_mfma_f32_16x16x32_bf16 v[108:111], v[150:153], v[194:197], v[108:111]
	v_mfma_f32_16x16x32_bf16 v[104:107], v[170:173], v[194:197], v[104:107]
	v_mfma_f32_16x16x32_bf16 v[92:95], v[150:153], v[202:205], v[92:95]
	v_mfma_f32_16x16x32_bf16 v[88:91], v[170:173], v[202:205], v[88:91]
	v_mfma_f32_16x16x32_bf16 v[76:79], v[150:153], v[210:213], v[76:79]
	v_mfma_f32_16x16x32_bf16 v[72:75], v[170:173], v[210:213], v[72:75]
	s_setprio 0
	s_barrier
	s_add_i32 s5, 0, 0x1c000
	s_add_i32 s0, s4, s74
	v_add_u32_e32 v137, s5, v163
	v_lshl_add_u64 v[158:159], v[158:159], 0, s[40:41]
	s_mov_b32 m0, s0
	ds_read_b128 v[214:217], v137
	ds_read_b128 v[218:221], v137 offset:1024
	ds_read_b128 v[222:225], v137 offset:2048
	ds_read_b128 v[226:229], v137 offset:3072
	global_load_lds_dwordx4 v[158:159], off
	v_lshl_add_u64 v[158:159], v[182:183], 0, s[40:41]
	s_add_i32 m0, s0, 0x2000
	s_nop 0
	global_load_lds_dwordx4 v[158:159], off
	s_barrier
	s_waitcnt lgkmcnt(0)
	s_setprio 1
	s_waitcnt lgkmcnt(0)
	v_mfma_f32_16x16x32_bf16 v[116:119], v[214:217], v[174:177], v[116:119]
	v_mfma_f32_16x16x32_bf16 v[112:115], v[222:225], v[174:177], v[112:115]
	v_mfma_f32_16x16x32_bf16 v[100:103], v[214:217], v[188:191], v[100:103]
	v_mfma_f32_16x16x32_bf16 v[96:99], v[222:225], v[188:191], v[96:99]
	v_mfma_f32_16x16x32_bf16 v[84:87], v[214:217], v[198:201], v[84:87]
	v_mfma_f32_16x16x32_bf16 v[80:83], v[222:225], v[198:201], v[80:83]
	v_mfma_f32_16x16x32_bf16 v[68:71], v[214:217], v[206:209], v[68:71]
	v_mfma_f32_16x16x32_bf16 v[64:67], v[222:225], v[206:209], v[64:67]
	v_mfma_f32_16x16x32_bf16 v[116:119], v[218:221], v[178:181], v[116:119]
	v_mfma_f32_16x16x32_bf16 v[112:115], v[226:229], v[178:181], v[112:115]
	v_mfma_f32_16x16x32_bf16 v[100:103], v[218:221], v[194:197], v[100:103]
	v_mfma_f32_16x16x32_bf16 v[96:99], v[226:229], v[194:197], v[96:99]
	v_mfma_f32_16x16x32_bf16 v[84:87], v[218:221], v[202:205], v[84:87]
	v_mfma_f32_16x16x32_bf16 v[80:83], v[226:229], v[202:205], v[80:83]
	v_mfma_f32_16x16x32_bf16 v[68:71], v[218:221], v[210:213], v[68:71]
	v_mfma_f32_16x16x32_bf16 v[64:67], v[226:229], v[210:213], v[64:67]
	s_setprio 0
	s_mov_b32 m0, s97
	v_lshl_add_u64 v[158:159], v[230:231], 0, s[40:41]
	s_barrier
	ds_read_b128 v[174:177], v165 offset:49152
	ds_read_b128 v[178:181], v165 offset:50176
	ds_read_b128 v[188:191], v165 offset:51200
	ds_read_b128 v[194:197], v165 offset:52224
	ds_read_b128 v[198:201], v165 offset:53248
	ds_read_b128 v[202:205], v165 offset:54272
	ds_read_b128 v[206:209], v165 offset:55296
	ds_read_b128 v[210:213], v165 offset:56320
	global_load_lds_dwordx4 v[158:159], off
	v_lshl_add_u64 v[158:159], v[232:233], 0, s[40:41]
	s_mov_b32 m0, s84
	s_nop 0
	global_load_lds_dwordx4 v[158:159], off
	s_barrier
;     DI void operator()(AccRef acc, const Unit& u, int wr, int wc, int fr, int fq) const {
;         const int pn = u.pn, pm = u.pm; const bool smp = pm >= 128;
;         const int rl0 = wr * 64 + fr;
;         const int cc0 = wc * 32 + 8 * fq;
;         if (pn < 4 || (pn >= 12 && pn < 15)) {
;             bf16_t* dst = (pn < 4) ? QA + pn * 256 : CQ + (pn - 12) * 256; const int ld = (pn < 4) ? 1024 : 768;
; #pragma unroll
;             for (int ai = 0; ai < 2; ++ai)
; #pragma unroll
;                 for (int m = 0; m < 4; ++m) { const size_t row = (size_t)pm * 256 + rl0 + ai * 128 + m * 16; const float r = rs_of(ss, (int)row) * ((pn < 4) ? 0.08838834764831845f * LOG2E : 1.0f);
; #pragma unroll
;                     for (int bj = 0; bj < 2; ++bj) *(u32x4*)(dst + row * ld + cc0 + bj * 128) = pack8((acc[ai][bj][m][0] * r), (acc[ai][bj][m][1] * r)); }
;         } else if (pn < 12) {
;             const bool isv = pn >= 8; const int c0 = (pn - (isv ? 8 : 4)) * 256 + cc0;
;             const bool f32out = smp || ((pm & 15) >= 14);
;             float* fo = out + (smp ? (isv ? O_AVS : O_AKS) : (isv ? O_AVP : O_AKP));
; #pragma unroll
;             for (int ai = 0; ai < 2; ++ai)
; #pragma unroll
;                 for (int m = 0; m < 4; ++m) {
;                     const int rl = rl0 + ai * 128 + m * 16; const float r = rs_of(ss, pm * 256 + rl);
;                     int b, s; if (smp) { b = rl >> 5; s = rl & 31; } else { b = pm >> 4; s = (pm & 15) * 256 + rl; }
;                     if (f32out) { const size_t orow = smp ? (size_t)rl : (size_t)b * 512 + (s - 3584);
; #pragma unroll
;                         for (int bj = 0; bj < 2; ++bj) { float* p = fo + orow * 1024 + c0 + bj * 128; *(f32x4*)p = (acc[ai][bj][m][0] * r); *(f32x4*)(p + 4) = (acc[ai][bj][m][1] * r); } }
;                     if (!isv) { bf16_t* dst = smp ? KAs + ((size_t)b * LA + 512 + s) * 1024 : KA + ((size_t)pm * 256 + rl) * 1024;
; #pragma unroll
;                         for (int bj = 0; bj < 2; ++bj) *(u32x4*)(dst + c0 + bj * 128) = pack8((acc[ai][bj][m][0] * r), (acc[ai][bj][m][1] * r));
;                     } else { bf16_t* dst; size_t cs; if (smp) { dst = VtAs + (size_t)b * 1024 * LA + 512 + s; cs = LA; } else { dst = VtA + (size_t)b * 1024 * SEQ + s; cs = SEQ; }
; #pragma unroll
;                         for (int bj = 0; bj < 2; ++bj)
; #pragma unroll
	s_waitcnt lgkmcnt(0)
	s_setprio 1
	s_waitcnt lgkmcnt(0)
	v_mfma_f32_16x16x32_bf16 v[60:63], v[146:149], v[174:177], v[60:63]
	v_mfma_f32_16x16x32_bf16 v[56:59], v[154:157], v[174:177], v[56:59]
	v_mfma_f32_16x16x32_bf16 v[44:47], v[146:149], v[188:191], v[44:47]
	v_mfma_f32_16x16x32_bf16 v[40:43], v[154:157], v[188:191], v[40:43]
	v_mfma_f32_16x16x32_bf16 v[28:31], v[146:149], v[198:201], v[28:31]
	v_mfma_f32_16x16x32_bf16 v[24:27], v[154:157], v[198:201], v[24:27]
	v_mfma_f32_16x16x32_bf16 v[12:15], v[146:149], v[206:209], v[12:15]
	v_mfma_f32_16x16x32_bf16 v[8:11], v[154:157], v[206:209], v[8:11]
	v_mfma_f32_16x16x32_bf16 v[60:63], v[150:153], v[178:181], v[60:63]
	v_mfma_f32_16x16x32_bf16 v[56:59], v[170:173], v[178:181], v[56:59]
	v_mfma_f32_16x16x32_bf16 v[44:47], v[150:153], v[194:197], v[44:47]
	v_mfma_f32_16x16x32_bf16 v[40:43], v[170:173], v[194:197], v[40:43]
	v_mfma_f32_16x16x32_bf16 v[28:31], v[150:153], v[202:205], v[28:31]
	v_mfma_f32_16x16x32_bf16 v[24:27], v[170:173], v[202:205], v[24:27]
	v_mfma_f32_16x16x32_bf16 v[12:15], v[150:153], v[210:213], v[12:15]
	v_mfma_f32_16x16x32_bf16 v[8:11], v[170:173], v[210:213], v[8:11]
	s_setprio 0
	s_barrier
	s_add_u32 s0, s10, 0x80080
	s_addc_u32 s1, s11, 0
	s_add_i32 s4, s5, s74
	v_lshl_add_u64 v[146:147], s[0:1], 0, v[130:131]
	s_mov_b32 m0, s4
	s_nop 0
	global_load_lds_dwordx4 v[146:147], off
	v_lshl_add_u64 v[146:147], s[0:1], 0, v[134:135]
	s_add_i32 m0, s4, 0x2000
	s_nop 0
	global_load_lds_dwordx4 v[146:147], off
	s_waitcnt vmcnt(6)
	s_barrier
	s_setprio 1
	v_mfma_f32_16x16x32_bf16 v[52:55], v[214:217], v[174:177], v[52:55]
	v_mfma_f32_16x16x32_bf16 v[48:51], v[222:225], v[174:177], v[48:51]
	v_mfma_f32_16x16x32_bf16 v[36:39], v[214:217], v[188:191], v[36:39]
	v_mfma_f32_16x16x32_bf16 v[32:35], v[222:225], v[188:191], v[32:35]
	v_mfma_f32_16x16x32_bf16 v[20:23], v[214:217], v[198:201], v[20:23]
	v_mfma_f32_16x16x32_bf16 v[16:19], v[222:225], v[198:201], v[16:19]
	v_mfma_f32_16x16x32_bf16 v[4:7], v[214:217], v[206:209], v[4:7]
	v_mfma_f32_16x16x32_bf16 v[0:3], v[222:225], v[206:209], v[0:3]
	v_mfma_f32_16x16x32_bf16 v[52:55], v[218:221], v[178:181], v[52:55]
	v_mfma_f32_16x16x32_bf16 v[48:51], v[226:229], v[178:181], v[48:51]
	v_mfma_f32_16x16x32_bf16 v[36:39], v[218:221], v[194:197], v[36:39]
	v_mfma_f32_16x16x32_bf16 v[32:35], v[226:229], v[194:197], v[32:35]
	v_mfma_f32_16x16x32_bf16 v[20:23], v[218:221], v[202:205], v[20:23]
	v_mfma_f32_16x16x32_bf16 v[16:19], v[226:229], v[202:205], v[16:19]
	v_mfma_f32_16x16x32_bf16 v[4:7], v[218:221], v[210:213], v[4:7]
	v_mfma_f32_16x16x32_bf16 v[0:3], v[226:229], v[210:213], v[0:3]
	s_setprio 0
	s_add_i32 s35, s35, 2
	s_add_u32 s8, s8, 0x100
	s_addc_u32 s9, s9, 0
	s_add_u32 s28, s28, 0x100
	s_addc_u32 s34, s34, 0
	s_cmp_gt_u32 s35, 29
	s_barrier
	s_cbranch_scc0 .LBB0_527
	s_cmp_lt_i32 s58, 4
	s_cselect_b64 s[8:9], -1, 0
	s_add_i32 s0, s58, -12
	s_cmp_lt_u32 s0, 3
	v_mov_b32_e32 v146, v162
	v_mov_b32_e32 v137, v161
	s_cselect_b64 s[0:1], -1, 0
	s_or_b64 s[0:1], s[8:9], s[0:1]
	v_add_u32_e32 v148, s95, v137
	v_lshl_add_u32 v146, v146, 3, s96
	s_andn2_b64 vcc, exec, s[0:1]
	s_mov_b64 s[10:11], -1
	s_cbranch_vccz .LBB0_684
	s_cmpk_gt_i32 s56, 0x7f
	s_cselect_b64 s[12:13], -1, 0
	s_cmpk_lt_i32 s56, 0x80
	s_cselect_b64 s[16:17], -1, 0
	s_cmp_gt_u32 s58, 11
	s_cbranch_scc0 .LBB0_537
	s_cmp_gt_u32 s58, 16
	s_cbranch_scc0 .LBB0_534
	s_andn2_b64 vcc, exec, s[42:43]
	s_cbranch_vccnz .LBB0_533
	s_ashr_i32 s57, s56, 31
	s_lshl_b64 s[0:1], s[56:57], 16
	v_readlane_b32 s4, v244, 10
	s_add_u32 s4, s4, s0
	v_readlane_b32 s0, v244, 8
	s_addc_u32 s5, s0, s1
	s_and_b64 s[0:1], s[12:13], exec
	v_readlane_b32 s0, v244, 13
	v_readlane_b32 s1, v244, 9
	s_cselect_b32 s0, s0, s5
	s_cselect_b32 s1, s1, s4
	s_lshl_b32 s14, s56, 8
	v_add_u32_e32 v150, s14, v148
	v_ashrrev_i32_e32 v151, 31, v150
	v_lshl_add_u64 v[150:151], v[150:151], 2, s[38:39]
	v_mov_b64_e32 v[240:241], v[150:151]
	s_mov_b32 s61, 0
	global_load_dword v192, v[240:241], off
	s_mov_b32 s60, 0x40
	v_lshl_add_u64 v[240:241], v[240:241], 0, s[60:61]
	global_load_dword v236, v[240:241], off
	s_mov_b32 s60, 0x40
	v_lshl_add_u64 v[240:241], v[240:241], 0, s[60:61]
	global_load_dword v237, v[240:241], off
	s_mov_b32 s60, 0x40
	v_lshl_add_u64 v[240:241], v[240:241], 0, s[60:61]
	global_load_dword v238, v[240:241], off
	s_mov_b32 s60, 0x140
	v_lshl_add_u64 v[240:241], v[240:241], 0, s[60:61]
	global_load_dword v239, v[240:241], off
	s_mov_b32 s60, 0x40
	v_lshl_add_u64 v[240:241], v[240:241], 0, s[60:61]
	global_load_dword v232, v[240:241], off
	s_mov_b32 s60, 0x40
	v_lshl_add_u64 v[240:241], v[240:241], 0, s[60:61]
	global_load_dword v233, v[240:241], off
	s_mov_b32 s60, 0x40
	v_lshl_add_u64 v[240:241], v[240:241], 0, s[60:61]
	global_load_dword v234, v[240:241], off
	s_waitcnt vmcnt(7)
	v_mov_b32_e32 v153, v192
	v_ashrrev_i32_e32 v149, 31, v148
	v_lshlrev_b64 v[154:155], 8, v[148:149]
	v_ashrrev_i32_e32 v147, 31, v146
	v_mov_b32_e32 v150, s1
	v_mov_b32_e32 v151, s0
	v_lshl_add_u64 v[150:151], v[146:147], 2, v[150:151]
	v_lshl_add_u64 v[158:159], v[150:151], 0, v[154:155]
	v_add_u32_e32 v152, 16, v148
	v_add_u32_e32 v156, s14, v152
	v_ashrrev_i32_e32 v157, 31, v156
	v_lshl_add_u64 v[174:175], v[156:157], 2, s[38:39]
	s_nop 1
	s_nop 0
	s_nop 1
	s_nop 1
	s_nop 1
	v_mov_b32_e32 v170, v192
	v_pk_mul_f32 v[156:157], v[126:127], v[170:171] op_sel_hi:[1,0]
	v_pk_mul_f32 v[154:155], v[124:125], v[170:171] op_sel_hi:[1,0]
	v_pk_mul_f32 v[172:173], v[122:123], v[170:171] op_sel_hi:[1,0]
	v_pk_mul_f32 v[170:171], v[120:121], v[170:171] op_sel_hi:[1,0]
	global_store_dwordx4 v[158:159], v[154:157], off
	global_store_dwordx4 v[158:159], v[170:173], off offset:16
	s_waitcnt vmcnt(8)
; DI float rs_of(const float* ss, int row) { return 1.0f / sqrtf(ss[row] * (1.0f / DM) + EPS); }
;     DI void operator()(AccRef acc, const Unit& u, int wr, int wc, int fr, int fq) const {
;     ...
;             if (wc < 2) { float* fo = smp ? out + O_KRS : out + O_KRP + (size_t)pm * 256 * 64;
; #pragma unroll
;                 for (int ai = 0; ai < 2; ++ai)
; #pragma unroll
;                     for (int m = 0; m < 4; ++m) { const int rl = rl0 + ai * 128 + m * 16; const float r = rs_of(ss, pm * 256 + rl); float* p = fo + (size_t)rl * 64 + cc0; *(f32x4*)p = (acc[ai][0][m][0] * r); *(f32x4*)(p + 4) = (acc[ai][0][m][1] * r); } }
	v_mov_b32_e32 v147, v236
	v_add_u32_e32 v154, 32, v148
	v_add_u32_e32 v156, s14, v154
	v_ashrrev_i32_e32 v157, 31, v156
	v_lshl_add_u64 v[174:175], v[156:157], 2, s[38:39]
	v_ashrrev_i32_e32 v153, 31, v152
	v_lshlrev_b64 v[152:153], 8, v[152:153]
	v_lshl_add_u64 v[152:153], v[150:151], 0, v[152:153]
	s_nop 1
	s_nop 0
	s_nop 1
	s_nop 1
	s_nop 1
	v_mov_b32_e32 v170, v236
	v_pk_mul_f32 v[158:159], v[110:111], v[170:171] op_sel_hi:[1,0]
	v_pk_mul_f32 v[156:157], v[108:109], v[170:171] op_sel_hi:[1,0]
	v_pk_mul_f32 v[172:173], v[106:107], v[170:171] op_sel_hi:[1,0]
	v_pk_mul_f32 v[170:171], v[104:105], v[170:171] op_sel_hi:[1,0]
	global_store_dwordx4 v[152:153], v[156:159], off
	global_store_dwordx4 v[152:153], v[170:173], off offset:16
	s_waitcnt vmcnt(9)
	v_mov_b32_e32 v147, v237
	v_ashrrev_i32_e32 v155, 31, v154
	v_lshlrev_b64 v[154:155], 8, v[154:155]
	v_lshl_add_u64 v[158:159], v[150:151], 0, v[154:155]
	v_add_u32_e32 v152, 48, v148
	v_add_u32_e32 v156, s14, v152
	v_ashrrev_i32_e32 v157, 31, v156
	v_lshl_add_u64 v[174:175], v[156:157], 2, s[38:39]
	s_nop 1
	s_nop 0
	s_nop 1
	s_nop 1
	s_nop 1
	v_mov_b32_e32 v170, v237
	v_pk_mul_f32 v[156:157], v[94:95], v[170:171] op_sel_hi:[1,0]
	v_pk_mul_f32 v[154:155], v[92:93], v[170:171] op_sel_hi:[1,0]
	v_pk_mul_f32 v[172:173], v[90:91], v[170:171] op_sel_hi:[1,0]
	v_pk_mul_f32 v[170:171], v[88:89], v[170:171] op_sel_hi:[1,0]
	global_store_dwordx4 v[158:159], v[154:157], off
	global_store_dwordx4 v[158:159], v[170:173], off offset:16
	s_waitcnt vmcnt(10)
	v_mov_b32_e32 v147, v238
	v_add_u32_e32 v154, 0x80, v148
	v_add_u32_e32 v156, s14, v154
	v_ashrrev_i32_e32 v157, 31, v156
	v_lshl_add_u64 v[174:175], v[156:157], 2, s[38:39]
	v_ashrrev_i32_e32 v153, 31, v152
	v_lshlrev_b64 v[152:153], 8, v[152:153]
	v_lshl_add_u64 v[152:153], v[150:151], 0, v[152:153]
	s_nop 1
	s_nop 0
	s_nop 1
	s_nop 1
	s_nop 1
	v_mov_b32_e32 v170, v238
	v_pk_mul_f32 v[158:159], v[78:79], v[170:171] op_sel_hi:[1,0]
	v_pk_mul_f32 v[156:157], v[76:77], v[170:171] op_sel_hi:[1,0]
	v_pk_mul_f32 v[172:173], v[74:75], v[170:171] op_sel_hi:[1,0]
	v_pk_mul_f32 v[170:171], v[72:73], v[170:171] op_sel_hi:[1,0]
	global_store_dwordx4 v[152:153], v[156:159], off
	global_store_dwordx4 v[152:153], v[170:173], off offset:16
	s_waitcnt vmcnt(11)
	v_mov_b32_e32 v147, v239
	v_ashrrev_i32_e32 v155, 31, v154
	v_lshlrev_b64 v[154:155], 8, v[154:155]
	v_lshl_add_u64 v[158:159], v[150:151], 0, v[154:155]
	v_add_u32_e32 v152, 0x90, v148
	v_add_u32_e32 v156, s14, v152
	v_ashrrev_i32_e32 v157, 31, v156
	v_lshl_add_u64 v[174:175], v[156:157], 2, s[38:39]
	s_nop 1
	s_nop 0
	s_nop 1
	s_nop 1
	s_nop 1
	v_mov_b32_e32 v170, v239
	v_pk_mul_f32 v[156:157], v[62:63], v[170:171] op_sel_hi:[1,0]
	v_pk_mul_f32 v[154:155], v[60:61], v[170:171] op_sel_hi:[1,0]
	v_pk_mul_f32 v[172:173], v[58:59], v[170:171] op_sel_hi:[1,0]
	v_pk_mul_f32 v[170:171], v[56:57], v[170:171] op_sel_hi:[1,0]
	global_store_dwordx4 v[158:159], v[154:157], off
	global_store_dwordx4 v[158:159], v[170:173], off offset:16
	s_waitcnt vmcnt(12)
	v_mov_b32_e32 v147, v232
	v_add_u32_e32 v154, 0xa0, v148
	v_add_u32_e32 v156, s14, v154
	v_ashrrev_i32_e32 v157, 31, v156
	v_lshl_add_u64 v[174:175], v[156:157], 2, s[38:39]
	v_ashrrev_i32_e32 v153, 31, v152
	v_lshlrev_b64 v[152:153], 8, v[152:153]
	v_lshl_add_u64 v[152:153], v[150:151], 0, v[152:153]
	s_nop 1
	s_nop 0
	s_nop 1
	s_nop 1
	s_nop 1
	v_mov_b32_e32 v170, v232
	v_pk_mul_f32 v[158:159], v[46:47], v[170:171] op_sel_hi:[1,0]
	v_pk_mul_f32 v[156:157], v[44:45], v[170:171] op_sel_hi:[1,0]
	v_pk_mul_f32 v[172:173], v[42:43], v[170:171] op_sel_hi:[1,0]
	v_pk_mul_f32 v[170:171], v[40:41], v[170:171] op_sel_hi:[1,0]
	global_store_dwordx4 v[152:153], v[156:159], off
	global_store_dwordx4 v[152:153], v[170:173], off offset:16
	s_waitcnt vmcnt(13)
	v_mov_b32_e32 v147, v233
	v_ashrrev_i32_e32 v155, 31, v154
	v_lshlrev_b64 v[154:155], 8, v[154:155]
	v_lshl_add_u64 v[158:159], v[150:151], 0, v[154:155]
	v_add_u32_e32 v152, 0xb0, v148
	v_add_u32_e32 v156, s14, v152
	v_ashrrev_i32_e32 v157, 31, v156
	v_lshl_add_u64 v[174:175], v[156:157], 2, s[38:39]
	s_nop 1
	s_nop 0
	s_nop 1
	s_nop 1
	s_nop 1
	v_mov_b32_e32 v170, v233
	v_pk_mul_f32 v[156:157], v[30:31], v[170:171] op_sel_hi:[1,0]
	v_pk_mul_f32 v[154:155], v[28:29], v[170:171] op_sel_hi:[1,0]
	v_pk_mul_f32 v[172:173], v[26:27], v[170:171] op_sel_hi:[1,0]
	v_pk_mul_f32 v[170:171], v[24:25], v[170:171] op_sel_hi:[1,0]
	global_store_dwordx4 v[158:159], v[154:157], off
	global_store_dwordx4 v[158:159], v[170:173], off offset:16
	s_waitcnt vmcnt(14)
	v_mov_b32_e32 v147, v234
	v_ashrrev_i32_e32 v153, 31, v152
	v_lshlrev_b64 v[152:153], 8, v[152:153]
	v_lshl_add_u64 v[158:159], v[150:151], 0, v[152:153]
	s_nop 1
	s_nop 0
	s_nop 1
	s_nop 1
	s_nop 1
	v_mov_b32_e32 v154, v234
	v_pk_mul_f32 v[152:153], v[14:15], v[154:155] op_sel_hi:[1,0]
	v_pk_mul_f32 v[150:151], v[12:13], v[154:155] op_sel_hi:[1,0]
	v_pk_mul_f32 v[156:157], v[10:11], v[154:155] op_sel_hi:[1,0]
	v_pk_mul_f32 v[154:155], v[8:9], v[154:155] op_sel_hi:[1,0]
	global_store_dwordx4 v[158:159], v[150:153], off
	global_store_dwordx4 v[158:159], v[154:157], off offset:16

; DI float rs_of(const float* ss, int row) { return 1.0f / sqrtf(ss[row] * (1.0f / DM) + EPS); }
;     DI void operator()(AccRef acc, const Unit& u, int wr, int wc, int fr, int fq) const {
;     ...
;         } else if (pn < 17) {
;             float* fo = smp ? out + O_CKVS : out + O_CKVP + (size_t)pm * 256 * 512; const int c0 = (pn - 15) * 256 + cc0;
; #pragma unroll
;             for (int ai = 0; ai < 2; ++ai)
; #pragma unroll
;                 for (int m = 0; m < 4; ++m) { const int rl = rl0 + ai * 128 + m * 16; const float r = rs_of(ss, pm * 256 + rl);
; #pragma unroll
;                     for (int bj = 0; bj < 2; ++bj) { float* p = fo + (size_t)rl * 512 + c0 + bj * 128; *(f32x4*)p = (acc[ai][bj][m][0] * r); *(f32x4*)(p + 4) = (acc[ai][bj][m][1] * r); } }
.LBB0_534:
	s_andn2_b64 vcc, exec, s[10:11]
	s_cbranch_vccnz .LBB0_536
	s_ashr_i32 s57, s56, 31
	s_lshl_b64 s[0:1], s[56:57], 19
	v_readlane_b32 s4, v244, 11
	s_add_u32 s4, s4, s0
	s_addc_u32 s5, s92, s1
	s_and_b64 s[0:1], s[12:13], exec
	s_cselect_b32 s0, s94, s5
	s_cselect_b32 s1, s93, s4
	s_lshl_b32 s14, s56, 8
	v_add_u32_e32 v150, s14, v148
	v_ashrrev_i32_e32 v151, 31, v150
	v_lshl_add_u64 v[150:151], v[150:151], 2, s[38:39]
	v_mov_b64_e32 v[240:241], v[150:151]
	s_mov_b32 s61, 0
	global_load_dword v192, v[240:241], off
	s_mov_b32 s60, 0x40
	v_lshl_add_u64 v[240:241], v[240:241], 0, s[60:61]
	global_load_dword v236, v[240:241], off
	s_mov_b32 s60, 0x40
	v_lshl_add_u64 v[240:241], v[240:241], 0, s[60:61]
	global_load_dword v237, v[240:241], off
	s_mov_b32 s60, 0x40
	v_lshl_add_u64 v[240:241], v[240:241], 0, s[60:61]
	global_load_dword v238, v[240:241], off
	s_mov_b32 s60, 0x140
	v_lshl_add_u64 v[240:241], v[240:241], 0, s[60:61]
	global_load_dword v239, v[240:241], off
	s_mov_b32 s60, 0x40
	v_lshl_add_u64 v[240:241], v[240:241], 0, s[60:61]
	global_load_dword v232, v[240:241], off
	s_mov_b32 s60, 0x40
	v_lshl_add_u64 v[240:241], v[240:241], 0, s[60:61]
	global_load_dword v233, v[240:241], off
	s_mov_b32 s60, 0x40
	v_lshl_add_u64 v[240:241], v[240:241], 0, s[60:61]
	global_load_dword v234, v[240:241], off
	s_waitcnt vmcnt(7)
	v_mov_b32_e32 v147, v192
	v_ashrrev_i32_e32 v149, 31, v148
	v_lshlrev_b64 v[154:155], 11, v[148:149]
	v_add_u32_e32 v152, 16, v148
	s_lshl_b32 s4, s58, 8
	s_addk_i32 s4, 0xf100
	v_add_u32_e32 v156, s14, v152
	v_add_u32_e32 v158, s4, v146
	v_ashrrev_i32_e32 v157, 31, v156
	v_mov_b32_e32 v150, s1
	v_mov_b32_e32 v151, s0
	v_ashrrev_i32_e32 v159, 31, v158
	v_lshl_add_u64 v[182:183], v[156:157], 2, s[38:39]
	v_lshl_add_u64 v[150:151], v[158:159], 2, v[150:151]
	s_nop 1
	s_nop 0
	s_nop 1
	v_lshl_add_u64 v[158:159], v[150:151], 0, v[154:155]
	s_nop 0
	s_nop 1
	v_mov_b32_e32 v178, v192
	v_pk_mul_f32 v[156:157], v[126:127], v[178:179] op_sel_hi:[1,0]
	v_pk_mul_f32 v[154:155], v[124:125], v[178:179] op_sel_hi:[1,0]
	v_pk_mul_f32 v[172:173], v[122:123], v[178:179] op_sel_hi:[1,0]
	v_pk_mul_f32 v[170:171], v[120:121], v[178:179] op_sel_hi:[1,0]
	v_pk_mul_f32 v[176:177], v[118:119], v[178:179] op_sel_hi:[1,0]
	v_pk_mul_f32 v[174:175], v[116:117], v[178:179] op_sel_hi:[1,0]
	v_pk_mul_f32 v[180:181], v[114:115], v[178:179] op_sel_hi:[1,0]
	v_pk_mul_f32 v[178:179], v[112:113], v[178:179] op_sel_hi:[1,0]
	global_store_dwordx4 v[158:159], v[154:157], off
	global_store_dwordx4 v[158:159], v[170:173], off offset:16
	global_store_dwordx4 v[158:159], v[174:177], off offset:512
	global_store_dwordx4 v[158:159], v[178:181], off offset:528
	s_waitcnt vmcnt(10)
	v_mov_b32_e32 v147, v236
	v_add_u32_e32 v154, 32, v148
	v_add_u32_e32 v156, s14, v154
	v_ashrrev_i32_e32 v157, 31, v156
	v_lshl_add_u64 v[182:183], v[156:157], 2, s[38:39]
	v_ashrrev_i32_e32 v153, 31, v152
	v_lshlrev_b64 v[152:153], 11, v[152:153]
	v_lshl_add_u64 v[152:153], v[150:151], 0, v[152:153]
	s_nop 1
	s_nop 0
	s_nop 1
	s_nop 1
	s_nop 1
	v_mov_b32_e32 v178, v236
	v_pk_mul_f32 v[158:159], v[110:111], v[178:179] op_sel_hi:[1,0]
	v_pk_mul_f32 v[156:157], v[108:109], v[178:179] op_sel_hi:[1,0]
	v_pk_mul_f32 v[172:173], v[106:107], v[178:179] op_sel_hi:[1,0]
	v_pk_mul_f32 v[170:171], v[104:105], v[178:179] op_sel_hi:[1,0]
	v_pk_mul_f32 v[176:177], v[102:103], v[178:179] op_sel_hi:[1,0]
	v_pk_mul_f32 v[174:175], v[100:101], v[178:179] op_sel_hi:[1,0]
	v_pk_mul_f32 v[180:181], v[98:99], v[178:179] op_sel_hi:[1,0]
	v_pk_mul_f32 v[178:179], v[96:97], v[178:179] op_sel_hi:[1,0]
	global_store_dwordx4 v[152:153], v[156:159], off
	global_store_dwordx4 v[152:153], v[170:173], off offset:16
	global_store_dwordx4 v[152:153], v[174:177], off offset:512
	global_store_dwordx4 v[152:153], v[178:181], off offset:528
	s_waitcnt vmcnt(13)
	v_mov_b32_e32 v147, v237
	v_add_u32_e32 v152, 48, v148
	v_add_u32_e32 v156, s14, v152
	v_ashrrev_i32_e32 v157, 31, v156
	v_lshl_add_u64 v[158:159], v[156:157], 2, s[38:39]
	v_ashrrev_i32_e32 v155, 31, v154
	v_lshlrev_b64 v[154:155], 11, v[154:155]
	v_lshl_add_u64 v[182:183], v[150:151], 0, v[154:155]
	s_nop 1
	s_nop 0
	s_nop 1
	s_nop 1
	s_nop 1
	v_mov_b32_e32 v178, v237
	v_pk_mul_f32 v[156:157], v[94:95], v[178:179] op_sel_hi:[1,0]
	v_pk_mul_f32 v[154:155], v[92:93], v[178:179] op_sel_hi:[1,0]
	v_pk_mul_f32 v[172:173], v[90:91], v[178:179] op_sel_hi:[1,0]
	v_pk_mul_f32 v[170:171], v[88:89], v[178:179] op_sel_hi:[1,0]
	v_pk_mul_f32 v[176:177], v[86:87], v[178:179] op_sel_hi:[1,0]
	v_pk_mul_f32 v[174:175], v[84:85], v[178:179] op_sel_hi:[1,0]
	v_pk_mul_f32 v[180:181], v[82:83], v[178:179] op_sel_hi:[1,0]
	v_pk_mul_f32 v[178:179], v[80:81], v[178:179] op_sel_hi:[1,0]
	global_store_dwordx4 v[182:183], v[154:157], off
	global_store_dwordx4 v[182:183], v[170:173], off offset:16
	global_store_dwordx4 v[182:183], v[174:177], off offset:512
	global_store_dwordx4 v[182:183], v[178:181], off offset:528
	s_waitcnt vmcnt(16)
; DI float rs_of(const float* ss, int row) { return 1.0f / sqrtf(ss[row] * (1.0f / DM) + EPS); }
;     DI void operator()(AccRef acc, const Unit& u, int wr, int wc, int fr, int fq) const {
;     ...
;             for (int ai = 0; ai < 2; ++ai)
; #pragma unroll
;                 for (int m = 0; m < 4; ++m) { const int rl = rl0 + ai * 128 + m * 16; const float r = rs_of(ss, pm * 256 + rl);
; #pragma unroll
;                     for (int bj = 0; bj < 2; ++bj) { float* p = fo + (size_t)rl * 512 + c0 + bj * 128; *(f32x4*)p = (acc[ai][bj][m][0] * r); *(f32x4*)(p + 4) = (acc[ai][bj][m][1] * r); } }
	v_mov_b32_e32 v147, v238
	v_add_u32_e32 v154, 0x80, v148
	v_add_u32_e32 v156, s14, v154
	v_ashrrev_i32_e32 v157, 31, v156
	v_lshl_add_u64 v[182:183], v[156:157], 2, s[38:39]
	v_ashrrev_i32_e32 v153, 31, v152
	v_lshlrev_b64 v[152:153], 11, v[152:153]
	v_lshl_add_u64 v[152:153], v[150:151], 0, v[152:153]
	s_nop 1
	s_nop 0
	s_nop 1
	s_nop 1
	s_nop 1
	v_mov_b32_e32 v178, v238
	v_pk_mul_f32 v[158:159], v[78:79], v[178:179] op_sel_hi:[1,0]
	v_pk_mul_f32 v[156:157], v[76:77], v[178:179] op_sel_hi:[1,0]
	v_pk_mul_f32 v[172:173], v[74:75], v[178:179] op_sel_hi:[1,0]
	v_pk_mul_f32 v[170:171], v[72:73], v[178:179] op_sel_hi:[1,0]
	v_pk_mul_f32 v[176:177], v[70:71], v[178:179] op_sel_hi:[1,0]
	v_pk_mul_f32 v[174:175], v[68:69], v[178:179] op_sel_hi:[1,0]
	v_pk_mul_f32 v[180:181], v[66:67], v[178:179] op_sel_hi:[1,0]
	v_pk_mul_f32 v[178:179], v[64:65], v[178:179] op_sel_hi:[1,0]
	global_store_dwordx4 v[152:153], v[156:159], off
	global_store_dwordx4 v[152:153], v[170:173], off offset:16
	global_store_dwordx4 v[152:153], v[174:177], off offset:512
	global_store_dwordx4 v[152:153], v[178:181], off offset:528
	s_waitcnt vmcnt(19)
	v_mov_b32_e32 v147, v239
	v_add_u32_e32 v152, 0x90, v148
	v_add_u32_e32 v156, s14, v152
	v_ashrrev_i32_e32 v157, 31, v156
	v_lshl_add_u64 v[158:159], v[156:157], 2, s[38:39]
	v_ashrrev_i32_e32 v155, 31, v154
	v_lshlrev_b64 v[154:155], 11, v[154:155]
	v_lshl_add_u64 v[182:183], v[150:151], 0, v[154:155]
	s_nop 1
	s_nop 0
	s_nop 1
	s_nop 1
	s_nop 1
	v_mov_b32_e32 v178, v239
	v_pk_mul_f32 v[156:157], v[62:63], v[178:179] op_sel_hi:[1,0]
	v_pk_mul_f32 v[154:155], v[60:61], v[178:179] op_sel_hi:[1,0]
	v_pk_mul_f32 v[172:173], v[58:59], v[178:179] op_sel_hi:[1,0]
	v_pk_mul_f32 v[170:171], v[56:57], v[178:179] op_sel_hi:[1,0]
	v_pk_mul_f32 v[176:177], v[54:55], v[178:179] op_sel_hi:[1,0]
	v_pk_mul_f32 v[174:175], v[52:53], v[178:179] op_sel_hi:[1,0]
	v_pk_mul_f32 v[180:181], v[50:51], v[178:179] op_sel_hi:[1,0]
	v_pk_mul_f32 v[178:179], v[48:49], v[178:179] op_sel_hi:[1,0]
	global_store_dwordx4 v[182:183], v[154:157], off
	global_store_dwordx4 v[182:183], v[170:173], off offset:16
	global_store_dwordx4 v[182:183], v[174:177], off offset:512
	global_store_dwordx4 v[182:183], v[178:181], off offset:528
	s_waitcnt vmcnt(22)
	v_mov_b32_e32 v147, v232
	v_add_u32_e32 v154, 0xa0, v148
	v_add_u32_e32 v156, s14, v154
	v_ashrrev_i32_e32 v157, 31, v156
	v_lshl_add_u64 v[182:183], v[156:157], 2, s[38:39]
	v_ashrrev_i32_e32 v153, 31, v152
	v_lshlrev_b64 v[152:153], 11, v[152:153]
	v_lshl_add_u64 v[152:153], v[150:151], 0, v[152:153]
	s_nop 1
	s_nop 0
	s_nop 1
	s_nop 1
	s_nop 1
	v_mov_b32_e32 v178, v232
	v_pk_mul_f32 v[158:159], v[46:47], v[178:179] op_sel_hi:[1,0]
	v_pk_mul_f32 v[156:157], v[44:45], v[178:179] op_sel_hi:[1,0]
	v_pk_mul_f32 v[172:173], v[42:43], v[178:179] op_sel_hi:[1,0]
	v_pk_mul_f32 v[170:171], v[40:41], v[178:179] op_sel_hi:[1,0]
	v_pk_mul_f32 v[176:177], v[38:39], v[178:179] op_sel_hi:[1,0]
	v_pk_mul_f32 v[174:175], v[36:37], v[178:179] op_sel_hi:[1,0]
	v_pk_mul_f32 v[180:181], v[34:35], v[178:179] op_sel_hi:[1,0]
	v_pk_mul_f32 v[178:179], v[32:33], v[178:179] op_sel_hi:[1,0]
	global_store_dwordx4 v[152:153], v[156:159], off
	global_store_dwordx4 v[152:153], v[170:173], off offset:16
	global_store_dwordx4 v[152:153], v[174:177], off offset:512
	global_store_dwordx4 v[152:153], v[178:181], off offset:528
	s_waitcnt vmcnt(25)
	v_mov_b32_e32 v147, v233
	v_add_u32_e32 v152, 0xb0, v148
	v_add_u32_e32 v156, s14, v152
	v_ashrrev_i32_e32 v157, 31, v156
	v_lshl_add_u64 v[158:159], v[156:157], 2, s[38:39]
	v_ashrrev_i32_e32 v155, 31, v154
	v_lshlrev_b64 v[154:155], 11, v[154:155]
	v_lshl_add_u64 v[182:183], v[150:151], 0, v[154:155]
	s_nop 1
	s_nop 0
	s_nop 1
	s_nop 1
	s_nop 1
	v_mov_b32_e32 v178, v233
	v_pk_mul_f32 v[156:157], v[30:31], v[178:179] op_sel_hi:[1,0]
	v_pk_mul_f32 v[154:155], v[28:29], v[178:179] op_sel_hi:[1,0]
	v_pk_mul_f32 v[172:173], v[26:27], v[178:179] op_sel_hi:[1,0]
	v_pk_mul_f32 v[170:171], v[24:25], v[178:179] op_sel_hi:[1,0]
	v_pk_mul_f32 v[176:177], v[22:23], v[178:179] op_sel_hi:[1,0]
	v_pk_mul_f32 v[174:175], v[20:21], v[178:179] op_sel_hi:[1,0]
	v_pk_mul_f32 v[180:181], v[18:19], v[178:179] op_sel_hi:[1,0]
	v_pk_mul_f32 v[178:179], v[16:17], v[178:179] op_sel_hi:[1,0]
	global_store_dwordx4 v[182:183], v[154:157], off
	global_store_dwordx4 v[182:183], v[170:173], off offset:16
	global_store_dwordx4 v[182:183], v[174:177], off offset:512
	global_store_dwordx4 v[182:183], v[178:181], off offset:528
	s_waitcnt vmcnt(28)
	v_mov_b32_e32 v147, v234
	v_ashrrev_i32_e32 v153, 31, v152
	v_lshlrev_b64 v[152:153], 11, v[152:153]
	v_lshl_add_u64 v[158:159], v[150:151], 0, v[152:153]
	s_nop 1
	s_nop 0
	s_nop 1
	s_nop 1
	s_nop 1
	v_mov_b32_e32 v174, v234
	v_pk_mul_f32 v[152:153], v[14:15], v[174:175] op_sel_hi:[1,0]
	v_pk_mul_f32 v[150:151], v[12:13], v[174:175] op_sel_hi:[1,0]
	v_pk_mul_f32 v[156:157], v[10:11], v[174:175] op_sel_hi:[1,0]
	v_pk_mul_f32 v[154:155], v[8:9], v[174:175] op_sel_hi:[1,0]
	v_pk_mul_f32 v[172:173], v[6:7], v[174:175] op_sel_hi:[1,0]
	v_pk_mul_f32 v[170:171], v[4:5], v[174:175] op_sel_hi:[1,0]
	v_pk_mul_f32 v[176:177], v[2:3], v[174:175] op_sel_hi:[1,0]
	v_pk_mul_f32 v[174:175], v[0:1], v[174:175] op_sel_hi:[1,0]
	global_store_dwordx4 v[158:159], v[150:153], off
	global_store_dwordx4 v[158:159], v[154:157], off offset:16
	global_store_dwordx4 v[158:159], v[170:173], off offset:512
	global_store_dwordx4 v[158:159], v[174:177], off offset:528

; DI float rs_of(const float* ss, int row) { return 1.0f / sqrtf(ss[row] * (1.0f / DM) + EPS); }
;     DI void operator()(AccRef acc, const Unit& u, int wr, int wc, int fr, int fq) const {
;     ...
;         } else if (pn < 12) {
;             const bool isv = pn >= 8; const int c0 = (pn - (isv ? 8 : 4)) * 256 + cc0;
;             const bool f32out = smp || ((pm & 15) >= 14);
;             float* fo = out + (smp ? (isv ? O_AVS : O_AKS) : (isv ? O_AVP : O_AKP));
; #pragma unroll
;             for (int ai = 0; ai < 2; ++ai)
; #pragma unroll
;                 for (int m = 0; m < 4; ++m) {
;                     const int rl = rl0 + ai * 128 + m * 16; const float r = rs_of(ss, pm * 256 + rl);
;                     int b, s; if (smp) { b = rl >> 5; s = rl & 31; } else { b = pm >> 4; s = (pm & 15) * 256 + rl; }
;                     if (f32out) { const size_t orow = smp ? (size_t)rl : (size_t)b * 512 + (s - 3584);
.LBB0_537:
	s_andn2_b64 vcc, exec, s[10:11]
	s_cbranch_vccnz .LBB0_683
	s_cmp_lt_u32 s58, 8
	s_cselect_b64 s[14:15], -1, 0
	s_cmp_gt_u32 s58, 7
	s_mov_b32 s1, 0x4480000
	s_cselect_b32 s0, -8, -4
	s_cselect_b32 s4, s1, 0x4080000
	s_mov_b32 s1, 0x5ac0000
	s_cselect_b32 s5, s1, 0x5a80000
	s_add_i32 s0, s0, s58
	s_and_b32 s10, s56, 15
	s_cmp_gt_u32 s10, 13
	v_lshl_add_u32 v150, s0, 8, v146
	s_cselect_b64 s[0:1], -1, 0
	s_or_b64 s[64:65], s[12:13], s[0:1]
	s_and_b64 s[0:1], s[12:13], exec
	s_cselect_b32 s0, s5, s4
	s_lshl_b32 s0, s0, 2
	s_add_u32 s0, s20, s0
	s_addc_u32 s1, s21, 0
	s_lshl_b32 s49, s56, 8
	v_add_u32_e32 v154, s49, v148
	v_ashrrev_i32_e32 v155, 31, v154
	v_lshl_add_u64 v[154:155], v[154:155], 2, s[38:39]
	v_mov_b64_e32 v[240:241], v[154:155]
	v_mov_b32_e32 v235, 0
	global_load_dword v192, v[240:241], off
	v_mov_b32_e32 v234, 0x40
	v_lshl_add_u64 v[240:241], v[240:241], 0, v[234:235]
	global_load_dword v215, v[240:241], off
	v_mov_b32_e32 v234, 0x40
	v_lshl_add_u64 v[240:241], v[240:241], 0, v[234:235]
	global_load_dword v236, v[240:241], off
	v_mov_b32_e32 v234, 0x40
	v_lshl_add_u64 v[240:241], v[240:241], 0, v[234:235]
	global_load_dword v237, v[240:241], off
	v_mov_b32_e32 v234, 0x140
	v_lshl_add_u64 v[240:241], v[240:241], 0, v[234:235]
	global_load_dword v238, v[240:241], off
	v_mov_b32_e32 v234, 0x40
	v_lshl_add_u64 v[240:241], v[240:241], 0, v[234:235]
	global_load_dword v239, v[240:241], off
	v_mov_b32_e32 v234, 0x40
	v_lshl_add_u64 v[240:241], v[240:241], 0, v[234:235]
	global_load_dword v232, v[240:241], off
	v_mov_b32_e32 v234, 0x40
	v_lshl_add_u64 v[240:241], v[240:241], 0, v[234:235]
	global_load_dword v233, v[240:241], off
	s_waitcnt vmcnt(0)
	v_mov_b32_e32 v147, v192
	s_lshl_b32 s60, s10, 8
	v_ashrrev_i32_e32 v151, 31, v150
	v_lshl_add_u64 v[152:153], v[150:151], 2, s[0:1]
	s_ashr_i32 s62, s56, 4
	s_nop 0
	s_nop 0
	s_nop 0
	s_nop 1
	s_nop 1
	s_nop 0
	v_mov_b32_e32 v154, v192
	v_cndmask_b32_e64 v147, 0, 1, s[64:65]
	v_add_u32_e32 v156, s60, v148
	v_cmp_ne_u32_e64 s[10:11], 1, v147
	s_andn2_b64 vcc, exec, s[64:65]
	s_cbranch_vccnz .LBB0_544
	s_mov_b64 s[12:13], -1
	s_and_b64 vcc, exec, s[16:17]
	s_cbranch_vccz .LBB0_541
	s_ashr_i32 s63, s62, 31
	v_add_u32_e32 v158, 0xfffff200, v156
	s_lshl_b64 s[0:1], s[62:63], 9
	v_ashrrev_i32_e32 v159, 31, v158
	v_lshl_add_u64 v[158:159], s[0:1], 0, v[158:159]
	s_mov_b64 s[12:13], 0

; DI float rs_of(const float* ss, int row) { return 1.0f / sqrtf(ss[row] * (1.0f / DM) + EPS); }
;     DI void operator()(AccRef acc, const Unit& u, int wr, int wc, int fr, int fq) const {
;     ...
;                 for (int m = 0; m < 4; ++m) {
;                     const int rl = rl0 + ai * 128 + m * 16; const float r = rs_of(ss, pm * 256 + rl);
;                     int b, s; if (smp) { b = rl >> 5; s = rl & 31; } else { b = pm >> 4; s = (pm & 15) * 256 + rl; }
;                     if (f32out) { const size_t orow = smp ? (size_t)rl : (size_t)b * 512 + (s - 3584);
.LBB0_556:
	v_add_u32_e32 v156, 16, v148
	v_add_u32_e32 v154, s49, v156
	v_ashrrev_i32_e32 v155, 31, v154
	v_lshl_add_u64 v[154:155], v[154:155], 2, s[38:39]
	v_mov_b32_e32 v147, v215
	s_nop 0
	s_nop 0
	s_nop 0
	s_nop 1
	s_nop 1
	s_nop 0
	v_mov_b32_e32 v154, v215
	v_cndmask_b32_e64 v147, 0, 1, s[16:17]
	s_and_b64 vcc, exec, s[10:11]
	v_cmp_ne_u32_e64 s[14:15], 1, v147
	s_cbranch_vccnz .LBB0_562
	s_and_b64 vcc, exec, s[14:15]
	s_mov_b64 s[16:17], -1
	s_cbranch_vccnz .LBB0_559
	v_add_u32_e32 v147, s60, v156
	s_ashr_i32 s63, s62, 31
	v_add_u32_e32 v158, 0xfffff200, v147
	s_lshl_b64 s[0:1], s[62:63], 9
	v_ashrrev_i32_e32 v159, 31, v158
	v_lshl_add_u64 v[158:159], s[0:1], 0, v[158:159]
	s_mov_b64 s[16:17], 0

; DI float rs_of(const float* ss, int row) { return 1.0f / sqrtf(ss[row] * (1.0f / DM) + EPS); }
;     DI void operator()(AccRef acc, const Unit& u, int wr, int wc, int fr, int fq) const {
;     ...
;                 for (int m = 0; m < 4; ++m) {
;                     const int rl = rl0 + ai * 128 + m * 16; const float r = rs_of(ss, pm * 256 + rl);
;                     int b, s; if (smp) { b = rl >> 5; s = rl & 31; } else { b = pm >> 4; s = (pm & 15) * 256 + rl; }
;                     if (f32out) { const size_t orow = smp ? (size_t)rl : (size_t)b * 512 + (s - 3584);
.LBB0_574:
	v_add_u32_e32 v156, 32, v148
	v_add_u32_e32 v154, s49, v156
	v_ashrrev_i32_e32 v155, 31, v154
	v_lshl_add_u64 v[154:155], v[154:155], 2, s[38:39]
	v_mov_b32_e32 v149, v236
	s_nop 1
	s_nop 0
	s_nop 1
	s_nop 1
	s_nop 1
	s_and_b64 vcc, exec, s[10:11]
	v_mov_b32_e32 v154, v236
	s_cbranch_vccnz .LBB0_581
	s_and_b64 vcc, exec, s[14:15]
	s_mov_b64 s[16:17], -1
	s_cbranch_vccnz .LBB0_577
	v_add_u32_e32 v149, s60, v156
	s_ashr_i32 s63, s62, 31
	v_add_u32_e32 v158, 0xfffff200, v149
	s_lshl_b64 s[0:1], s[62:63], 9
	v_ashrrev_i32_e32 v159, 31, v158
	v_lshl_add_u64 v[158:159], s[0:1], 0, v[158:159]
	s_mov_b64 s[16:17], 0

; DI float rs_of(const float* ss, int row) { return 1.0f / sqrtf(ss[row] * (1.0f / DM) + EPS); }
;     DI void operator()(AccRef acc, const Unit& u, int wr, int wc, int fr, int fq) const {
;     ...
;                 for (int m = 0; m < 4; ++m) {
;                     const int rl = rl0 + ai * 128 + m * 16; const float r = rs_of(ss, pm * 256 + rl);
;                     int b, s; if (smp) { b = rl >> 5; s = rl & 31; } else { b = pm >> 4; s = (pm & 15) * 256 + rl; }
;                     if (f32out) { const size_t orow = smp ? (size_t)rl : (size_t)b * 512 + (s - 3584);
.LBB0_592:
	s_nop 0
	v_add_u32_e32 v156, 48, v148
	v_add_u32_e32 v154, s49, v156
	v_ashrrev_i32_e32 v155, 31, v154
	v_lshl_add_u64 v[154:155], v[154:155], 2, s[38:39]
	v_mov_b32_e32 v149, v237
	s_nop 1
	s_nop 0
	s_nop 1
	s_nop 1
	s_nop 1
	s_and_b64 vcc, exec, s[10:11]
	v_mov_b32_e32 v154, v237
	s_cbranch_vccnz .LBB0_599
	s_and_b64 vcc, exec, s[14:15]
	s_mov_b64 s[16:17], -1
	s_cbranch_vccnz .LBB0_595
	v_add_u32_e32 v149, s60, v156
	s_ashr_i32 s63, s62, 31
	v_add_u32_e32 v158, 0xfffff200, v149
	s_lshl_b64 s[0:1], s[62:63], 9
	v_ashrrev_i32_e32 v159, 31, v158
	v_lshl_add_u64 v[158:159], s[0:1], 0, v[158:159]
	s_mov_b64 s[16:17], 0

; DI float rs_of(const float* ss, int row) { return 1.0f / sqrtf(ss[row] * (1.0f / DM) + EPS); }
;     DI void operator()(AccRef acc, const Unit& u, int wr, int wc, int fr, int fq) const {
;     ...
;                 for (int m = 0; m < 4; ++m) {
;                     const int rl = rl0 + ai * 128 + m * 16; const float r = rs_of(ss, pm * 256 + rl);
;                     int b, s; if (smp) { b = rl >> 5; s = rl & 31; } else { b = pm >> 4; s = (pm & 15) * 256 + rl; }
;                     if (f32out) { const size_t orow = smp ? (size_t)rl : (size_t)b * 512 + (s - 3584);
.LBB0_610:
	s_nop 0
	v_add_u32_e32 v156, 0x80, v148
	v_add_u32_e32 v154, s49, v156
	v_ashrrev_i32_e32 v155, 31, v154
	v_lshl_add_u64 v[154:155], v[154:155], 2, s[38:39]
	v_mov_b32_e32 v149, v238
	s_nop 1
	s_nop 0
	s_nop 1
	s_nop 1
	s_nop 1
	s_and_b64 vcc, exec, s[10:11]
	v_mov_b32_e32 v154, v238
	s_cbranch_vccnz .LBB0_617
	s_and_b64 vcc, exec, s[14:15]
	s_mov_b64 s[16:17], -1
	s_cbranch_vccnz .LBB0_613
	v_add_u32_e32 v149, s60, v156
	s_ashr_i32 s63, s62, 31
	v_add_u32_e32 v158, 0xfffff200, v149
	s_lshl_b64 s[0:1], s[62:63], 9
	v_ashrrev_i32_e32 v159, 31, v158
	v_lshl_add_u64 v[158:159], s[0:1], 0, v[158:159]
	s_mov_b64 s[16:17], 0

; DI float rs_of(const float* ss, int row) { return 1.0f / sqrtf(ss[row] * (1.0f / DM) + EPS); }
;     DI void operator()(AccRef acc, const Unit& u, int wr, int wc, int fr, int fq) const {
;     ...
;                 for (int m = 0; m < 4; ++m) {
;                     const int rl = rl0 + ai * 128 + m * 16; const float r = rs_of(ss, pm * 256 + rl);
;                     int b, s; if (smp) { b = rl >> 5; s = rl & 31; } else { b = pm >> 4; s = (pm & 15) * 256 + rl; }
;                     if (f32out) { const size_t orow = smp ? (size_t)rl : (size_t)b * 512 + (s - 3584);
.LBB0_628:
	s_nop 0
	v_add_u32_e32 v156, 0x90, v148
	v_add_u32_e32 v154, s49, v156
	v_ashrrev_i32_e32 v155, 31, v154
	v_lshl_add_u64 v[154:155], v[154:155], 2, s[38:39]
	v_mov_b32_e32 v149, v239
	s_nop 1
	s_nop 0
	s_nop 1
	s_nop 1
	s_nop 1
	s_and_b64 vcc, exec, s[10:11]
	v_mov_b32_e32 v154, v239
	s_cbranch_vccnz .LBB0_635
	s_and_b64 vcc, exec, s[14:15]
	s_mov_b64 s[16:17], -1
	s_cbranch_vccnz .LBB0_631
	v_add_u32_e32 v149, s60, v156
	s_ashr_i32 s63, s62, 31
	v_add_u32_e32 v158, 0xfffff200, v149
	s_lshl_b64 s[0:1], s[62:63], 9
	v_ashrrev_i32_e32 v159, 31, v158
	v_lshl_add_u64 v[158:159], s[0:1], 0, v[158:159]
	s_mov_b64 s[16:17], 0

; DI float rs_of(const float* ss, int row) { return 1.0f / sqrtf(ss[row] * (1.0f / DM) + EPS); }
;     DI void operator()(AccRef acc, const Unit& u, int wr, int wc, int fr, int fq) const {
;     ...
;                 for (int m = 0; m < 4; ++m) {
;                     const int rl = rl0 + ai * 128 + m * 16; const float r = rs_of(ss, pm * 256 + rl);
;                     int b, s; if (smp) { b = rl >> 5; s = rl & 31; } else { b = pm >> 4; s = (pm & 15) * 256 + rl; }
;                     if (f32out) { const size_t orow = smp ? (size_t)rl : (size_t)b * 512 + (s - 3584);
.LBB0_646:
	s_nop 0
	v_add_u32_e32 v156, 0xa0, v148
	v_add_u32_e32 v154, s49, v156
	v_ashrrev_i32_e32 v155, 31, v154
	v_lshl_add_u64 v[154:155], v[154:155], 2, s[38:39]
	v_mov_b32_e32 v149, v232
	s_nop 1
	s_nop 0
	s_nop 1
	s_nop 1
	s_nop 1
	s_and_b64 vcc, exec, s[10:11]
	v_mov_b32_e32 v154, v232
	s_cbranch_vccnz .LBB0_653
	s_and_b64 vcc, exec, s[14:15]
	s_mov_b64 s[16:17], -1
	s_cbranch_vccnz .LBB0_649
	v_add_u32_e32 v149, s60, v156
	s_ashr_i32 s63, s62, 31
	v_add_u32_e32 v158, 0xfffff200, v149
	s_lshl_b64 s[0:1], s[62:63], 9
	v_ashrrev_i32_e32 v159, 31, v158
	v_lshl_add_u64 v[158:159], s[0:1], 0, v[158:159]
	s_mov_b64 s[16:17], 0

; DI float rs_of(const float* ss, int row) { return 1.0f / sqrtf(ss[row] * (1.0f / DM) + EPS); }
;     DI void operator()(AccRef acc, const Unit& u, int wr, int wc, int fr, int fq) const {
;     ...
;                 for (int m = 0; m < 4; ++m) {
;                     const int rl = rl0 + ai * 128 + m * 16; const float r = rs_of(ss, pm * 256 + rl);
;                     int b, s; if (smp) { b = rl >> 5; s = rl & 31; } else { b = pm >> 4; s = (pm & 15) * 256 + rl; }
;                     if (f32out) { const size_t orow = smp ? (size_t)rl : (size_t)b * 512 + (s - 3584);
.LBB0_664:
	s_nop 0
	v_add_u32_e32 v156, 0xb0, v148
	v_add_u32_e32 v154, s49, v156
	v_ashrrev_i32_e32 v155, 31, v154
	v_lshl_add_u64 v[154:155], v[154:155], 2, s[38:39]
	v_mov_b32_e32 v137, v233
	s_nop 1
	s_nop 0
	s_nop 1
	s_nop 1
	s_nop 1
	s_and_b64 vcc, exec, s[10:11]
	v_mov_b32_e32 v154, v233
	s_cbranch_vccnz .LBB0_671
	s_and_b64 vcc, exec, s[14:15]
	s_mov_b64 s[10:11], -1
	s_cbranch_vccnz .LBB0_667
	v_add_u32_e32 v137, s60, v156
	s_ashr_i32 s63, s62, 31
	v_add_u32_e32 v158, 0xfffff200, v137
	s_lshl_b64 s[0:1], s[62:63], 9
	v_ashrrev_i32_e32 v159, 31, v158
	v_lshl_add_u64 v[158:159], s[0:1], 0, v[158:159]
	s_mov_b64 s[10:11], 0

; DI u32x4 pack8(f32x4 a, f32x4 b) { u32x4 w; w.x = cvt_pk_bf16(a[0], a[1]); w.y = cvt_pk_bf16(a[2], a[3]); w.z = cvt_pk_bf16(b[0], b[1]); w.w = cvt_pk_bf16(b[2], b[3]); return w; }
; DI float rs_of(const float* ss, int row) { return 1.0f / sqrtf(ss[row] * (1.0f / DM) + EPS); }
;     DI void operator()(AccRef acc, const Unit& u, int wr, int wc, int fr, int fq) const {
;     ...
;         if (pn < 4 || (pn >= 12 && pn < 15)) {
;             bf16_t* dst = (pn < 4) ? QA + pn * 256 : CQ + (pn - 12) * 256; const int ld = (pn < 4) ? 1024 : 768;
; #pragma unroll
;             for (int ai = 0; ai < 2; ++ai)
; #pragma unroll
;                 for (int m = 0; m < 4; ++m) { const size_t row = (size_t)pm * 256 + rl0 + ai * 128 + m * 16; const float r = rs_of(ss, (int)row) * ((pn < 4) ? 0.08838834764831845f * LOG2E : 1.0f);
; #pragma unroll
;                     for (int bj = 0; bj < 2; ++bj) *(u32x4*)(dst + row * ld + cc0 + bj * 128) = pack8((acc[ai][bj][m][0] * r), (acc[ai][bj][m][1] * r)); }
.LBB0_684:
	s_andn2_b64 vcc, exec, s[10:11]
	s_cbranch_vccnz .LBB0_519
	s_lshl_b32 s0, s58, 8
	s_ashr_i32 s1, s0, 31
	s_lshl_b64 s[4:5], s[0:1], 1
	s_add_u32 s4, s78, s4
	s_mov_b32 s1, s29
	s_addc_u32 s5, s79, s5
	s_lshl_b64 s[0:1], s[0:1], 1
	s_add_u32 s0, s22, s0
	s_addc_u32 s1, s23, s1
	s_add_u32 s10, s0, 0x23a01800
	s_addc_u32 s11, s1, 0
	s_and_b64 s[0:1], s[8:9], exec
	s_cselect_b32 s0, s69, 0x300
	s_cselect_b32 s1, s5, s11
	s_cselect_b32 s10, s4, s10
	s_ashr_i32 s57, s56, 31
	s_lshl_b64 s[4:5], s[56:57], 8
	v_ashrrev_i32_e32 v149, 31, v148
	v_lshl_add_u64 v[148:149], s[4:5], 0, v[148:149]
	v_mov_b32_e32 v137, v148
	v_ashrrev_i64 v[150:151], 30, v[136:137]
	v_lshl_add_u64 v[150:151], s[38:39], 0, v[150:151]
	v_mov_b64_e32 v[240:241], v[150:151]
	s_mov_b32 s13, 0
	global_load_dword v192, v[240:241], off
	s_mov_b32 s12, 0x40
	v_lshl_add_u64 v[240:241], v[240:241], 0, s[12:13]
	global_load_dword v236, v[240:241], off
	s_mov_b32 s12, 0x40
	v_lshl_add_u64 v[240:241], v[240:241], 0, s[12:13]
	global_load_dword v237, v[240:241], off
	s_mov_b32 s12, 0x40
	v_lshl_add_u64 v[240:241], v[240:241], 0, s[12:13]
	global_load_dword v238, v[240:241], off
	s_mov_b32 s12, 0x140
	v_lshl_add_u64 v[240:241], v[240:241], 0, s[12:13]
	global_load_dword v239, v[240:241], off
	s_mov_b32 s12, 0x40
	v_lshl_add_u64 v[240:241], v[240:241], 0, s[12:13]
	global_load_dword v232, v[240:241], off
	s_mov_b32 s12, 0x40
	v_lshl_add_u64 v[240:241], v[240:241], 0, s[12:13]
	global_load_dword v233, v[240:241], off
	s_mov_b32 s12, 0x40
	v_lshl_add_u64 v[240:241], v[240:241], 0, s[12:13]
	global_load_dword v234, v[240:241], off
	s_waitcnt vmcnt(7)
	v_mov_b32_e32 v137, v192
	v_cndmask_b32_e64 v150, 1.0, v169, s[8:9]
	v_ashrrev_i32_e32 v147, 31, v146
	v_mov_b32_e32 v152, s10
	v_mov_b32_e32 v153, s1
	v_lshl_add_u64 v[146:147], v[146:147], 1, v[152:153]
	v_mad_u64_u32 v[152:153], s[4:5], v148, s0, 0
	v_mad_i32_i24 v153, v149, s0, v153
	v_lshl_add_u64 v[152:153], v[152:153], 1, v[146:147]
	s_lshl_b32 s28, s0, 4
	s_mov_b32 s1, s29
	s_nop 1
	v_add_u32_e32 v137, 16, v148
	v_ashrrev_i64 v[154:155], 30, v[136:137]
	v_lshl_add_u64 v[154:155], s[38:39], 0, v[154:155]
	s_nop 1
	s_nop 1
	s_nop 1
	v_mov_b32_e32 v137, v192
	v_mul_f32_e32 v156, v150, v137
	v_pk_mul_f32 v[126:127], v[126:127], v[156:157] op_sel_hi:[1,0]
	v_pk_mul_f32 v[124:125], v[124:125], v[156:157] op_sel_hi:[1,0]
	v_pk_mul_f32 v[122:123], v[122:123], v[156:157] op_sel_hi:[1,0]
	v_pk_mul_f32 v[120:121], v[120:121], v[156:157] op_sel_hi:[1,0]
	v_pk_mul_f32 v[118:119], v[118:119], v[156:157] op_sel_hi:[1,0]
	v_pk_mul_f32 v[116:117], v[116:117], v[156:157] op_sel_hi:[1,0]
	v_pk_mul_f32 v[158:159], v[114:115], v[156:157] op_sel_hi:[1,0]
	v_pk_mul_f32 v[156:157], v[112:113], v[156:157] op_sel_hi:[1,0]
	v_cvt_pk_bf16_f32 v112, v124, v125
	v_cvt_pk_bf16_f32 v113, v126, v127
	v_cvt_pk_bf16_f32 v114, v120, v121
	v_cvt_pk_bf16_f32 v115, v122, v123
	global_store_dwordx4 v[152:153], v[112:115], off
	v_add_u32_e32 v137, 32, v148
	s_nop 0
	v_cvt_pk_bf16_f32 v112, v116, v117
	v_cvt_pk_bf16_f32 v113, v118, v119
	v_cvt_pk_bf16_f32 v114, v156, v157
	v_cvt_pk_bf16_f32 v115, v158, v159
	global_store_dwordx4 v[152:153], v[112:115], off offset:256
	s_waitcnt vmcnt(8)
	s_nop 1
	v_mov_b32_e32 v114, v236
	v_ashrrev_i64 v[116:117], 30, v[136:137]
	v_mov_b64_e32 v[112:113], s[28:29]
	v_mad_u64_u32 v[112:113], s[4:5], v148, s0, v[112:113]
	v_mad_i32_i24 v113, v149, s0, v113
	v_lshl_add_u64 v[116:117], s[38:39], 0, v[116:117]
	v_add_u32_e32 v137, 48, v148
	s_mulk_i32 s0, 0x50
	s_nop 1
	v_lshl_add_u64 v[114:115], v[112:113], 1, v[146:147]
	s_nop 1
	s_nop 1
	s_nop 1
	v_mov_b32_e32 v118, v236
	v_mul_f32_e32 v118, v150, v118
	v_pk_mul_f32 v[110:111], v[110:111], v[118:119] op_sel_hi:[1,0]
	v_pk_mul_f32 v[108:109], v[108:109], v[118:119] op_sel_hi:[1,0]
	v_pk_mul_f32 v[106:107], v[106:107], v[118:119] op_sel_hi:[1,0]
	v_pk_mul_f32 v[104:105], v[104:105], v[118:119] op_sel_hi:[1,0]
	v_pk_mul_f32 v[102:103], v[102:103], v[118:119] op_sel_hi:[1,0]
	v_pk_mul_f32 v[100:101], v[100:101], v[118:119] op_sel_hi:[1,0]
	v_pk_mul_f32 v[120:121], v[98:99], v[118:119] op_sel_hi:[1,0]
	v_pk_mul_f32 v[118:119], v[96:97], v[118:119] op_sel_hi:[1,0]
	v_cvt_pk_bf16_f32 v96, v108, v109
	v_cvt_pk_bf16_f32 v97, v110, v111
	v_cvt_pk_bf16_f32 v98, v104, v105
	v_cvt_pk_bf16_f32 v99, v106, v107
	global_store_dwordx4 v[114:115], v[96:99], off
	s_nop 1
	v_cvt_pk_bf16_f32 v96, v100, v101
	v_cvt_pk_bf16_f32 v97, v102, v103
	v_cvt_pk_bf16_f32 v98, v118, v119
	v_cvt_pk_bf16_f32 v99, v120, v121
	global_store_dwordx4 v[114:115], v[96:99], off offset:256
	s_waitcnt vmcnt(9)
	s_nop 1
	v_mov_b32_e32 v98, v237
	v_ashrrev_i64 v[100:101], 30, v[136:137]
	v_lshl_add_u64 v[96:97], v[112:113], 0, s[28:29]
	v_lshl_add_u64 v[100:101], s[38:39], 0, v[100:101]
	v_add_u32_e32 v137, 0x80, v148
	s_nop 1
	v_lshl_add_u64 v[98:99], v[96:97], 1, v[146:147]
	s_nop 1
	s_nop 1
	s_nop 1
	v_mov_b32_e32 v102, v237
	v_mul_f32_e32 v102, v150, v102
	v_pk_mul_f32 v[94:95], v[94:95], v[102:103] op_sel_hi:[1,0]
	v_pk_mul_f32 v[92:93], v[92:93], v[102:103] op_sel_hi:[1,0]
	v_pk_mul_f32 v[90:91], v[90:91], v[102:103] op_sel_hi:[1,0]
	v_pk_mul_f32 v[88:89], v[88:89], v[102:103] op_sel_hi:[1,0]
	v_pk_mul_f32 v[86:87], v[86:87], v[102:103] op_sel_hi:[1,0]
	v_pk_mul_f32 v[84:85], v[84:85], v[102:103] op_sel_hi:[1,0]
	v_pk_mul_f32 v[104:105], v[82:83], v[102:103] op_sel_hi:[1,0]
	v_pk_mul_f32 v[102:103], v[80:81], v[102:103] op_sel_hi:[1,0]
	v_cvt_pk_bf16_f32 v80, v92, v93
	v_cvt_pk_bf16_f32 v81, v94, v95
	v_cvt_pk_bf16_f32 v82, v88, v89
	v_cvt_pk_bf16_f32 v83, v90, v91
	global_store_dwordx4 v[98:99], v[80:83], off
	s_nop 1
	v_cvt_pk_bf16_f32 v80, v84, v85
	v_cvt_pk_bf16_f32 v81, v86, v87
	v_cvt_pk_bf16_f32 v82, v102, v103
	v_cvt_pk_bf16_f32 v83, v104, v105
	global_store_dwordx4 v[98:99], v[80:83], off offset:256
	s_waitcnt vmcnt(10)
; DI u32x4 pack8(f32x4 a, f32x4 b) { u32x4 w; w.x = cvt_pk_bf16(a[0], a[1]); w.y = cvt_pk_bf16(a[2], a[3]); w.z = cvt_pk_bf16(b[0], b[1]); w.w = cvt_pk_bf16(b[2], b[3]); return w; }
; DI float rs_of(const float* ss, int row) { return 1.0f / sqrtf(ss[row] * (1.0f / DM) + EPS); }
;     DI void operator()(AccRef acc, const Unit& u, int wr, int wc, int fr, int fq) const {
;     ...
; #pragma unroll
;             for (int ai = 0; ai < 2; ++ai)
; #pragma unroll
;                 for (int m = 0; m < 4; ++m) { const size_t row = (size_t)pm * 256 + rl0 + ai * 128 + m * 16; const float r = rs_of(ss, (int)row) * ((pn < 4) ? 0.08838834764831845f * LOG2E : 1.0f);
; #pragma unroll
;                     for (int bj = 0; bj < 2; ++bj) *(u32x4*)(dst + row * ld + cc0 + bj * 128) = pack8((acc[ai][bj][m][0] * r), (acc[ai][bj][m][1] * r)); }
	s_nop 1
	v_mov_b32_e32 v82, v238
	v_ashrrev_i64 v[84:85], 30, v[136:137]
	v_lshl_add_u64 v[80:81], v[96:97], 0, s[28:29]
	v_lshl_add_u64 v[84:85], s[38:39], 0, v[84:85]
	v_add_u32_e32 v137, 0x90, v148
	s_nop 1
	v_lshl_add_u64 v[82:83], v[80:81], 1, v[146:147]
	s_nop 1
	s_nop 1
	s_nop 1
	v_mov_b32_e32 v86, v238
	v_mul_f32_e32 v86, v150, v86
	v_pk_mul_f32 v[78:79], v[78:79], v[86:87] op_sel_hi:[1,0]
	v_pk_mul_f32 v[76:77], v[76:77], v[86:87] op_sel_hi:[1,0]
	v_pk_mul_f32 v[74:75], v[74:75], v[86:87] op_sel_hi:[1,0]
	v_pk_mul_f32 v[72:73], v[72:73], v[86:87] op_sel_hi:[1,0]
	v_pk_mul_f32 v[70:71], v[70:71], v[86:87] op_sel_hi:[1,0]
	v_pk_mul_f32 v[68:69], v[68:69], v[86:87] op_sel_hi:[1,0]
	v_pk_mul_f32 v[88:89], v[66:67], v[86:87] op_sel_hi:[1,0]
	v_pk_mul_f32 v[86:87], v[64:65], v[86:87] op_sel_hi:[1,0]
	v_cvt_pk_bf16_f32 v64, v76, v77
	v_cvt_pk_bf16_f32 v65, v78, v79
	v_cvt_pk_bf16_f32 v66, v72, v73
	v_cvt_pk_bf16_f32 v67, v74, v75
	global_store_dwordx4 v[82:83], v[64:67], off
	s_nop 1
	v_cvt_pk_bf16_f32 v64, v68, v69
	v_cvt_pk_bf16_f32 v65, v70, v71
	v_cvt_pk_bf16_f32 v66, v86, v87
	v_cvt_pk_bf16_f32 v67, v88, v89
	global_store_dwordx4 v[82:83], v[64:67], off offset:256
	s_waitcnt vmcnt(11)
	s_nop 1
	v_mov_b32_e32 v66, v239
	v_ashrrev_i64 v[68:69], 30, v[136:137]
	v_lshl_add_u64 v[64:65], v[80:81], 0, s[0:1]
	v_lshl_add_u64 v[68:69], s[38:39], 0, v[68:69]
	v_add_u32_e32 v137, 0xa0, v148
	s_nop 1
	v_lshl_add_u64 v[66:67], v[64:65], 1, v[146:147]
	s_nop 1
	s_nop 1
	s_nop 1
	v_mov_b32_e32 v70, v239
	v_mul_f32_e32 v70, v150, v70
	v_pk_mul_f32 v[62:63], v[62:63], v[70:71] op_sel_hi:[1,0]
	v_pk_mul_f32 v[60:61], v[60:61], v[70:71] op_sel_hi:[1,0]
	v_pk_mul_f32 v[58:59], v[58:59], v[70:71] op_sel_hi:[1,0]
	v_pk_mul_f32 v[56:57], v[56:57], v[70:71] op_sel_hi:[1,0]
	v_pk_mul_f32 v[54:55], v[54:55], v[70:71] op_sel_hi:[1,0]
	v_pk_mul_f32 v[52:53], v[52:53], v[70:71] op_sel_hi:[1,0]
	v_pk_mul_f32 v[72:73], v[50:51], v[70:71] op_sel_hi:[1,0]
	v_pk_mul_f32 v[70:71], v[48:49], v[70:71] op_sel_hi:[1,0]
	v_cvt_pk_bf16_f32 v48, v60, v61
	v_cvt_pk_bf16_f32 v49, v62, v63
	v_cvt_pk_bf16_f32 v50, v56, v57
	v_cvt_pk_bf16_f32 v51, v58, v59
	global_store_dwordx4 v[66:67], v[48:51], off
	s_nop 1
	v_cvt_pk_bf16_f32 v48, v52, v53
	v_cvt_pk_bf16_f32 v49, v54, v55
	v_cvt_pk_bf16_f32 v50, v70, v71
	v_cvt_pk_bf16_f32 v51, v72, v73
	global_store_dwordx4 v[66:67], v[48:51], off offset:256
	s_waitcnt vmcnt(12)
	s_nop 1
	v_mov_b32_e32 v50, v232
	v_ashrrev_i64 v[52:53], 30, v[136:137]
	v_lshl_add_u64 v[48:49], v[64:65], 0, s[28:29]
	v_lshl_add_u64 v[52:53], s[38:39], 0, v[52:53]
	v_add_u32_e32 v137, 0xb0, v148
	s_nop 1
	v_lshl_add_u64 v[50:51], v[48:49], 1, v[146:147]
	s_nop 1
	s_nop 1
	s_nop 1
	v_mov_b32_e32 v54, v232
	v_mul_f32_e32 v54, v150, v54
	v_pk_mul_f32 v[46:47], v[46:47], v[54:55] op_sel_hi:[1,0]
	v_pk_mul_f32 v[44:45], v[44:45], v[54:55] op_sel_hi:[1,0]
	v_pk_mul_f32 v[42:43], v[42:43], v[54:55] op_sel_hi:[1,0]
	v_pk_mul_f32 v[40:41], v[40:41], v[54:55] op_sel_hi:[1,0]
	v_pk_mul_f32 v[38:39], v[38:39], v[54:55] op_sel_hi:[1,0]
	v_pk_mul_f32 v[36:37], v[36:37], v[54:55] op_sel_hi:[1,0]
	v_pk_mul_f32 v[56:57], v[34:35], v[54:55] op_sel_hi:[1,0]
	v_pk_mul_f32 v[54:55], v[32:33], v[54:55] op_sel_hi:[1,0]
	v_cvt_pk_bf16_f32 v32, v44, v45
	v_cvt_pk_bf16_f32 v33, v46, v47
	v_cvt_pk_bf16_f32 v34, v40, v41
	v_cvt_pk_bf16_f32 v35, v42, v43
	global_store_dwordx4 v[50:51], v[32:35], off
	s_nop 1
	v_cvt_pk_bf16_f32 v32, v36, v37
	v_cvt_pk_bf16_f32 v33, v38, v39
	v_cvt_pk_bf16_f32 v34, v54, v55
	v_cvt_pk_bf16_f32 v35, v56, v57
	global_store_dwordx4 v[50:51], v[32:35], off offset:256
	s_waitcnt vmcnt(13)
	s_nop 1
	v_mov_b32_e32 v34, v233
	v_ashrrev_i64 v[36:37], 30, v[136:137]
	v_lshl_add_u64 v[32:33], v[48:49], 0, s[28:29]
	v_lshl_add_u64 v[36:37], s[38:39], 0, v[36:37]
	s_nop 1
	v_lshl_add_u64 v[34:35], v[32:33], 1, v[146:147]
	s_nop 1
	s_nop 1
	s_nop 1
	v_mov_b32_e32 v38, v233
	v_mul_f32_e32 v38, v150, v38
	v_pk_mul_f32 v[30:31], v[30:31], v[38:39] op_sel_hi:[1,0]
	v_pk_mul_f32 v[28:29], v[28:29], v[38:39] op_sel_hi:[1,0]
	v_pk_mul_f32 v[26:27], v[26:27], v[38:39] op_sel_hi:[1,0]
	v_pk_mul_f32 v[24:25], v[24:25], v[38:39] op_sel_hi:[1,0]
	v_pk_mul_f32 v[22:23], v[22:23], v[38:39] op_sel_hi:[1,0]
	v_pk_mul_f32 v[20:21], v[20:21], v[38:39] op_sel_hi:[1,0]
	v_pk_mul_f32 v[40:41], v[18:19], v[38:39] op_sel_hi:[1,0]
	v_pk_mul_f32 v[38:39], v[16:17], v[38:39] op_sel_hi:[1,0]
	v_cvt_pk_bf16_f32 v16, v28, v29
	v_cvt_pk_bf16_f32 v17, v30, v31
	v_cvt_pk_bf16_f32 v18, v24, v25
	v_cvt_pk_bf16_f32 v19, v26, v27
	global_store_dwordx4 v[34:35], v[16:19], off
	s_nop 1
	v_cvt_pk_bf16_f32 v16, v20, v21
	v_cvt_pk_bf16_f32 v17, v22, v23
	v_cvt_pk_bf16_f32 v18, v38, v39
	v_cvt_pk_bf16_f32 v19, v40, v41
	global_store_dwordx4 v[34:35], v[16:19], off offset:256
	s_waitcnt vmcnt(14)
	s_nop 1
	v_mov_b32_e32 v16, v234
	s_nop 1
	v_lshl_add_u64 v[16:17], v[32:33], 0, s[28:29]
	v_lshl_add_u64 v[16:17], v[16:17], 1, v[146:147]
	s_nop 1
	s_nop 1
	s_nop 1
	v_mov_b32_e32 v18, v234
	v_mul_f32_e32 v18, v150, v18
	v_pk_mul_f32 v[14:15], v[14:15], v[18:19] op_sel_hi:[1,0]
	v_pk_mul_f32 v[12:13], v[12:13], v[18:19] op_sel_hi:[1,0]
	v_pk_mul_f32 v[10:11], v[10:11], v[18:19] op_sel_hi:[1,0]
	v_pk_mul_f32 v[8:9], v[8:9], v[18:19] op_sel_hi:[1,0]
	v_pk_mul_f32 v[6:7], v[6:7], v[18:19] op_sel_hi:[1,0]
	v_pk_mul_f32 v[4:5], v[4:5], v[18:19] op_sel_hi:[1,0]
	v_pk_mul_f32 v[20:21], v[2:3], v[18:19] op_sel_hi:[1,0]
	v_pk_mul_f32 v[18:19], v[0:1], v[18:19] op_sel_hi:[1,0]
	v_cvt_pk_bf16_f32 v0, v12, v13
	v_cvt_pk_bf16_f32 v1, v14, v15
	v_cvt_pk_bf16_f32 v2, v8, v9
	v_cvt_pk_bf16_f32 v3, v10, v11
	global_store_dwordx4 v[16:17], v[0:3], off
	s_nop 1
	v_cvt_pk_bf16_f32 v0, v4, v5
	v_cvt_pk_bf16_f32 v1, v6, v7
	v_cvt_pk_bf16_f32 v2, v18, v19
	v_cvt_pk_bf16_f32 v3, v20, v21
	global_store_dwordx4 v[16:17], v[0:3], off offset:256
	s_branch .LBB0_519

; DI float sigmoidf_(float x) { return __builtin_amdgcn_rcpf(1.0f + __builtin_amdgcn_exp2f(-x * LOG2E)); }
; DI u32x4 pack8(f32x4 a, f32x4 b) { u32x4 w; w.x = cvt_pk_bf16(a[0], a[1]); w.y = cvt_pk_bf16(a[2], a[3]); w.z = cvt_pk_bf16(b[0], b[1]); w.w = cvt_pk_bf16(b[2], b[3]); return w; }
; DI float rs_of(const float* ss, int row) { return 1.0f / sqrtf(ss[row] * (1.0f / DM) + EPS); }
;     DI void operator()(AccRef acc, const Unit& u, int wr, int wc, int fr, int fq) const {
;         const int col0 = u.pn * 128 + wc * 32 + 8 * fq;
; #pragma unroll
;         for (int ai = 0; ai < 2; ++ai)
; #pragma unroll
;             for (int m = 0; m < 4; ++m) { const int row = u.pm * 256 + ai * 128 + wr * 64 + m * 16 + fr; const float r = rs_of(ss, row); f32x4 ra[2], sb[2];
; #pragma unroll
;                 for (int n = 0; n < 2; ++n)
; #pragma unroll
;                     for (int j = 0; j < 4; ++j) { const float a = sigmoidf_(acc[ai][0][m][n][j] * r), b = fmaxf(sigmoidf_(acc[ai][1][m][n][j] * r), 1e-4f); sb[n][j] = b; ra[n][j] = a * __builtin_amdgcn_rcpf(b); }
;                 *(u32x4*)(RAT + (size_t)row * DM + col0) = pack8(ra[0], ra[1]); *(u32x4*)(SB + (size_t)row * DM + col0) = pack8(sb[0], sb[1]); }
.LBB0_1351:
	v_mov_b32_e32 v134, v192
	v_mov_b32_e32 v1, v194
	s_mov_b64 s[40:41], -1
	s_and_b64 vcc, exec, s[8:9]
	s_cbranch_vccz .LBB0_1353
	s_add_i32 s0, s31, s57
	v_add_u32_e32 v2, s0, v1
	v_ashrrev_i32_e32 v3, 31, v2
	v_lshl_add_u64 v[132:133], v[2:3], 2, s[14:15]
	v_mov_b64_e32 v[166:167], v[132:133]
	s_mov_b32 s5, 0
	global_load_dword v157, v[166:167], off
	s_mov_b32 s4, 0x40
	v_lshl_add_u64 v[166:167], v[166:167], 0, s[4:5]
	global_load_dword v207, v[166:167], off
	s_mov_b32 s4, 0x40
	v_lshl_add_u64 v[166:167], v[166:167], 0, s[4:5]
	global_load_dword v240, v[166:167], off
	s_mov_b32 s4, 0x40
	v_lshl_add_u64 v[166:167], v[166:167], 0, s[4:5]
	global_load_dword v241, v[166:167], off
	s_mov_b32 s4, 0x140
	v_lshl_add_u64 v[166:167], v[166:167], 0, s[4:5]
	global_load_dword v242, v[166:167], off
	s_mov_b32 s4, 0x40
	v_lshl_add_u64 v[166:167], v[166:167], 0, s[4:5]
	global_load_dword v243, v[166:167], off
	s_mov_b32 s4, 0x40
	v_lshl_add_u64 v[166:167], v[166:167], 0, s[4:5]
	global_load_dword v236, v[166:167], off
	s_mov_b32 s4, 0x40
	v_lshl_add_u64 v[166:167], v[166:167], 0, s[4:5]
	global_load_dword v237, v[166:167], off
	s_waitcnt vmcnt(7)
	v_mov_b32_e32 v132, v157
	s_lshl_b32 s0, s34, 7
	s_or_b32 s0, s0, s58
	s_add_i32 s0, s0, s35
	s_mov_b64 s[40:41], 0
	s_nop 1
	v_lshl_add_u32 v132, v134, 3, s0
	s_nop 1
	s_nop 1
	s_nop 1
	v_ashrrev_i32_e32 v133, 31, v132
	v_mov_b32_e32 v135, v157
	v_mul_f32_e32 v137, v120, v135
	v_mul_f32_e32 v139, v121, v135
	v_mul_f32_e32 v141, v122, v135
	v_mul_f32_e32 v137, 0xbfb8aa3b, v137
	v_mul_f32_e32 v139, 0xbfb8aa3b, v139
	v_mul_f32_e32 v141, 0xbfb8aa3b, v141
	v_exp_f32_e32 v137, v137
	v_exp_f32_e32 v139, v139
	v_exp_f32_e32 v141, v141
	v_mul_f32_e32 v136, v128, v135
	v_mul_f32_e32 v138, v129, v135
	v_mul_f32_e32 v140, v130, v135
	v_mul_f32_e32 v136, 0xbfb8aa3b, v136
	v_mul_f32_e32 v138, 0xbfb8aa3b, v138
	v_mul_f32_e32 v140, 0xbfb8aa3b, v140
	v_add_f32_e32 v137, 1.0, v137
	v_add_f32_e32 v139, 1.0, v139
	v_add_f32_e32 v141, 1.0, v141
	v_exp_f32_e32 v136, v136
	v_exp_f32_e32 v138, v138
	v_exp_f32_e32 v140, v140
	v_rcp_f32_e32 v137, v137
	v_rcp_f32_e32 v139, v139
	v_rcp_f32_e32 v141, v141
	v_add_f32_e32 v136, 1.0, v136
	v_add_f32_e32 v138, 1.0, v138
	v_add_f32_e32 v140, 1.0, v140
	v_max_f32_e32 v150, 0x38d1b717, v137
	v_max_f32_e32 v151, 0x38d1b717, v139
	v_max_f32_e32 v152, 0x38d1b717, v141
	v_rcp_f32_e32 v136, v136
	v_rcp_f32_e32 v138, v138
	v_rcp_f32_e32 v140, v140
	v_rcp_f32_e32 v137, v150
	v_rcp_f32_e32 v139, v151
	v_rcp_f32_e32 v141, v152
	v_mul_f32_e32 v143, v123, v135
	v_mul_f32_e32 v149, v118, v135
	v_mul_f32_e32 v145, v116, v135
	v_mul_f32_e32 v147, v117, v135
	v_mul_f32_e32 v143, 0xbfb8aa3b, v143
	v_mul_f32_e32 v149, 0xbfb8aa3b, v149
	v_mul_f32_e32 v136, v136, v137
	v_mul_f32_e32 v137, v138, v139
	v_mul_f32_e32 v138, v140, v141
	v_mul_f32_e32 v140, v119, v135
	v_mul_f32_e32 v145, 0xbfb8aa3b, v145
	v_mul_f32_e32 v147, 0xbfb8aa3b, v147
	v_exp_f32_e32 v143, v143
	v_exp_f32_e32 v149, v149
	v_mul_f32_e32 v140, 0xbfb8aa3b, v140
	v_exp_f32_e32 v145, v145
	v_exp_f32_e32 v147, v147
	v_exp_f32_e32 v140, v140
	v_mul_f32_e32 v142, v131, v135
	v_mul_f32_e32 v148, v126, v135
	v_mul_f32_e32 v144, v124, v135
	v_mul_f32_e32 v146, v125, v135
	v_mul_f32_e32 v142, 0xbfb8aa3b, v142
	v_mul_f32_e32 v148, 0xbfb8aa3b, v148
	v_add_f32_e32 v143, 1.0, v143
	v_add_f32_e32 v149, 1.0, v149
	v_mul_f32_e32 v135, v127, v135
	v_mul_f32_e32 v144, 0xbfb8aa3b, v144
	v_mul_f32_e32 v146, 0xbfb8aa3b, v146
	v_exp_f32_e32 v142, v142
	v_exp_f32_e32 v148, v148
	v_add_f32_e32 v145, 1.0, v145
	v_add_f32_e32 v147, 1.0, v147
	v_rcp_f32_e32 v143, v143
	v_rcp_f32_e32 v149, v149
	v_mul_f32_e32 v135, 0xbfb8aa3b, v135
	v_add_f32_e32 v140, 1.0, v140
	v_exp_f32_e32 v144, v144
	v_exp_f32_e32 v146, v146
	v_rcp_f32_e32 v145, v145
	v_rcp_f32_e32 v147, v147
	v_exp_f32_e32 v135, v135
	v_rcp_f32_e32 v140, v140
	v_add_f32_e32 v142, 1.0, v142
	v_add_f32_e32 v148, 1.0, v148
	v_max_f32_e32 v153, 0x38d1b717, v143
	v_max_f32_e32 v149, 0x38d1b717, v149
	v_add_f32_e32 v144, 1.0, v144
	v_add_f32_e32 v146, 1.0, v146
	v_rcp_f32_e32 v142, v142
	v_rcp_f32_e32 v148, v148
	v_max_f32_e32 v145, 0x38d1b717, v145
	v_max_f32_e32 v147, 0x38d1b717, v147
	v_rcp_f32_e32 v143, v153
	v_rcp_f32_e32 v141, v149
	v_add_f32_e32 v135, 1.0, v135
	v_max_f32_e32 v156, 0x38d1b717, v140
	v_rcp_f32_e32 v144, v144
	v_rcp_f32_e32 v146, v146
	v_rcp_f32_e32 v154, v145
	v_rcp_f32_e32 v155, v147
	v_rcp_f32_e32 v135, v135
	v_rcp_f32_e32 v140, v156
	v_mul_f32_e32 v139, v142, v143
	v_mul_f32_e32 v141, v148, v141
	v_mul_f32_e32 v142, v144, v154
	v_mul_f32_e32 v143, v146, v155
	v_mul_f32_e32 v135, v135, v140
	v_cvt_pk_bf16_f32 v136, v136, v137
	v_cvt_pk_bf16_f32 v137, v138, v139
	v_cvt_pk_bf16_f32 v138, v142, v143
	v_cvt_pk_bf16_f32 v139, v141, v135
	v_lshlrev_b64 v[140:141], 12, v[2:3]
	v_lshl_add_u64 v[142:143], s[16:17], 0, v[140:141]
	v_lshlrev_b64 v[132:133], 1, v[132:133]
	v_lshl_add_u64 v[140:141], s[18:19], 0, v[140:141]
	v_lshl_add_u64 v[142:143], v[142:143], 0, v[132:133]
	v_lshl_add_u64 v[140:141], v[140:141], 0, v[132:133]
	global_store_dwordx4 v[142:143], v[136:139], off
	s_nop 1
	v_cvt_pk_bf16_f32 v136, v150, v151
	v_cvt_pk_bf16_f32 v137, v152, v153
	v_cvt_pk_bf16_f32 v138, v145, v147
	v_cvt_pk_bf16_f32 v139, v149, v156
	global_store_dwordx4 v[140:141], v[136:139], off
	v_add_u32_e32 v140, 16, v2
	v_ashrrev_i32_e32 v141, 31, v140
	v_lshl_add_u64 v[136:137], v[140:141], 2, s[14:15]
	s_waitcnt vmcnt(8)
; DI float sigmoidf_(float x) { return __builtin_amdgcn_rcpf(1.0f + __builtin_amdgcn_exp2f(-x * LOG2E)); }
; DI u32x4 pack8(f32x4 a, f32x4 b) { u32x4 w; w.x = cvt_pk_bf16(a[0], a[1]); w.y = cvt_pk_bf16(a[2], a[3]); w.z = cvt_pk_bf16(b[0], b[1]); w.w = cvt_pk_bf16(b[2], b[3]); return w; }
; DI float rs_of(const float* ss, int row) { return 1.0f / sqrtf(ss[row] * (1.0f / DM) + EPS); }
;     DI void operator()(AccRef acc, const Unit& u, int wr, int wc, int fr, int fq) const {
;     ...
;             for (int m = 0; m < 4; ++m) { const int row = u.pm * 256 + ai * 128 + wr * 64 + m * 16 + fr; const float r = rs_of(ss, row); f32x4 ra[2], sb[2];
; #pragma unroll
;                 for (int n = 0; n < 2; ++n)
; #pragma unroll
;                     for (int j = 0; j < 4; ++j) { const float a = sigmoidf_(acc[ai][0][m][n][j] * r), b = fmaxf(sigmoidf_(acc[ai][1][m][n][j] * r), 1e-4f); sb[n][j] = b; ra[n][j] = a * __builtin_amdgcn_rcpf(b); }
;                 *(u32x4*)(RAT + (size_t)row * DM + col0) = pack8(ra[0], ra[1]); *(u32x4*)(SB + (size_t)row * DM + col0) = pack8(sb[0], sb[1]); }
	v_mov_b32_e32 v3, v207
	v_lshlrev_b64 v[140:141], 12, v[140:141]
	s_nop 1
	s_nop 0
	s_nop 1
	s_nop 1
	s_nop 1
	v_mov_b32_e32 v3, v207
	v_mul_f32_e32 v136, v104, v3
	v_mul_f32_e32 v138, v105, v3
	v_mul_f32_e32 v142, v106, v3
	v_mul_f32_e32 v136, 0xbfb8aa3b, v136
	v_mul_f32_e32 v138, 0xbfb8aa3b, v138
	v_mul_f32_e32 v142, 0xbfb8aa3b, v142
	v_exp_f32_e32 v136, v136
	v_exp_f32_e32 v138, v138
	v_exp_f32_e32 v142, v142
	v_mul_f32_e32 v135, v112, v3
	v_mul_f32_e32 v137, v113, v3
	v_mul_f32_e32 v139, v114, v3
	v_mul_f32_e32 v135, 0xbfb8aa3b, v135
	v_mul_f32_e32 v137, 0xbfb8aa3b, v137
	v_mul_f32_e32 v139, 0xbfb8aa3b, v139
	v_add_f32_e32 v136, 1.0, v136
	v_add_f32_e32 v138, 1.0, v138
	v_add_f32_e32 v142, 1.0, v142
	v_exp_f32_e32 v135, v135
	v_exp_f32_e32 v137, v137
	v_exp_f32_e32 v139, v139
	v_rcp_f32_e32 v136, v136
	v_rcp_f32_e32 v138, v138
	v_rcp_f32_e32 v142, v142
	v_mul_f32_e32 v144, v107, v3
	v_add_f32_e32 v135, 1.0, v135
	v_add_f32_e32 v137, 1.0, v137
	v_add_f32_e32 v139, 1.0, v139
	v_max_f32_e32 v147, 0x38d1b717, v136
	v_max_f32_e32 v148, 0x38d1b717, v138
	v_max_f32_e32 v149, 0x38d1b717, v142
	v_mul_f32_e32 v144, 0xbfb8aa3b, v144
	v_rcp_f32_e32 v135, v135
	v_rcp_f32_e32 v137, v137
	v_rcp_f32_e32 v139, v139
	v_rcp_f32_e32 v136, v147
	v_rcp_f32_e32 v138, v148
	v_rcp_f32_e32 v142, v149
	v_exp_f32_e32 v144, v144
	v_mul_f32_e32 v143, v115, v3
	v_mul_f32_e32 v135, v135, v136
	v_mul_f32_e32 v136, v137, v138
	v_mul_f32_e32 v137, v139, v142
	v_mul_f32_e32 v142, v101, v3
	v_mul_f32_e32 v143, 0xbfb8aa3b, v143
	v_add_f32_e32 v144, 1.0, v144
	v_mul_f32_e32 v142, 0xbfb8aa3b, v142
	v_exp_f32_e32 v143, v143
	v_rcp_f32_e32 v144, v144
	v_exp_f32_e32 v142, v142
	v_mul_f32_e32 v146, v100, v3
	v_add_f32_e32 v143, 1.0, v143
	v_max_f32_e32 v144, 0x38d1b717, v144
	v_add_f32_e32 v142, 1.0, v142
	v_rcp_f32_e32 v143, v143
	v_rcp_f32_e32 v150, v144
	v_rcp_f32_e32 v142, v142
	v_mul_f32_e32 v146, 0xbfb8aa3b, v146
	v_exp_f32_e32 v146, v146
	v_mul_f32_e32 v138, v143, v150
	v_max_f32_e32 v150, 0x38d1b717, v142
	v_mul_f32_e32 v142, v102, v3
	v_mul_f32_e32 v142, 0xbfb8aa3b, v142
	v_exp_f32_e32 v142, v142
	v_mul_f32_e32 v143, v109, v3
	v_mul_f32_e32 v145, v108, v3
	v_mul_f32_e32 v143, 0xbfb8aa3b, v143
	v_add_f32_e32 v142, 1.0, v142
	v_rcp_f32_e32 v142, v142
	v_mul_f32_e32 v151, v110, v3
	v_mul_f32_e32 v145, 0xbfb8aa3b, v145
	v_add_f32_e32 v146, 1.0, v146
	v_max_f32_e32 v153, 0x38d1b717, v142
	v_mul_f32_e32 v142, v103, v3
	v_mul_f32_e32 v142, 0xbfb8aa3b, v142
	v_exp_f32_e32 v142, v142
	v_mul_f32_e32 v3, v111, v3
	v_exp_f32_e32 v143, v143
	v_mul_f32_e32 v3, 0xbfb8aa3b, v3
	v_add_f32_e32 v142, 1.0, v142
	v_exp_f32_e32 v145, v145
	v_rcp_f32_e32 v146, v146
	v_mul_f32_e32 v151, 0xbfb8aa3b, v151
	v_exp_f32_e32 v3, v3
	v_rcp_f32_e32 v142, v142
	v_exp_f32_e32 v151, v151
	v_add_f32_e32 v143, 1.0, v143
	v_add_f32_e32 v139, 1.0, v145
	v_max_f32_e32 v145, 0x38d1b717, v146
	v_rcp_f32_e32 v143, v143
	v_rcp_f32_e32 v152, v150
	v_add_f32_e32 v3, 1.0, v3
	v_max_f32_e32 v155, 0x38d1b717, v142
	v_rcp_f32_e32 v139, v139
	v_rcp_f32_e32 v146, v145
	v_add_f32_e32 v151, 1.0, v151
	v_rcp_f32_e32 v3, v3
	v_rcp_f32_e32 v142, v155
	v_rcp_f32_e32 v151, v151
	v_rcp_f32_e32 v154, v153
	v_mul_f32_e32 v143, v143, v152
	v_mul_f32_e32 v139, v139, v146
	v_mul_f32_e32 v3, v3, v142
	v_cvt_pk_bf16_f32 v136, v135, v136
	v_cvt_pk_bf16_f32 v137, v137, v138
	v_cvt_pk_bf16_f32 v138, v139, v143
	v_lshl_add_u64 v[142:143], s[16:17], 0, v[140:141]
	v_lshl_add_u64 v[140:141], s[18:19], 0, v[140:141]
	v_mul_f32_e32 v146, v151, v154
	v_cvt_pk_bf16_f32 v139, v146, v3
	v_lshl_add_u64 v[142:143], v[142:143], 0, v[132:133]
	v_lshl_add_u64 v[140:141], v[140:141], 0, v[132:133]
	global_store_dwordx4 v[142:143], v[136:139], off
	s_nop 1
	v_cvt_pk_bf16_f32 v136, v147, v148
	v_cvt_pk_bf16_f32 v137, v149, v144
	v_cvt_pk_bf16_f32 v138, v145, v150
	v_cvt_pk_bf16_f32 v139, v153, v155
	global_store_dwordx4 v[140:141], v[136:139], off
	v_add_u32_e32 v140, 32, v2
	v_ashrrev_i32_e32 v141, 31, v140
	v_lshl_add_u64 v[136:137], v[140:141], 2, s[14:15]
	s_waitcnt vmcnt(9)
	v_mov_b32_e32 v3, v240
	v_lshlrev_b64 v[140:141], 12, v[140:141]
	s_nop 1
	s_nop 0
	s_nop 1
	s_nop 1
	s_nop 1
	v_mov_b32_e32 v3, v240
	v_mul_f32_e32 v136, v88, v3
	v_mul_f32_e32 v136, 0xbfb8aa3b, v136
	v_exp_f32_e32 v136, v136
	v_mul_f32_e32 v138, v89, v3
	v_mul_f32_e32 v135, v96, v3
	v_mul_f32_e32 v138, 0xbfb8aa3b, v138
	v_mul_f32_e32 v135, 0xbfb8aa3b, v135
	v_exp_f32_e32 v138, v138
	v_add_f32_e32 v136, 1.0, v136
	v_exp_f32_e32 v135, v135
	v_rcp_f32_e32 v136, v136
	v_mul_f32_e32 v137, v97, v3
	v_mul_f32_e32 v142, v90, v3
	v_mul_f32_e32 v137, 0xbfb8aa3b, v137
	v_mul_f32_e32 v142, 0xbfb8aa3b, v142
	v_add_f32_e32 v138, 1.0, v138
	v_exp_f32_e32 v137, v137
	v_exp_f32_e32 v142, v142
	v_add_f32_e32 v135, 1.0, v135
	v_rcp_f32_e32 v138, v138
	v_max_f32_e32 v144, 0x38d1b717, v136
	v_rcp_f32_e32 v135, v135
	v_rcp_f32_e32 v136, v144
	v_mul_f32_e32 v139, v98, v3
	v_mul_f32_e32 v139, 0xbfb8aa3b, v139
	v_add_f32_e32 v137, 1.0, v137
	v_max_f32_e32 v145, 0x38d1b717, v138
	v_add_f32_e32 v142, 1.0, v142
	v_exp_f32_e32 v139, v139
	v_rcp_f32_e32 v137, v137
	v_rcp_f32_e32 v138, v145
	v_mul_f32_e32 v135, v135, v136
	v_rcp_f32_e32 v136, v142
	v_mul_f32_e32 v142, v99, v3
	v_mul_f32_e32 v137, v137, v138
	v_add_f32_e32 v138, 1.0, v139
	v_max_f32_e32 v146, 0x38d1b717, v136
	v_mul_f32_e32 v142, 0xbfb8aa3b, v142
	v_rcp_f32_e32 v138, v138
	v_rcp_f32_e32 v136, v146
	v_exp_f32_e32 v142, v142
	v_mul_f32_e32 v139, v91, v3
	v_mul_f32_e32 v139, 0xbfb8aa3b, v139
	v_mul_f32_e32 v138, v138, v136
	v_add_f32_e32 v136, 1.0, v142
	v_mul_f32_e32 v142, v84, v3
	v_mul_f32_e32 v142, 0xbfb8aa3b, v142
	v_exp_f32_e32 v142, v142
; DI float sigmoidf_(float x) { return __builtin_amdgcn_rcpf(1.0f + __builtin_amdgcn_exp2f(-x * LOG2E)); }
; DI u32x4 pack8(f32x4 a, f32x4 b) { u32x4 w; w.x = cvt_pk_bf16(a[0], a[1]); w.y = cvt_pk_bf16(a[2], a[3]); w.z = cvt_pk_bf16(b[0], b[1]); w.w = cvt_pk_bf16(b[2], b[3]); return w; }
; DI float rs_of(const float* ss, int row) { return 1.0f / sqrtf(ss[row] * (1.0f / DM) + EPS); }
;     DI void operator()(AccRef acc, const Unit& u, int wr, int wc, int fr, int fq) const {
;     ...
;             for (int m = 0; m < 4; ++m) { const int row = u.pm * 256 + ai * 128 + wr * 64 + m * 16 + fr; const float r = rs_of(ss, row); f32x4 ra[2], sb[2];
; #pragma unroll
;                 for (int n = 0; n < 2; ++n)
; #pragma unroll
;                     for (int j = 0; j < 4; ++j) { const float a = sigmoidf_(acc[ai][0][m][n][j] * r), b = fmaxf(sigmoidf_(acc[ai][1][m][n][j] * r), 1e-4f); sb[n][j] = b; ra[n][j] = a * __builtin_amdgcn_rcpf(b); }
;                 *(u32x4*)(RAT + (size_t)row * DM + col0) = pack8(ra[0], ra[1]); *(u32x4*)(SB + (size_t)row * DM + col0) = pack8(sb[0], sb[1]); }
	v_exp_f32_e32 v139, v139
	v_mul_f32_e32 v143, v92, v3
	v_mul_f32_e32 v143, 0xbfb8aa3b, v143
	v_add_f32_e32 v142, 1.0, v142
	v_rcp_f32_e32 v142, v142
	v_add_f32_e32 v139, 1.0, v139
	v_rcp_f32_e32 v139, v139
	v_rcp_f32_e32 v136, v136
	v_max_f32_e32 v148, 0x38d1b717, v142
	v_mul_f32_e32 v142, v85, v3
	v_mul_f32_e32 v142, 0xbfb8aa3b, v142
	v_exp_f32_e32 v142, v142
	v_max_f32_e32 v147, 0x38d1b717, v139
	v_rcp_f32_e32 v139, v147
	v_exp_f32_e32 v143, v143
	v_add_f32_e32 v142, 1.0, v142
	v_rcp_f32_e32 v142, v142
	v_mul_f32_e32 v139, v136, v139
	v_add_f32_e32 v136, 1.0, v143
	v_mul_f32_e32 v143, v93, v3
	v_max_f32_e32 v150, 0x38d1b717, v142
	v_mul_f32_e32 v142, v86, v3
	v_mul_f32_e32 v142, 0xbfb8aa3b, v142
	v_exp_f32_e32 v142, v142
	v_mul_f32_e32 v143, 0xbfb8aa3b, v143
	v_mul_f32_e32 v151, v94, v3
	v_exp_f32_e32 v143, v143
	v_add_f32_e32 v142, 1.0, v142
	v_rcp_f32_e32 v142, v142
	v_mul_f32_e32 v151, 0xbfb8aa3b, v151
	v_exp_f32_e32 v151, v151
	v_add_f32_e32 v143, 1.0, v143
	v_max_f32_e32 v153, 0x38d1b717, v142
	v_mul_f32_e32 v142, v87, v3
	v_mul_f32_e32 v142, 0xbfb8aa3b, v142
	v_exp_f32_e32 v142, v142
	v_mul_f32_e32 v3, v95, v3
	v_mul_f32_e32 v3, 0xbfb8aa3b, v3
	v_exp_f32_e32 v3, v3
	v_add_f32_e32 v142, 1.0, v142
	v_rcp_f32_e32 v142, v142
	v_rcp_f32_e32 v143, v143
	v_rcp_f32_e32 v152, v150
	v_add_f32_e32 v3, 1.0, v3
	v_max_f32_e32 v155, 0x38d1b717, v142
	v_rcp_f32_e32 v136, v136
	v_rcp_f32_e32 v149, v148
	v_add_f32_e32 v151, 1.0, v151
	v_rcp_f32_e32 v3, v3
	v_rcp_f32_e32 v142, v155
	v_rcp_f32_e32 v151, v151
	v_rcp_f32_e32 v154, v153
	v_mul_f32_e32 v143, v143, v152
	v_mul_f32_e32 v149, v136, v149
	v_mul_f32_e32 v3, v3, v142
	v_cvt_pk_bf16_f32 v136, v135, v137
	v_cvt_pk_bf16_f32 v137, v138, v139
	v_cvt_pk_bf16_f32 v138, v149, v143
	v_lshl_add_u64 v[142:143], s[16:17], 0, v[140:141]
	v_lshl_add_u64 v[140:141], s[18:19], 0, v[140:141]
	v_mul_f32_e32 v151, v151, v154
	v_cvt_pk_bf16_f32 v139, v151, v3
	v_lshl_add_u64 v[142:143], v[142:143], 0, v[132:133]
	v_lshl_add_u64 v[140:141], v[140:141], 0, v[132:133]
	global_store_dwordx4 v[142:143], v[136:139], off
	s_nop 1
	v_cvt_pk_bf16_f32 v136, v144, v145
	v_cvt_pk_bf16_f32 v137, v146, v147
	v_cvt_pk_bf16_f32 v138, v148, v150
	v_cvt_pk_bf16_f32 v139, v153, v155
	global_store_dwordx4 v[140:141], v[136:139], off
	v_add_u32_e32 v140, 48, v2
	v_ashrrev_i32_e32 v141, 31, v140
	v_lshl_add_u64 v[136:137], v[140:141], 2, s[14:15]
	s_waitcnt vmcnt(10)
	v_mov_b32_e32 v3, v241
	v_lshlrev_b64 v[140:141], 12, v[140:141]
	s_nop 1
	s_nop 0
	s_nop 0
	s_nop 1
	s_nop 1
	s_nop 0
	v_mov_b32_e32 v3, v241
	v_mul_f32_e32 v135, v72, v3
	v_mul_f32_e32 v135, 0xbfb8aa3b, v135
	v_exp_f32_e32 v135, v135
	v_mul_f32_e32 v136, v80, v3
	v_mul_f32_e32 v136, 0xbfb8aa3b, v136
	v_exp_f32_e32 v136, v136
	v_add_f32_e32 v135, 1.0, v135
	v_rcp_f32_e32 v135, v135
	v_mul_f32_e32 v139, v81, v3
	v_add_f32_e32 v136, 1.0, v136
	v_mul_f32_e32 v138, v73, v3
	v_max_f32_e32 v135, 0x38d1b717, v135
	v_mul_f32_e32 v139, 0xbfb8aa3b, v139
	v_rcp_f32_e32 v136, v136
	v_rcp_f32_e32 v137, v135
	v_mul_f32_e32 v138, 0xbfb8aa3b, v138
	v_exp_f32_e32 v139, v139
	v_exp_f32_e32 v138, v138
	v_mul_f32_e32 v136, v136, v137
	v_mul_f32_e32 v142, v82, v3
	v_add_f32_e32 v137, 1.0, v139
	v_mul_f32_e32 v139, v74, v3
	v_add_f32_e32 v138, 1.0, v138
	v_mul_f32_e32 v139, 0xbfb8aa3b, v139
	v_rcp_f32_e32 v138, v138
	v_exp_f32_e32 v139, v139
	v_mul_f32_e32 v142, 0xbfb8aa3b, v142
	v_rcp_f32_e32 v137, v137
	v_max_f32_e32 v144, 0x38d1b717, v138
	v_add_f32_e32 v139, 1.0, v139
	v_rcp_f32_e32 v138, v144
	v_exp_f32_e32 v142, v142
	v_rcp_f32_e32 v139, v139
	v_mul_f32_e32 v143, v83, v3
	v_mul_f32_e32 v137, v137, v138
	v_add_f32_e32 v138, 1.0, v142
	v_max_f32_e32 v145, 0x38d1b717, v139
	v_mul_f32_e32 v142, v75, v3
	v_mul_f32_e32 v143, 0xbfb8aa3b, v143
	v_rcp_f32_e32 v138, v138
	v_rcp_f32_e32 v139, v145
	v_mul_f32_e32 v142, 0xbfb8aa3b, v142
	v_exp_f32_e32 v143, v143
	v_exp_f32_e32 v142, v142
	v_mul_f32_e32 v138, v138, v139
	v_mul_f32_e32 v147, v76, v3
	v_add_f32_e32 v139, 1.0, v143
	v_mul_f32_e32 v143, v68, v3
	v_add_f32_e32 v142, 1.0, v142
	v_mul_f32_e32 v143, 0xbfb8aa3b, v143
	v_rcp_f32_e32 v142, v142
	v_exp_f32_e32 v143, v143
	v_mul_f32_e32 v147, 0xbfb8aa3b, v147
	v_rcp_f32_e32 v139, v139
	v_max_f32_e32 v146, 0x38d1b717, v142
	v_add_f32_e32 v143, 1.0, v143
	v_rcp_f32_e32 v142, v146
	v_exp_f32_e32 v147, v147
	v_rcp_f32_e32 v143, v143
	v_mul_f32_e32 v148, v77, v3
	v_mul_f32_e32 v139, v139, v142
	v_add_f32_e32 v142, 1.0, v147
	v_max_f32_e32 v147, 0x38d1b717, v143
	v_mul_f32_e32 v143, v69, v3
	v_mul_f32_e32 v143, 0xbfb8aa3b, v143
	v_exp_f32_e32 v143, v143
	v_mul_f32_e32 v151, v78, v3
	v_mul_f32_e32 v148, 0xbfb8aa3b, v148
	v_exp_f32_e32 v148, v148
	v_add_f32_e32 v143, 1.0, v143
	v_rcp_f32_e32 v143, v143
	v_mul_f32_e32 v151, 0xbfb8aa3b, v151
	v_exp_f32_e32 v151, v151
	v_rcp_f32_e32 v142, v142
	v_max_f32_e32 v150, 0x38d1b717, v143
	v_mul_f32_e32 v143, v70, v3
	v_mul_f32_e32 v143, 0xbfb8aa3b, v143
	v_exp_f32_e32 v143, v143
	v_rcp_f32_e32 v149, v147
	v_add_f32_e32 v148, 1.0, v148
	v_rcp_f32_e32 v148, v148
	v_add_f32_e32 v143, 1.0, v143
	v_rcp_f32_e32 v143, v143
	v_rcp_f32_e32 v152, v150
	v_add_f32_e32 v151, 1.0, v151
	v_rcp_f32_e32 v151, v151
	v_max_f32_e32 v153, 0x38d1b717, v143
	v_mul_f32_e32 v143, v71, v3
	v_mul_f32_e32 v143, 0xbfb8aa3b, v143
	v_exp_f32_e32 v143, v143
	v_mul_f32_e32 v3, v79, v3
	v_mul_f32_e32 v3, 0xbfb8aa3b, v3
	v_exp_f32_e32 v3, v3
	v_add_f32_e32 v143, 1.0, v143
	v_rcp_f32_e32 v143, v143
	v_rcp_f32_e32 v154, v153
	v_add_f32_e32 v3, 1.0, v3
	v_rcp_f32_e32 v3, v3
	v_max_f32_e32 v155, 0x38d1b717, v143
	v_rcp_f32_e32 v143, v155
	v_mul_f32_e32 v142, v142, v149
	v_mul_f32_e32 v148, v148, v152
	v_cvt_pk_bf16_f32 v136, v136, v137
	v_mul_f32_e32 v3, v3, v143
	v_cvt_pk_bf16_f32 v137, v138, v139
	v_cvt_pk_bf16_f32 v138, v142, v148
	v_lshl_add_u64 v[142:143], s[16:17], 0, v[140:141]
	v_lshl_add_u64 v[140:141], s[18:19], 0, v[140:141]
	v_mul_f32_e32 v149, v151, v154
	v_cvt_pk_bf16_f32 v139, v149, v3
	v_lshl_add_u64 v[142:143], v[142:143], 0, v[132:133]
	v_lshl_add_u64 v[140:141], v[140:141], 0, v[132:133]
	global_store_dwordx4 v[142:143], v[136:139], off
	s_nop 1
	v_cvt_pk_bf16_f32 v136, v135, v144
	v_cvt_pk_bf16_f32 v137, v145, v146
	v_cvt_pk_bf16_f32 v138, v147, v150
	v_cvt_pk_bf16_f32 v139, v153, v155
	global_store_dwordx4 v[140:141], v[136:139], off
	v_add_u32_e32 v140, 0x80, v2
	v_ashrrev_i32_e32 v141, 31, v140
	v_lshl_add_u64 v[136:137], v[140:141], 2, s[14:15]
	s_waitcnt vmcnt(11)
; DI float sigmoidf_(float x) { return __builtin_amdgcn_rcpf(1.0f + __builtin_amdgcn_exp2f(-x * LOG2E)); }
; DI u32x4 pack8(f32x4 a, f32x4 b) { u32x4 w; w.x = cvt_pk_bf16(a[0], a[1]); w.y = cvt_pk_bf16(a[2], a[3]); w.z = cvt_pk_bf16(b[0], b[1]); w.w = cvt_pk_bf16(b[2], b[3]); return w; }
; DI float rs_of(const float* ss, int row) { return 1.0f / sqrtf(ss[row] * (1.0f / DM) + EPS); }
;     DI void operator()(AccRef acc, const Unit& u, int wr, int wc, int fr, int fq) const {
;     ...
;             for (int m = 0; m < 4; ++m) { const int row = u.pm * 256 + ai * 128 + wr * 64 + m * 16 + fr; const float r = rs_of(ss, row); f32x4 ra[2], sb[2];
; #pragma unroll
;                 for (int n = 0; n < 2; ++n)
; #pragma unroll
;                     for (int j = 0; j < 4; ++j) { const float a = sigmoidf_(acc[ai][0][m][n][j] * r), b = fmaxf(sigmoidf_(acc[ai][1][m][n][j] * r), 1e-4f); sb[n][j] = b; ra[n][j] = a * __builtin_amdgcn_rcpf(b); }
;                 *(u32x4*)(RAT + (size_t)row * DM + col0) = pack8(ra[0], ra[1]); *(u32x4*)(SB + (size_t)row * DM + col0) = pack8(sb[0], sb[1]); }
	v_mov_b32_e32 v3, v242
	v_lshlrev_b64 v[140:141], 12, v[140:141]
	s_nop 1
	s_nop 0
	s_nop 0
	s_nop 1
	s_nop 1
	s_nop 0
	v_mov_b32_e32 v3, v242
	v_mul_f32_e32 v135, v56, v3
	v_mul_f32_e32 v135, 0xbfb8aa3b, v135
	v_exp_f32_e32 v135, v135
	v_mul_f32_e32 v136, v64, v3
	v_mul_f32_e32 v136, 0xbfb8aa3b, v136
	v_exp_f32_e32 v136, v136
	v_add_f32_e32 v135, 1.0, v135
	v_rcp_f32_e32 v135, v135
	v_mul_f32_e32 v139, v65, v3
	v_add_f32_e32 v136, 1.0, v136
	v_mul_f32_e32 v138, v57, v3
	v_max_f32_e32 v135, 0x38d1b717, v135
	v_mul_f32_e32 v139, 0xbfb8aa3b, v139
	v_rcp_f32_e32 v136, v136
	v_rcp_f32_e32 v137, v135
	v_mul_f32_e32 v138, 0xbfb8aa3b, v138
	v_exp_f32_e32 v139, v139
	v_exp_f32_e32 v138, v138
	v_mul_f32_e32 v136, v136, v137
	v_mul_f32_e32 v142, v66, v3
	v_add_f32_e32 v137, 1.0, v139
	v_mul_f32_e32 v139, v58, v3
	v_add_f32_e32 v138, 1.0, v138
	v_mul_f32_e32 v139, 0xbfb8aa3b, v139
	v_rcp_f32_e32 v138, v138
	v_exp_f32_e32 v139, v139
	v_mul_f32_e32 v142, 0xbfb8aa3b, v142
	v_rcp_f32_e32 v137, v137
	v_max_f32_e32 v144, 0x38d1b717, v138
	v_add_f32_e32 v139, 1.0, v139
	v_rcp_f32_e32 v138, v144
	v_exp_f32_e32 v142, v142
	v_rcp_f32_e32 v139, v139
	v_mul_f32_e32 v143, v67, v3
	v_mul_f32_e32 v137, v137, v138
	v_add_f32_e32 v138, 1.0, v142
	v_max_f32_e32 v145, 0x38d1b717, v139
	v_mul_f32_e32 v142, v59, v3
	v_mul_f32_e32 v143, 0xbfb8aa3b, v143
	v_rcp_f32_e32 v138, v138
	v_rcp_f32_e32 v139, v145
	v_mul_f32_e32 v142, 0xbfb8aa3b, v142
	v_exp_f32_e32 v143, v143
	v_exp_f32_e32 v142, v142
	v_mul_f32_e32 v138, v138, v139
	v_mul_f32_e32 v147, v60, v3
	v_add_f32_e32 v139, 1.0, v143
	v_mul_f32_e32 v143, v52, v3
	v_add_f32_e32 v142, 1.0, v142
	v_mul_f32_e32 v143, 0xbfb8aa3b, v143
	v_rcp_f32_e32 v142, v142
	v_exp_f32_e32 v143, v143
	v_mul_f32_e32 v147, 0xbfb8aa3b, v147
	v_rcp_f32_e32 v139, v139
	v_max_f32_e32 v146, 0x38d1b717, v142
	v_add_f32_e32 v143, 1.0, v143
	v_rcp_f32_e32 v142, v146
	v_exp_f32_e32 v147, v147
	v_rcp_f32_e32 v143, v143
	v_mul_f32_e32 v148, v61, v3
	v_mul_f32_e32 v139, v139, v142
	v_add_f32_e32 v142, 1.0, v147
	v_max_f32_e32 v147, 0x38d1b717, v143
	v_mul_f32_e32 v143, v53, v3
	v_mul_f32_e32 v143, 0xbfb8aa3b, v143
	v_exp_f32_e32 v143, v143
	v_mul_f32_e32 v151, v62, v3
	v_mul_f32_e32 v148, 0xbfb8aa3b, v148
	v_exp_f32_e32 v148, v148
	v_add_f32_e32 v143, 1.0, v143
	v_rcp_f32_e32 v143, v143
	v_mul_f32_e32 v151, 0xbfb8aa3b, v151
	v_exp_f32_e32 v151, v151
	v_rcp_f32_e32 v142, v142
	v_max_f32_e32 v150, 0x38d1b717, v143
	v_mul_f32_e32 v143, v54, v3
	v_mul_f32_e32 v143, 0xbfb8aa3b, v143
	v_exp_f32_e32 v143, v143
	v_rcp_f32_e32 v149, v147
	v_add_f32_e32 v148, 1.0, v148
	v_rcp_f32_e32 v148, v148
	v_add_f32_e32 v143, 1.0, v143
	v_rcp_f32_e32 v143, v143
	v_rcp_f32_e32 v152, v150
	v_add_f32_e32 v151, 1.0, v151
	v_rcp_f32_e32 v151, v151
	v_max_f32_e32 v153, 0x38d1b717, v143
	v_mul_f32_e32 v143, v55, v3
	v_mul_f32_e32 v143, 0xbfb8aa3b, v143
	v_exp_f32_e32 v143, v143
	v_mul_f32_e32 v3, v63, v3
	v_mul_f32_e32 v3, 0xbfb8aa3b, v3
	v_exp_f32_e32 v3, v3
	v_add_f32_e32 v143, 1.0, v143
	v_rcp_f32_e32 v143, v143
	v_rcp_f32_e32 v154, v153
	v_add_f32_e32 v3, 1.0, v3
	v_rcp_f32_e32 v3, v3
	v_max_f32_e32 v155, 0x38d1b717, v143
	v_rcp_f32_e32 v143, v155
	v_mul_f32_e32 v142, v142, v149
	v_mul_f32_e32 v148, v148, v152
	v_cvt_pk_bf16_f32 v136, v136, v137
	v_mul_f32_e32 v3, v3, v143
	v_cvt_pk_bf16_f32 v137, v138, v139
	v_cvt_pk_bf16_f32 v138, v142, v148
	v_lshl_add_u64 v[142:143], s[16:17], 0, v[140:141]
	v_lshl_add_u64 v[140:141], s[18:19], 0, v[140:141]
	v_mul_f32_e32 v149, v151, v154
	v_cvt_pk_bf16_f32 v139, v149, v3
	v_lshl_add_u64 v[142:143], v[142:143], 0, v[132:133]
	v_lshl_add_u64 v[140:141], v[140:141], 0, v[132:133]
	global_store_dwordx4 v[142:143], v[136:139], off
	s_nop 1
	v_cvt_pk_bf16_f32 v136, v135, v144
	v_cvt_pk_bf16_f32 v137, v145, v146
	v_cvt_pk_bf16_f32 v138, v147, v150
	v_cvt_pk_bf16_f32 v139, v153, v155
	global_store_dwordx4 v[140:141], v[136:139], off
	v_add_u32_e32 v140, 0x90, v2
	v_ashrrev_i32_e32 v141, 31, v140
	v_lshl_add_u64 v[136:137], v[140:141], 2, s[14:15]
	s_waitcnt vmcnt(12)
	v_mov_b32_e32 v3, v243
	v_lshlrev_b64 v[140:141], 12, v[140:141]
	s_nop 1
	s_nop 0
	s_nop 0
	s_nop 1
	s_nop 1
	s_nop 0
	v_mov_b32_e32 v3, v243
	v_mul_f32_e32 v135, v40, v3
	v_mul_f32_e32 v135, 0xbfb8aa3b, v135
	v_exp_f32_e32 v135, v135
	v_mul_f32_e32 v136, v48, v3
	v_mul_f32_e32 v136, 0xbfb8aa3b, v136
	v_exp_f32_e32 v136, v136
	v_add_f32_e32 v135, 1.0, v135
	v_rcp_f32_e32 v135, v135
	v_mul_f32_e32 v139, v49, v3
	v_add_f32_e32 v136, 1.0, v136
	v_mul_f32_e32 v138, v41, v3
	v_max_f32_e32 v135, 0x38d1b717, v135
	v_mul_f32_e32 v139, 0xbfb8aa3b, v139
	v_rcp_f32_e32 v136, v136
	v_rcp_f32_e32 v137, v135
	v_mul_f32_e32 v138, 0xbfb8aa3b, v138
	v_exp_f32_e32 v139, v139
	v_exp_f32_e32 v138, v138
	v_mul_f32_e32 v136, v136, v137
	v_mul_f32_e32 v142, v50, v3
	v_add_f32_e32 v137, 1.0, v139
	v_mul_f32_e32 v139, v42, v3
	v_add_f32_e32 v138, 1.0, v138
	v_mul_f32_e32 v139, 0xbfb8aa3b, v139
	v_rcp_f32_e32 v138, v138
	v_exp_f32_e32 v139, v139
	v_mul_f32_e32 v142, 0xbfb8aa3b, v142
	v_rcp_f32_e32 v137, v137
	v_max_f32_e32 v144, 0x38d1b717, v138
	v_add_f32_e32 v139, 1.0, v139
	v_rcp_f32_e32 v138, v144
	v_exp_f32_e32 v142, v142
	v_rcp_f32_e32 v139, v139
	v_mul_f32_e32 v143, v51, v3
	v_mul_f32_e32 v137, v137, v138
	v_add_f32_e32 v138, 1.0, v142
	v_max_f32_e32 v145, 0x38d1b717, v139
	v_mul_f32_e32 v142, v43, v3
	v_mul_f32_e32 v143, 0xbfb8aa3b, v143
	v_rcp_f32_e32 v138, v138
	v_rcp_f32_e32 v139, v145
	v_mul_f32_e32 v142, 0xbfb8aa3b, v142
	v_exp_f32_e32 v143, v143
	v_exp_f32_e32 v142, v142
	v_mul_f32_e32 v138, v138, v139
	v_mul_f32_e32 v147, v44, v3
	v_add_f32_e32 v139, 1.0, v143
	v_mul_f32_e32 v143, v36, v3
; DI float sigmoidf_(float x) { return __builtin_amdgcn_rcpf(1.0f + __builtin_amdgcn_exp2f(-x * LOG2E)); }
; DI u32x4 pack8(f32x4 a, f32x4 b) { u32x4 w; w.x = cvt_pk_bf16(a[0], a[1]); w.y = cvt_pk_bf16(a[2], a[3]); w.z = cvt_pk_bf16(b[0], b[1]); w.w = cvt_pk_bf16(b[2], b[3]); return w; }
; DI float rs_of(const float* ss, int row) { return 1.0f / sqrtf(ss[row] * (1.0f / DM) + EPS); }
;     DI void operator()(AccRef acc, const Unit& u, int wr, int wc, int fr, int fq) const {
;     ...
;             for (int m = 0; m < 4; ++m) { const int row = u.pm * 256 + ai * 128 + wr * 64 + m * 16 + fr; const float r = rs_of(ss, row); f32x4 ra[2], sb[2];
; #pragma unroll
;                 for (int n = 0; n < 2; ++n)
; #pragma unroll
;                     for (int j = 0; j < 4; ++j) { const float a = sigmoidf_(acc[ai][0][m][n][j] * r), b = fmaxf(sigmoidf_(acc[ai][1][m][n][j] * r), 1e-4f); sb[n][j] = b; ra[n][j] = a * __builtin_amdgcn_rcpf(b); }
;                 *(u32x4*)(RAT + (size_t)row * DM + col0) = pack8(ra[0], ra[1]); *(u32x4*)(SB + (size_t)row * DM + col0) = pack8(sb[0], sb[1]); }
	v_add_f32_e32 v142, 1.0, v142
	v_mul_f32_e32 v143, 0xbfb8aa3b, v143
	v_rcp_f32_e32 v142, v142
	v_exp_f32_e32 v143, v143
	v_mul_f32_e32 v147, 0xbfb8aa3b, v147
	v_rcp_f32_e32 v139, v139
	v_max_f32_e32 v146, 0x38d1b717, v142
	v_add_f32_e32 v143, 1.0, v143
	v_rcp_f32_e32 v142, v146
	v_exp_f32_e32 v147, v147
	v_rcp_f32_e32 v143, v143
	v_mul_f32_e32 v148, v45, v3
	v_mul_f32_e32 v139, v139, v142
	v_add_f32_e32 v142, 1.0, v147
	v_max_f32_e32 v147, 0x38d1b717, v143
	v_mul_f32_e32 v143, v37, v3
	v_mul_f32_e32 v143, 0xbfb8aa3b, v143
	v_exp_f32_e32 v143, v143
	v_mul_f32_e32 v151, v46, v3
	v_mul_f32_e32 v148, 0xbfb8aa3b, v148
	v_exp_f32_e32 v148, v148
	v_add_f32_e32 v143, 1.0, v143
	v_rcp_f32_e32 v143, v143
	v_mul_f32_e32 v151, 0xbfb8aa3b, v151
	v_exp_f32_e32 v151, v151
	v_rcp_f32_e32 v142, v142
	v_max_f32_e32 v150, 0x38d1b717, v143
	v_mul_f32_e32 v143, v38, v3
	v_mul_f32_e32 v143, 0xbfb8aa3b, v143
	v_exp_f32_e32 v143, v143
	v_rcp_f32_e32 v149, v147
	v_add_f32_e32 v148, 1.0, v148
	v_rcp_f32_e32 v148, v148
	v_add_f32_e32 v143, 1.0, v143
	v_rcp_f32_e32 v143, v143
	v_rcp_f32_e32 v152, v150
	v_add_f32_e32 v151, 1.0, v151
	v_rcp_f32_e32 v151, v151
	v_max_f32_e32 v153, 0x38d1b717, v143
	v_mul_f32_e32 v143, v39, v3
	v_mul_f32_e32 v143, 0xbfb8aa3b, v143
	v_exp_f32_e32 v143, v143
	v_mul_f32_e32 v3, v47, v3
	v_mul_f32_e32 v3, 0xbfb8aa3b, v3
	v_exp_f32_e32 v3, v3
	v_add_f32_e32 v143, 1.0, v143
	v_rcp_f32_e32 v143, v143
	v_rcp_f32_e32 v154, v153
	v_add_f32_e32 v3, 1.0, v3
	v_rcp_f32_e32 v3, v3
	v_max_f32_e32 v155, 0x38d1b717, v143
	v_rcp_f32_e32 v143, v155
	v_mul_f32_e32 v142, v142, v149
	v_mul_f32_e32 v148, v148, v152
	v_cvt_pk_bf16_f32 v136, v136, v137
	v_mul_f32_e32 v3, v3, v143
	v_cvt_pk_bf16_f32 v137, v138, v139
	v_cvt_pk_bf16_f32 v138, v142, v148
	v_lshl_add_u64 v[142:143], s[16:17], 0, v[140:141]
	v_lshl_add_u64 v[140:141], s[18:19], 0, v[140:141]
	v_mul_f32_e32 v149, v151, v154
	v_cvt_pk_bf16_f32 v139, v149, v3
	v_lshl_add_u64 v[142:143], v[142:143], 0, v[132:133]
	v_lshl_add_u64 v[140:141], v[140:141], 0, v[132:133]
	global_store_dwordx4 v[142:143], v[136:139], off
	s_nop 1
	v_cvt_pk_bf16_f32 v136, v135, v144
	v_cvt_pk_bf16_f32 v137, v145, v146
	v_cvt_pk_bf16_f32 v138, v147, v150
	v_cvt_pk_bf16_f32 v139, v153, v155
	global_store_dwordx4 v[140:141], v[136:139], off
	v_add_u32_e32 v140, 0xa0, v2
	v_ashrrev_i32_e32 v141, 31, v140
	v_lshl_add_u64 v[136:137], v[140:141], 2, s[14:15]
	s_waitcnt vmcnt(13)
	v_mov_b32_e32 v3, v236
	v_lshlrev_b64 v[140:141], 12, v[140:141]
	v_add_u32_e32 v2, 0xb0, v2
	s_nop 1
	s_nop 0
	s_nop 0
	s_nop 1
	s_nop 1
	s_nop 0
	v_mov_b32_e32 v3, v236
	v_mul_f32_e32 v135, v24, v3
	v_mul_f32_e32 v135, 0xbfb8aa3b, v135
	v_exp_f32_e32 v135, v135
	v_mul_f32_e32 v136, v32, v3
	v_mul_f32_e32 v136, 0xbfb8aa3b, v136
	v_exp_f32_e32 v136, v136
	v_add_f32_e32 v135, 1.0, v135
	v_rcp_f32_e32 v135, v135
	v_mul_f32_e32 v139, v33, v3
	v_add_f32_e32 v136, 1.0, v136
	v_mul_f32_e32 v138, v25, v3
	v_max_f32_e32 v135, 0x38d1b717, v135
	v_mul_f32_e32 v139, 0xbfb8aa3b, v139
	v_rcp_f32_e32 v136, v136
	v_rcp_f32_e32 v137, v135
	v_mul_f32_e32 v138, 0xbfb8aa3b, v138
	v_exp_f32_e32 v139, v139
	v_exp_f32_e32 v138, v138
	v_mul_f32_e32 v136, v136, v137
	v_mul_f32_e32 v142, v34, v3
	v_add_f32_e32 v137, 1.0, v139
	v_mul_f32_e32 v139, v26, v3
	v_add_f32_e32 v138, 1.0, v138
	v_mul_f32_e32 v139, 0xbfb8aa3b, v139
	v_rcp_f32_e32 v138, v138
	v_exp_f32_e32 v139, v139
	v_mul_f32_e32 v142, 0xbfb8aa3b, v142
	v_rcp_f32_e32 v137, v137
	v_max_f32_e32 v144, 0x38d1b717, v138
	v_add_f32_e32 v139, 1.0, v139
	v_rcp_f32_e32 v138, v144
	v_exp_f32_e32 v142, v142
	v_rcp_f32_e32 v139, v139
	v_mul_f32_e32 v143, v35, v3
	v_mul_f32_e32 v137, v137, v138
	v_add_f32_e32 v138, 1.0, v142
	v_max_f32_e32 v145, 0x38d1b717, v139
	v_mul_f32_e32 v142, v27, v3
	v_mul_f32_e32 v143, 0xbfb8aa3b, v143
	v_rcp_f32_e32 v138, v138
	v_rcp_f32_e32 v139, v145
	v_mul_f32_e32 v142, 0xbfb8aa3b, v142
	v_exp_f32_e32 v143, v143
	v_exp_f32_e32 v142, v142
	v_mul_f32_e32 v138, v138, v139
	v_mul_f32_e32 v147, v28, v3
	v_add_f32_e32 v139, 1.0, v143
	v_mul_f32_e32 v143, v20, v3
	v_add_f32_e32 v142, 1.0, v142
	v_mul_f32_e32 v143, 0xbfb8aa3b, v143
	v_rcp_f32_e32 v142, v142
	v_exp_f32_e32 v143, v143
	v_mul_f32_e32 v147, 0xbfb8aa3b, v147
	v_rcp_f32_e32 v139, v139
	v_max_f32_e32 v146, 0x38d1b717, v142
	v_add_f32_e32 v143, 1.0, v143
	v_rcp_f32_e32 v142, v146
	v_exp_f32_e32 v147, v147
	v_rcp_f32_e32 v143, v143
	v_mul_f32_e32 v148, v29, v3
	v_mul_f32_e32 v139, v139, v142
	v_add_f32_e32 v142, 1.0, v147
	v_max_f32_e32 v147, 0x38d1b717, v143
	v_mul_f32_e32 v143, v21, v3
	v_mul_f32_e32 v143, 0xbfb8aa3b, v143
	v_exp_f32_e32 v143, v143
	v_mul_f32_e32 v151, v30, v3
	v_mul_f32_e32 v148, 0xbfb8aa3b, v148
	v_exp_f32_e32 v148, v148
	v_add_f32_e32 v143, 1.0, v143
	v_rcp_f32_e32 v143, v143
	v_mul_f32_e32 v151, 0xbfb8aa3b, v151
	v_exp_f32_e32 v151, v151
	v_rcp_f32_e32 v142, v142
	v_max_f32_e32 v150, 0x38d1b717, v143
	v_mul_f32_e32 v143, v22, v3
	v_mul_f32_e32 v143, 0xbfb8aa3b, v143
	v_exp_f32_e32 v143, v143
	v_rcp_f32_e32 v149, v147
	v_add_f32_e32 v148, 1.0, v148
	v_rcp_f32_e32 v148, v148
	v_add_f32_e32 v143, 1.0, v143
	v_rcp_f32_e32 v143, v143
	v_rcp_f32_e32 v152, v150
	v_add_f32_e32 v151, 1.0, v151
	v_rcp_f32_e32 v151, v151
	v_max_f32_e32 v153, 0x38d1b717, v143
	v_mul_f32_e32 v143, v23, v3
	v_mul_f32_e32 v143, 0xbfb8aa3b, v143
	v_exp_f32_e32 v143, v143
	v_mul_f32_e32 v3, v31, v3
	v_mul_f32_e32 v3, 0xbfb8aa3b, v3
	v_exp_f32_e32 v3, v3
	v_add_f32_e32 v143, 1.0, v143
	v_rcp_f32_e32 v143, v143
	v_rcp_f32_e32 v154, v153
	v_add_f32_e32 v3, 1.0, v3
	v_rcp_f32_e32 v3, v3
	v_max_f32_e32 v155, 0x38d1b717, v143
	v_rcp_f32_e32 v143, v155
	v_mul_f32_e32 v142, v142, v149
	v_mul_f32_e32 v148, v148, v152
	v_cvt_pk_bf16_f32 v136, v136, v137
	v_mul_f32_e32 v3, v3, v143
	v_cvt_pk_bf16_f32 v137, v138, v139
	v_cvt_pk_bf16_f32 v138, v142, v148
	v_lshl_add_u64 v[142:143], s[16:17], 0, v[140:141]
	v_lshl_add_u64 v[142:143], v[142:143], 0, v[132:133]
	v_lshl_add_u64 v[140:141], s[18:19], 0, v[140:141]
	v_mul_f32_e32 v149, v151, v154
	v_cvt_pk_bf16_f32 v139, v149, v3
	global_store_dwordx4 v[142:143], v[136:139], off
	v_lshl_add_u64 v[140:141], v[140:141], 0, v[132:133]
	v_ashrrev_i32_e32 v3, 31, v2
	v_cvt_pk_bf16_f32 v136, v135, v144
	v_cvt_pk_bf16_f32 v137, v145, v146
	v_cvt_pk_bf16_f32 v138, v147, v150
	v_cvt_pk_bf16_f32 v139, v153, v155
	global_store_dwordx4 v[140:141], v[136:139], off
	s_nop 1
	v_lshl_add_u64 v[136:137], v[2:3], 2, s[14:15]
	s_waitcnt vmcnt(14)
; DI float sigmoidf_(float x) { return __builtin_amdgcn_rcpf(1.0f + __builtin_amdgcn_exp2f(-x * LOG2E)); }
; DI u32x4 pack8(f32x4 a, f32x4 b) { u32x4 w; w.x = cvt_pk_bf16(a[0], a[1]); w.y = cvt_pk_bf16(a[2], a[3]); w.z = cvt_pk_bf16(b[0], b[1]); w.w = cvt_pk_bf16(b[2], b[3]); return w; }
; DI float rs_of(const float* ss, int row) { return 1.0f / sqrtf(ss[row] * (1.0f / DM) + EPS); }
;     DI void operator()(AccRef acc, const Unit& u, int wr, int wc, int fr, int fq) const {
;     ...
;             for (int m = 0; m < 4; ++m) { const int row = u.pm * 256 + ai * 128 + wr * 64 + m * 16 + fr; const float r = rs_of(ss, row); f32x4 ra[2], sb[2];
; #pragma unroll
;                 for (int n = 0; n < 2; ++n)
; #pragma unroll
;                     for (int j = 0; j < 4; ++j) { const float a = sigmoidf_(acc[ai][0][m][n][j] * r), b = fmaxf(sigmoidf_(acc[ai][1][m][n][j] * r), 1e-4f); sb[n][j] = b; ra[n][j] = a * __builtin_amdgcn_rcpf(b); }
;                 *(u32x4*)(RAT + (size_t)row * DM + col0) = pack8(ra[0], ra[1]); *(u32x4*)(SB + (size_t)row * DM + col0) = pack8(sb[0], sb[1]); }
	v_mov_b32_e32 v135, v237
	v_lshlrev_b64 v[2:3], 12, v[2:3]
	s_nop 1
	s_nop 0
	s_nop 0
	s_nop 1
	s_nop 1
	s_nop 0
	v_mov_b32_e32 v135, v237
	v_mul_f32_e32 v136, v8, v135
	v_mul_f32_e32 v136, 0xbfb8aa3b, v136
	v_exp_f32_e32 v136, v136
	v_mul_f32_e32 v137, v16, v135
	v_mul_f32_e32 v137, 0xbfb8aa3b, v137
	v_exp_f32_e32 v137, v137
	v_add_f32_e32 v136, 1.0, v136
	v_rcp_f32_e32 v136, v136
	v_mul_f32_e32 v139, v17, v135
	v_add_f32_e32 v137, 1.0, v137
	v_mul_f32_e32 v138, v9, v135
	v_max_f32_e32 v142, 0x38d1b717, v136
	v_mul_f32_e32 v139, 0xbfb8aa3b, v139
	v_rcp_f32_e32 v137, v137
	v_rcp_f32_e32 v136, v142
	v_mul_f32_e32 v138, 0xbfb8aa3b, v138
	v_exp_f32_e32 v139, v139
	v_exp_f32_e32 v138, v138
	v_mul_f32_e32 v136, v137, v136
	v_mul_f32_e32 v140, v18, v135
	v_add_f32_e32 v137, 1.0, v139
	v_mul_f32_e32 v139, v10, v135
	v_add_f32_e32 v138, 1.0, v138
	v_mul_f32_e32 v139, 0xbfb8aa3b, v139
	v_rcp_f32_e32 v138, v138
	v_exp_f32_e32 v139, v139
	v_mul_f32_e32 v140, 0xbfb8aa3b, v140
	v_rcp_f32_e32 v137, v137
	v_max_f32_e32 v143, 0x38d1b717, v138
	v_add_f32_e32 v139, 1.0, v139
	v_rcp_f32_e32 v138, v143
	v_exp_f32_e32 v140, v140
	v_rcp_f32_e32 v139, v139
	v_mul_f32_e32 v141, v19, v135
	v_mul_f32_e32 v137, v137, v138
	v_add_f32_e32 v138, 1.0, v140
	v_max_f32_e32 v144, 0x38d1b717, v139
	v_mul_f32_e32 v140, v11, v135
	v_mul_f32_e32 v141, 0xbfb8aa3b, v141
	v_rcp_f32_e32 v138, v138
	v_rcp_f32_e32 v139, v144
	v_mul_f32_e32 v140, 0xbfb8aa3b, v140
	v_exp_f32_e32 v141, v141
	v_exp_f32_e32 v140, v140
	v_mul_f32_e32 v138, v138, v139
	v_mul_f32_e32 v146, v12, v135
	v_add_f32_e32 v139, 1.0, v141
	v_mul_f32_e32 v141, v4, v135
	v_add_f32_e32 v140, 1.0, v140
	v_mul_f32_e32 v141, 0xbfb8aa3b, v141
	v_rcp_f32_e32 v140, v140
	v_exp_f32_e32 v141, v141
	v_mul_f32_e32 v146, 0xbfb8aa3b, v146
	v_rcp_f32_e32 v139, v139
	v_max_f32_e32 v145, 0x38d1b717, v140
	v_add_f32_e32 v141, 1.0, v141
	v_rcp_f32_e32 v140, v145
	v_exp_f32_e32 v146, v146
	v_rcp_f32_e32 v141, v141
	v_mul_f32_e32 v147, v13, v135
	v_mul_f32_e32 v139, v139, v140
	v_add_f32_e32 v140, 1.0, v146
	v_max_f32_e32 v146, 0x38d1b717, v141
	v_mul_f32_e32 v141, v5, v135
	v_mul_f32_e32 v141, 0xbfb8aa3b, v141
	v_exp_f32_e32 v141, v141
	v_mul_f32_e32 v150, v14, v135
	v_mul_f32_e32 v147, 0xbfb8aa3b, v147
	v_exp_f32_e32 v147, v147
	v_add_f32_e32 v141, 1.0, v141
	v_rcp_f32_e32 v141, v141
	v_mul_f32_e32 v150, 0xbfb8aa3b, v150
	v_exp_f32_e32 v150, v150
	v_rcp_f32_e32 v140, v140
	v_max_f32_e32 v149, 0x38d1b717, v141
	v_mul_f32_e32 v141, v6, v135
	v_mul_f32_e32 v141, 0xbfb8aa3b, v141
	v_exp_f32_e32 v141, v141
	v_rcp_f32_e32 v148, v146
	v_add_f32_e32 v147, 1.0, v147
	v_rcp_f32_e32 v147, v147
	v_add_f32_e32 v141, 1.0, v141
	v_rcp_f32_e32 v141, v141
	v_rcp_f32_e32 v151, v149
	v_add_f32_e32 v150, 1.0, v150
	v_rcp_f32_e32 v150, v150
	v_max_f32_e32 v152, 0x38d1b717, v141
	v_mul_f32_e32 v141, v7, v135
	v_mul_f32_e32 v141, 0xbfb8aa3b, v141
	v_exp_f32_e32 v141, v141
	v_mul_f32_e32 v135, v15, v135
	v_mul_f32_e32 v135, 0xbfb8aa3b, v135
	v_exp_f32_e32 v135, v135
	v_add_f32_e32 v141, 1.0, v141
	v_rcp_f32_e32 v141, v141
	v_rcp_f32_e32 v153, v152
	v_add_f32_e32 v135, 1.0, v135
	v_rcp_f32_e32 v135, v135
	v_max_f32_e32 v154, 0x38d1b717, v141
	v_rcp_f32_e32 v141, v154
	v_mul_f32_e32 v140, v140, v148
	v_mul_f32_e32 v147, v147, v151
	v_cvt_pk_bf16_f32 v136, v136, v137
	v_mul_f32_e32 v135, v135, v141
	v_cvt_pk_bf16_f32 v137, v138, v139
	v_cvt_pk_bf16_f32 v138, v140, v147
	v_lshl_add_u64 v[140:141], s[16:17], 0, v[2:3]
	v_lshl_add_u64 v[2:3], s[18:19], 0, v[2:3]
	v_mul_f32_e32 v148, v150, v153
	v_cvt_pk_bf16_f32 v139, v148, v135
	v_lshl_add_u64 v[140:141], v[140:141], 0, v[132:133]
	v_lshl_add_u64 v[2:3], v[2:3], 0, v[132:133]
	global_store_dwordx4 v[140:141], v[136:139], off
	s_nop 1
	v_cvt_pk_bf16_f32 v136, v142, v143
	v_cvt_pk_bf16_f32 v137, v144, v145
	v_cvt_pk_bf16_f32 v138, v146, v149
	v_cvt_pk_bf16_f32 v139, v152, v154
	global_store_dwordx4 v[2:3], v[136:139], off

; DI float rs_of(const float* ss, int row) { return 1.0f / sqrtf(ss[row] * (1.0f / DM) + EPS); }
; __global__ void __launch_bounds__(512) mk_fwd(Params p) {
;     ...
;             const int gw = blockIdx.x * 8 + (tid >> 6);
;             if (gw < RS) {
;                 const float* pa = PART + (size_t)gw * DM + lane * 4; const float* pg = PART + (size_t)8 * 256 * DM + (size_t)gw * 4096; const float rg = rs_of(SSa, RP + gw);
; #pragma unroll
;                 for (int i = 0; i < 8; ++i) {
;                     const int col = i * 256 + lane * 4, gcol = 256 * (col >> 7) + (col & 127);
;                     f32x4 a1 = {0.f, 0.f, 0.f, 0.f}, a2 = a1, ga = a1, gb = a1;
;                     for (int ks = 0; ks < 4; ++ks) { a1 += *(const f32x4*)(pa + (size_t)ks * 256 * DM + i * 256); a2 += *(const f32x4*)(pa + (size_t)(ks + 4) * 256 * DM + i * 256); }
;                     for (int ks = 0; ks < 8; ++ks) { ga += *(const f32x4*)(pg + (size_t)ks * 256 * 4096 + gcol); gb += *(const f32x4*)(pg + (size_t)ks * 256 * 4096 + gcol + 128); }
.LBB0_1436:
	v_lshrrev_b32_e32 v0, 6, v184
	v_lshl_add_u32 v0, s2, 3, v0
	s_movk_i32 s5, 0x100
	v_cmp_gt_i32_e32 vcc, s5, v0
	s_and_saveexec_b64 s[16:17], vcc
	s_cbranch_execz .LBB0_1438
	v_add_u32_e32 v2, 0x8000, v0
	v_ashrrev_i32_e32 v3, 31, v2
	v_lshl_add_u64 v[4:5], v[2:3], 2, s[14:15]
	global_load_dword v14, v[4:5], off
	v_ashrrev_i32_e32 v1, 31, v0
	v_lshlrev_b64 v[4:5], 13, v[0:1]
	v_lshlrev_b32_e32 v10, 4, v186
	v_mov_b32_e32 v11, 0
	v_lshl_add_u64 v[4:5], s[8:9], 0, v[4:5]
	s_mov_b32 s7, 0x801000
	v_lshlrev_b64 v[0:1], 14, v[0:1]
	v_lshl_add_u64 v[18:19], v[4:5], 0, v[10:11]
	v_lshlrev_b32_e32 v6, 2, v186
	v_lshl_add_u64 v[12:13], s[18:19], 0, v[0:1]
	v_lshlrev_b64 v[0:1], 12, v[2:3]
	v_add_co_u32_e32 v2, vcc, s7, v18
	v_lshlrev_b32_e32 v7, 3, v184
	s_mov_b32 s14, 0x201000
	v_and_b32_e32 v6, 0x7c, v6
	v_addc_co_u32_e32 v3, vcc, 0, v19, vcc
	v_and_or_b32 v16, v7, s5, v6
	v_add_co_u32_e32 v6, vcc, s14, v18
	s_mov_b32 s15, 0xa01000
	s_nop 0
	v_addc_co_u32_e32 v7, vcc, 0, v19, vcc
	v_add_co_u32_e32 v4, vcc, s15, v18
	s_mov_b32 s28, 0x401000
	v_lshl_add_u64 v[0:1], s[12:13], 0, v[0:1]
	v_lshlrev_b32_e32 v10, 3, v186
	v_addc_co_u32_e32 v5, vcc, 0, v19, vcc
	v_lshl_add_u64 v[0:1], v[0:1], 0, v[10:11]
	v_add_co_u32_e32 v8, vcc, s28, v18
	v_lshlrev_b32_e32 v10, 2, v16
	s_mov_b32 s1, 0x400000
	v_addc_co_u32_e32 v9, vcc, 0, v19, vcc
	v_lshl_add_u64 v[16:17], v[12:13], 0, v[10:11]
	v_add_co_u32_e32 v40, vcc, s1, v16
	s_mov_b32 s3, 0x800000
	s_nop 0
	v_addc_co_u32_e32 v41, vcc, 0, v17, vcc
	v_add_co_u32_e32 v22, vcc, s28, v16
	s_mov_b32 s0, 0xc00000
	s_nop 0
	v_addc_co_u32_e32 v23, vcc, 0, v17, vcc
	v_add_co_u32_e32 v42, vcc, s3, v16
	s_mov_b32 s4, 0xc01000
	s_nop 0
	v_addc_co_u32_e32 v43, vcc, 0, v17, vcc
	v_add_co_u32_e32 v26, vcc, s7, v16
	v_mov_b32_e32 v15, 0x358637bd
	s_nop 0
	v_addc_co_u32_e32 v27, vcc, 0, v17, vcc
	v_add_co_u32_e32 v44, vcc, s0, v16
	s_mov_b32 s6, 0xf800000
	s_nop 0
	v_addc_co_u32_e32 v45, vcc, 0, v17, vcc
	v_add_co_u32_e32 v24, vcc, s4, v16
	s_mov_b32 s29, 0x1000000
	s_nop 0
	v_addc_co_u32_e32 v25, vcc, 0, v17, vcc
	s_mov_b32 s5, 0x1001000
	global_load_dwordx4 v[54:57], v[18:19], off
	global_load_dwordx4 v[58:61], v[6:7], off offset:-4096
	global_load_dwordx4 v[62:65], v[4:5], off offset:-4096
	global_load_dwordx4 v[66:69], v[16:17], off
	global_load_dwordx4 v[70:73], v[16:17], off offset:512
	global_load_dwordx4 v[74:77], v[22:23], off offset:-4096
	global_load_dwordx4 v[78:81], v[26:27], off offset:-4096
	global_load_dwordx4 v[82:85], v[40:41], off offset:512
	global_load_dwordx4 v[86:89], v[42:43], off offset:512
	s_waitcnt vmcnt(0)
	v_mov_b32_e32 v214, v14
	v_pk_add_f32 v[56:57], v[56:57], 0 op_sel_hi:[1,0]
	s_nop 0
	v_pk_add_f32 v[66:67], v[66:67], 0 op_sel_hi:[1,0]
	v_pk_add_f32 v[70:71], v[70:71], 0 op_sel_hi:[1,0]
	v_pk_add_f32 v[66:67], v[66:67], v[74:75]
	v_add_co_u32_e64 v20, s[6:7], s29, v16
	v_pk_add_f32 v[70:71], v[70:71], v[82:83]
	s_nop 0
	v_addc_co_u32_e64 v21, s[6:7], 0, v17, s[6:7]
	v_add_co_u32_e64 v28, s[6:7], s5, v16
	s_mov_b32 s5, 0x1400000
	s_nop 0
	v_addc_co_u32_e64 v29, s[6:7], 0, v17, s[6:7]
	v_add_co_u32_e64 v46, s[6:7], s5, v16
	s_mov_b32 s5, 0x1401000
	s_nop 0
	v_addc_co_u32_e64 v47, s[6:7], 0, v17, s[6:7]
	v_add_co_u32_e64 v30, s[6:7], s5, v16
	s_mov_b32 s5, 0x1800000
	s_nop 0
	v_addc_co_u32_e64 v31, s[6:7], 0, v17, s[6:7]
	v_add_co_u32_e64 v48, s[6:7], s5, v16
	s_mov_b32 s5, 0x1801000
	s_nop 0
	v_addc_co_u32_e64 v49, s[6:7], 0, v17, s[6:7]
	v_add_co_u32_e64 v32, s[6:7], s5, v16
	s_mov_b32 s5, 0x1c00000
	s_nop 0
	v_addc_co_u32_e64 v33, s[6:7], 0, v17, s[6:7]
	v_add_co_u32_e64 v50, s[6:7], s5, v16
	global_load_dwordx4 v[90:93], v[24:25], off offset:-4096
	global_load_dwordx4 v[94:97], v[28:29], off offset:-4096
	global_load_dwordx4 v[98:101], v[44:45], off offset:512
	global_load_dwordx4 v[102:105], v[20:21], off offset:512
	v_addc_co_u32_e64 v51, s[6:7], 0, v17, s[6:7]
	s_mov_b32 s5, 0x1c01000
	v_add_co_u32_e64 v34, s[6:7], s5, v16
	global_load_dwordx4 v[106:109], v[30:31], off offset:-4096
	global_load_dwordx4 v[110:113], v[32:33], off offset:-4096
	global_load_dwordx4 v[114:117], v[46:47], off offset:512
	global_load_dwordx4 v[118:121], v[48:49], off offset:512
	v_addc_co_u32_e64 v35, s[6:7], 0, v17, s[6:7]
	global_load_dwordx4 v[122:125], v[34:35], off offset:-4096
	global_load_dwordx4 v[126:129], v[2:3], off offset:-4096
	global_load_dwordx4 v[130:133], v[50:51], off offset:512
	v_add_co_u32_e64 v10, s[6:7], s4, v18
	s_mov_b32 s4, 0x601000
	s_nop 0
	v_addc_co_u32_e64 v11, s[6:7], 0, v19, s[6:7]
	v_add_co_u32_e64 v12, s[6:7], s4, v18
	global_load_dwordx4 v[134:137], v[8:9], off offset:-4096
	global_load_dwordx4 v[138:141], v[10:11], off offset:-4096
	v_addc_co_u32_e64 v13, s[6:7], 0, v19, s[6:7]
	global_load_dwordx4 v[142:145], v[12:13], off offset:-4096
	s_mov_b32 s4, 0xe01000
	v_add_co_u32_e64 v14, s[6:7], s4, v18
	v_pk_add_f32 v[66:67], v[66:67], v[78:79]
	s_nop 0
	v_addc_co_u32_e64 v15, s[6:7], 0, v19, s[6:7]
	global_load_dwordx4 v[146:149], v[14:15], off offset:-4096
	v_pk_add_f32 v[70:71], v[70:71], v[86:87]
	v_pk_add_f32 v[68:69], v[68:69], 0 op_sel_hi:[1,0]
	v_mov_b32_e32 v38, 0x260
	v_pk_add_f32 v[68:69], v[68:69], v[76:77]
	v_pk_add_f32 v[56:57], v[56:57], v[60:61]
	v_pk_add_f32 v[54:55], v[54:55], 0 op_sel_hi:[1,0]
	v_pk_add_f32 v[72:73], v[72:73], 0 op_sel_hi:[1,0]
	v_pk_add_f32 v[54:55], v[54:55], v[58:59]
	v_mov_b32_e32 v52, v214
	v_pk_add_f32 v[72:73], v[72:73], v[84:85]
	v_pk_add_f32 v[68:69], v[68:69], v[80:81]
	v_pk_add_f32 v[72:73], v[72:73], v[88:89]
	v_add_co_u32_e32 v36, vcc, s3, v18
	s_mov_b32 s3, 0x200000
	s_nop 0
	v_addc_co_u32_e32 v37, vcc, 0, v19, vcc
	v_add_co_u32_e32 v38, vcc, s3, v18
	s_mov_b32 s3, 0xa00000
	s_nop 0
	v_addc_co_u32_e32 v39, vcc, 0, v19, vcc
	s_waitcnt vmcnt(0)
; DI unsigned cvt_pk_bf16(float lo, float hi) { unsigned r; asm volatile("v_cvt_pk_bf16_f32 %0, %1, %2" : "=v"(r) : "v"(lo), "v"(hi)); return r; }
; DI float sigmoidf_(float x) { return __builtin_amdgcn_rcpf(1.0f + __builtin_amdgcn_exp2f(-x * LOG2E)); }
; __global__ void __launch_bounds__(512) mk_fwd(Params p) {
;     ...
;                 for (int i = 0; i < 8; ++i) {
;                     const int col = i * 256 + lane * 4, gcol = 256 * (col >> 7) + (col & 127);
;                     f32x4 a1 = {0.f, 0.f, 0.f, 0.f}, a2 = a1, ga = a1, gb = a1;
;                     for (int ks = 0; ks < 4; ++ks) { a1 += *(const f32x4*)(pa + (size_t)ks * 256 * DM + i * 256); a2 += *(const f32x4*)(pa + (size_t)(ks + 4) * 256 * DM + i * 256); }
;                     for (int ks = 0; ks < 8; ++ks) { ga += *(const f32x4*)(pg + (size_t)ks * 256 * 4096 + gcol); gb += *(const f32x4*)(pg + (size_t)ks * 256 * 4096 + gcol + 128); }
;                     f32x4 o;
; #pragma unroll
;                     for (int j = 0; j < 4; ++j) o[j] = sigmoidf_(ga[j] * rg) * a1[j] + sigmoidf_(gb[j] * rg) * a2[j];
;                     u32x2 w; w.x = cvt_pk_bf16(o[0], o[1]); w.y = cvt_pk_bf16(o[2], o[3]);
;                     *(u32x2*)(T + (size_t)(RP + gw) * DM + i * 256 + lane * 4) = w;
	v_pk_add_f32 v[66:67], v[66:67], v[90:91]
	s_nop 0
	v_pk_add_f32 v[66:67], v[66:67], v[94:95]
	v_pk_add_f32 v[70:71], v[70:71], v[98:99]
	v_pk_add_f32 v[68:69], v[68:69], v[92:93]
	v_pk_add_f32 v[70:71], v[70:71], v[102:103]
	v_pk_add_f32 v[72:73], v[72:73], v[100:101]
	v_pk_add_f32 v[66:67], v[66:67], v[106:107]
	v_pk_add_f32 v[68:69], v[68:69], v[96:97]
	v_pk_add_f32 v[70:71], v[70:71], v[114:115]
	v_pk_add_f32 v[66:67], v[66:67], v[110:111]
	v_pk_add_f32 v[70:71], v[70:71], v[118:119]
	v_pk_add_f32 v[66:67], v[66:67], v[122:123]
	v_pk_add_f32 v[70:71], v[70:71], v[130:131]
	v_pk_add_f32 v[76:77], v[126:127], 0 op_sel_hi:[1,0]
	v_mul_f32_e32 v53, v52, v66
	v_pk_add_f32 v[60:61], v[76:77], v[62:63]
	v_mul_f32_e32 v53, 0xbfb8aa3b, v53
	v_mul_f32_e32 v62, v52, v70
	v_exp_f32_e32 v53, v53
	v_mul_f32_e32 v62, 0xbfb8aa3b, v62
	v_exp_f32_e32 v63, v62
	v_pk_add_f32 v[54:55], v[54:55], v[134:135]
	v_add_f32_e32 v53, 1.0, v53
	v_rcp_f32_e32 v62, v53
	v_add_f32_e32 v53, 1.0, v63
	v_pk_add_f32 v[74:75], v[128:129], 0 op_sel_hi:[1,0]
	v_pk_add_f32 v[54:55], v[54:55], v[142:143]
	v_rcp_f32_e32 v63, v53
	v_mul_f32_e32 v53, v52, v67
	v_pk_add_f32 v[58:59], v[74:75], v[64:65]
	v_mov_b32_e32 v64, v54
	v_mul_f32_e32 v53, 0xbfb8aa3b, v53
	v_mul_f32_e32 v54, v52, v71
	v_exp_f32_e32 v53, v53
	v_mul_f32_e32 v54, 0xbfb8aa3b, v54
	v_exp_f32_e32 v54, v54
	v_pk_add_f32 v[72:73], v[72:73], v[104:105]
	v_add_f32_e32 v53, 1.0, v53
	v_rcp_f32_e32 v66, v53
	v_add_f32_e32 v53, 1.0, v54
	v_rcp_f32_e32 v67, v53
	v_pk_add_f32 v[68:69], v[68:69], v[108:109]
	v_pk_add_f32 v[60:61], v[60:61], v[138:139]
	v_pk_add_f32 v[72:73], v[72:73], v[116:117]
	v_pk_add_f32 v[68:69], v[68:69], v[112:113]
	v_pk_add_f32 v[60:61], v[60:61], v[146:147]
	v_pk_add_f32 v[72:73], v[72:73], v[120:121]
	v_pk_add_f32 v[68:69], v[68:69], v[124:125]
	v_mov_b32_e32 v65, v60
	v_mov_b32_e32 v60, v55
	v_pk_add_f32 v[72:73], v[72:73], v[132:133]
	v_pk_mul_f32 v[54:55], v[60:61], v[66:67]
	v_mul_f32_e32 v60, v52, v68
	v_mul_f32_e32 v60, 0xbfb8aa3b, v60
	v_mul_f32_e32 v61, v52, v72
	v_exp_f32_e32 v60, v60
	v_mul_f32_e32 v61, 0xbfb8aa3b, v61
	v_exp_f32_e32 v61, v61
	v_pk_add_f32 v[56:57], v[56:57], v[136:137]
	v_pk_mul_f32 v[62:63], v[64:65], v[62:63]
	v_pk_add_f32 v[56:57], v[56:57], v[144:145]
	v_add_f32_e32 v64, v54, v55
	v_add_f32_e32 v54, 1.0, v60
	v_mov_b32_e32 v60, v56
	v_mul_f32_e32 v56, v52, v69
	v_add_f32_e32 v55, 1.0, v61
	v_mul_f32_e32 v56, 0xbfb8aa3b, v56
	v_mul_f32_e32 v61, v52, v73
	v_exp_f32_e32 v56, v56
	v_mul_f32_e32 v61, 0xbfb8aa3b, v61
	v_add_f32_e32 v53, v62, v63
	v_exp_f32_e32 v63, v61
	v_add_f32_e32 v56, 1.0, v56
	v_rcp_f32_e32 v54, v54
	v_rcp_f32_e32 v55, v55
	v_rcp_f32_e32 v62, v56
	v_add_f32_e32 v56, 1.0, v63
	v_pk_add_f32 v[58:59], v[58:59], v[140:141]
	v_rcp_f32_e32 v63, v56
	v_pk_add_f32 v[58:59], v[58:59], v[148:149]
	s_nop 0
	v_mov_b32_e32 v61, v58
	v_pk_mul_f32 v[54:55], v[60:61], v[54:55]
	v_mov_b32_e32 v58, v57
	v_add_f32_e32 v56, v54, v55
	v_pk_mul_f32 v[54:55], v[58:59], v[62:63]
	s_nop 0
	v_add_f32_e32 v55, v54, v55
	v_cvt_pk_bf16_f32 v54, v53, v64
	v_cvt_pk_bf16_f32 v55, v56, v55
	global_store_dwordx2 v[0:1], v[54:55], off
	global_load_dwordx4 v[54:57], v[16:17], off offset:2048
	s_nop 0
	global_load_dwordx4 v[58:61], v[16:17], off offset:2560
	global_load_dwordx4 v[62:65], v[40:41], off offset:2048
	global_load_dwordx4 v[66:69], v[40:41], off offset:2560
	global_load_dwordx4 v[70:73], v[42:43], off offset:2048
	global_load_dwordx4 v[74:77], v[42:43], off offset:2560
	global_load_dwordx4 v[78:81], v[44:45], off offset:2048
	global_load_dwordx4 v[82:85], v[44:45], off offset:2560
	global_load_dwordx4 v[86:89], v[20:21], off offset:2048
	global_load_dwordx4 v[90:93], v[20:21], off offset:2560
	global_load_dwordx4 v[94:97], v[46:47], off offset:2048
	global_load_dwordx4 v[98:101], v[46:47], off offset:2560
	global_load_dwordx4 v[102:105], v[48:49], off offset:2048
	global_load_dwordx4 v[106:109], v[48:49], off offset:2560
	global_load_dwordx4 v[110:113], v[50:51], off offset:2048
	global_load_dwordx4 v[114:117], v[50:51], off offset:2560
	global_load_dwordx4 v[118:121], v[18:19], off offset:1024
	global_load_dwordx4 v[122:125], v[36:37], off offset:1024
	v_add_co_u32_e32 v40, vcc, s3, v18
	global_load_dwordx4 v[126:129], v[38:39], off offset:1024
	s_nop 0
	v_addc_co_u32_e32 v41, vcc, 0, v19, vcc
	v_add_co_u32_e32 v42, vcc, s1, v18
	s_movk_i32 s1, 0x2000
	s_nop 0
	v_addc_co_u32_e32 v43, vcc, 0, v19, vcc
	v_add_co_u32_e32 v44, vcc, s0, v18
	s_mov_b32 s0, 0x600000
	s_nop 0
	v_addc_co_u32_e32 v45, vcc, 0, v19, vcc
	v_add_co_u32_e32 v46, vcc, s0, v18
	s_mov_b32 s0, 0xe00000
	s_nop 0
	v_addc_co_u32_e32 v47, vcc, 0, v19, vcc
	v_add_co_u32_e32 v48, vcc, s0, v18
	global_load_dwordx4 v[130:133], v[40:41], off offset:1024
	global_load_dwordx4 v[134:137], v[42:43], off offset:1024
	global_load_dwordx4 v[138:141], v[44:45], off offset:1024
	global_load_dwordx4 v[142:145], v[46:47], off offset:1024
	v_addc_co_u32_e32 v49, vcc, 0, v19, vcc
	global_load_dwordx4 v[146:149], v[48:49], off offset:1024
	s_movk_i32 s0, 0x1000
	s_waitcnt vmcnt(0)
; DI unsigned cvt_pk_bf16(float lo, float hi) { unsigned r; asm volatile("v_cvt_pk_bf16_f32 %0, %1, %2" : "=v"(r) : "v"(lo), "v"(hi)); return r; }
; DI float sigmoidf_(float x) { return __builtin_amdgcn_rcpf(1.0f + __builtin_amdgcn_exp2f(-x * LOG2E)); }
; __global__ void __launch_bounds__(512) mk_fwd(Params p) {
;     ...
;                 for (int i = 0; i < 8; ++i) {
;                     const int col = i * 256 + lane * 4, gcol = 256 * (col >> 7) + (col & 127);
;                     f32x4 a1 = {0.f, 0.f, 0.f, 0.f}, a2 = a1, ga = a1, gb = a1;
;                     for (int ks = 0; ks < 4; ++ks) { a1 += *(const f32x4*)(pa + (size_t)ks * 256 * DM + i * 256); a2 += *(const f32x4*)(pa + (size_t)(ks + 4) * 256 * DM + i * 256); }
;                     for (int ks = 0; ks < 8; ++ks) { ga += *(const f32x4*)(pg + (size_t)ks * 256 * 4096 + gcol); gb += *(const f32x4*)(pg + (size_t)ks * 256 * 4096 + gcol + 128); }
;                     f32x4 o;
; #pragma unroll
;                     for (int j = 0; j < 4; ++j) o[j] = sigmoidf_(ga[j] * rg) * a1[j] + sigmoidf_(gb[j] * rg) * a2[j];
;                     u32x2 w; w.x = cvt_pk_bf16(o[0], o[1]); w.y = cvt_pk_bf16(o[2], o[3]);
;                     *(u32x2*)(T + (size_t)(RP + gw) * DM + i * 256 + lane * 4) = w;
;                 }
	v_pk_add_f32 v[50:51], v[54:55], 0 op_sel_hi:[1,0]
	v_pk_add_f32 v[20:21], v[56:57], 0 op_sel_hi:[1,0]
	v_pk_add_f32 v[56:57], v[58:59], 0 op_sel_hi:[1,0]
	v_pk_add_f32 v[50:51], v[50:51], v[62:63]
	v_pk_add_f32 v[56:57], v[56:57], v[66:67]
	v_pk_add_f32 v[50:51], v[50:51], v[70:71]
	v_pk_add_f32 v[56:57], v[56:57], v[74:75]
	v_pk_add_f32 v[50:51], v[50:51], v[78:79]
	v_pk_add_f32 v[56:57], v[56:57], v[82:83]
	v_pk_add_f32 v[50:51], v[50:51], v[86:87]
	v_pk_add_f32 v[56:57], v[56:57], v[90:91]
	v_pk_add_f32 v[50:51], v[50:51], v[94:95]
	v_pk_add_f32 v[56:57], v[56:57], v[98:99]
	v_pk_add_f32 v[50:51], v[50:51], v[102:103]
	v_pk_add_f32 v[56:57], v[56:57], v[106:107]
	v_pk_add_f32 v[50:51], v[50:51], v[110:111]
	v_pk_add_f32 v[56:57], v[56:57], v[114:115]
	v_mul_f32_e32 v50, v52, v50
	v_mul_f32_e32 v50, 0xbfb8aa3b, v50
	v_mul_f32_e32 v53, v52, v56
	v_exp_f32_e32 v50, v50
	v_mul_f32_e32 v53, 0xbfb8aa3b, v53
	v_exp_f32_e32 v53, v53
	v_pk_add_f32 v[54:55], v[60:61], 0 op_sel_hi:[1,0]
	v_pk_add_f32 v[20:21], v[20:21], v[64:65]
	v_mul_f32_e32 v51, v52, v51
	v_pk_add_f32 v[54:55], v[54:55], v[68:69]
	v_pk_add_f32 v[20:21], v[20:21], v[72:73]
	v_add_f32_e32 v50, 1.0, v50
	v_mul_f32_e32 v51, 0xbfb8aa3b, v51
	v_pk_add_f32 v[54:55], v[54:55], v[76:77]
	v_pk_add_f32 v[20:21], v[20:21], v[80:81]
	v_rcp_f32_e32 v66, v50
	v_add_f32_e32 v50, 1.0, v53
	v_exp_f32_e32 v53, v51
	v_mul_f32_e32 v51, v52, v57
	v_pk_add_f32 v[54:55], v[54:55], v[84:85]
	v_pk_add_f32 v[20:21], v[20:21], v[88:89]
	v_mul_f32_e32 v51, 0xbfb8aa3b, v51
	v_pk_add_f32 v[54:55], v[54:55], v[92:93]
	v_pk_add_f32 v[20:21], v[20:21], v[96:97]
	v_exp_f32_e32 v57, v51
	v_pk_add_f32 v[54:55], v[54:55], v[100:101]
	v_pk_add_f32 v[20:21], v[20:21], v[104:105]
	v_pk_add_f32 v[54:55], v[54:55], v[108:109]
	v_pk_add_f32 v[20:21], v[20:21], v[112:113]
	v_pk_add_f32 v[54:55], v[54:55], v[116:117]
	v_pk_add_f32 v[60:61], v[118:119], 0 op_sel_hi:[1,0]
	v_pk_add_f32 v[64:65], v[122:123], 0 op_sel_hi:[1,0]
	v_add_f32_e32 v53, 1.0, v53
	v_mul_f32_e32 v20, v52, v20
	v_pk_add_f32 v[60:61], v[60:61], v[126:127]
	v_pk_add_f32 v[64:65], v[64:65], v[130:131]
	v_rcp_f32_e32 v67, v50
	v_rcp_f32_e32 v56, v53
	v_add_f32_e32 v53, 1.0, v57
	v_mul_f32_e32 v20, 0xbfb8aa3b, v20
	v_mul_f32_e32 v54, v52, v54
	v_pk_add_f32 v[60:61], v[60:61], v[134:135]
	v_pk_add_f32 v[64:65], v[64:65], v[138:139]
	v_rcp_f32_e32 v57, v53
	v_exp_f32_e32 v20, v20
	v_mul_f32_e32 v54, 0xbfb8aa3b, v54
	v_pk_add_f32 v[60:61], v[60:61], v[142:143]
	v_pk_add_f32 v[64:65], v[64:65], v[146:147]
	v_exp_f32_e32 v54, v54
	v_mov_b32_e32 v50, v60
	v_mov_b32_e32 v51, v64
	v_pk_mul_f32 v[50:51], v[50:51], v[66:67]
	v_mov_b32_e32 v64, v61
	v_mul_f32_e32 v21, v52, v21
	v_add_f32_e32 v53, v50, v51
	v_pk_mul_f32 v[50:51], v[64:65], v[56:57]
	v_add_f32_e32 v20, 1.0, v20
	v_mul_f32_e32 v21, 0xbfb8aa3b, v21
	v_add_f32_e32 v56, v50, v51
	v_rcp_f32_e32 v50, v20
	v_add_f32_e32 v20, 1.0, v54
	v_exp_f32_e32 v54, v21
	v_mul_f32_e32 v21, v52, v55
	v_mul_f32_e32 v21, 0xbfb8aa3b, v21
	v_exp_f32_e32 v55, v21
	v_pk_add_f32 v[58:59], v[120:121], 0 op_sel_hi:[1,0]
	v_pk_add_f32 v[62:63], v[124:125], 0 op_sel_hi:[1,0]
	v_pk_add_f32 v[58:59], v[58:59], v[128:129]
	v_pk_add_f32 v[62:63], v[62:63], v[132:133]
	v_rcp_f32_e32 v51, v20
	v_add_f32_e32 v54, 1.0, v54
	v_add_f32_e32 v55, 1.0, v55
	v_pk_add_f32 v[58:59], v[58:59], v[136:137]
	v_pk_add_f32 v[62:63], v[62:63], v[140:141]
	v_rcp_f32_e32 v54, v54
	v_rcp_f32_e32 v55, v55
	v_pk_add_f32 v[58:59], v[58:59], v[144:145]
	v_pk_add_f32 v[62:63], v[62:63], v[148:149]
	v_mov_b32_e32 v20, v58
	v_mov_b32_e32 v21, v62
	v_pk_mul_f32 v[20:21], v[20:21], v[50:51]
	v_mov_b32_e32 v62, v59
	v_add_f32_e32 v50, v20, v21
	v_pk_mul_f32 v[20:21], v[62:63], v[54:55]
	s_nop 0
	v_add_f32_e32 v21, v20, v21
	v_cvt_pk_bf16_f32 v20, v53, v56
	v_cvt_pk_bf16_f32 v21, v50, v21
	global_store_dwordx2 v[0:1], v[20:21], off offset:512
	v_add_co_u32_e32 v20, vcc, s1, v16
	s_mov_b32 s1, 0x402000
	s_nop 0
	v_addc_co_u32_e32 v21, vcc, 0, v17, vcc
	global_load_dwordx4 v[54:57], v[20:21], off offset:-4096
	v_add_co_u32_e32 v50, vcc, s0, v16
	s_waitcnt vmcnt(0)
	v_pk_add_f32 v[54:55], v[54:55], 0 op_sel_hi:[1,0]
	v_addc_co_u32_e32 v51, vcc, 0, v17, vcc
	global_load_dwordx4 v[58:61], v[50:51], off offset:512
	global_load_dwordx4 v[62:65], v[22:23], off
	global_load_dwordx4 v[66:69], v[22:23], off offset:512
	global_load_dwordx4 v[70:73], v[26:27], off
	global_load_dwordx4 v[74:77], v[26:27], off offset:512
	global_load_dwordx4 v[78:81], v[24:25], off
	global_load_dwordx4 v[82:85], v[24:25], off offset:512
	global_load_dwordx4 v[86:89], v[28:29], off
	global_load_dwordx4 v[90:93], v[28:29], off offset:512
	global_load_dwordx4 v[94:97], v[30:31], off
	global_load_dwordx4 v[98:101], v[30:31], off offset:512
	global_load_dwordx4 v[102:105], v[32:33], off
	global_load_dwordx4 v[106:109], v[32:33], off offset:512
	global_load_dwordx4 v[110:113], v[34:35], off
	global_load_dwordx4 v[114:117], v[34:35], off offset:512
	global_load_dwordx4 v[118:121], v[18:19], off offset:2048
	global_load_dwordx4 v[122:125], v[36:37], off offset:2048
	global_load_dwordx4 v[126:129], v[38:39], off offset:2048
	global_load_dwordx4 v[130:133], v[40:41], off offset:2048
	global_load_dwordx4 v[134:137], v[42:43], off offset:2048
	global_load_dwordx4 v[138:141], v[44:45], off offset:2048
	global_load_dwordx4 v[142:145], v[46:47], off offset:2048
	global_load_dwordx4 v[146:149], v[48:49], off offset:2048
	v_pk_add_f32 v[56:57], v[56:57], 0 op_sel_hi:[1,0]
	s_waitcnt vmcnt(0)
; DI unsigned cvt_pk_bf16(float lo, float hi) { unsigned r; asm volatile("v_cvt_pk_bf16_f32 %0, %1, %2" : "=v"(r) : "v"(lo), "v"(hi)); return r; }
; DI float sigmoidf_(float x) { return __builtin_amdgcn_rcpf(1.0f + __builtin_amdgcn_exp2f(-x * LOG2E)); }
; __global__ void __launch_bounds__(512) mk_fwd(Params p) {
;     ...
;                 for (int i = 0; i < 8; ++i) {
;                     const int col = i * 256 + lane * 4, gcol = 256 * (col >> 7) + (col & 127);
;                     f32x4 a1 = {0.f, 0.f, 0.f, 0.f}, a2 = a1, ga = a1, gb = a1;
;                     for (int ks = 0; ks < 4; ++ks) { a1 += *(const f32x4*)(pa + (size_t)ks * 256 * DM + i * 256); a2 += *(const f32x4*)(pa + (size_t)(ks + 4) * 256 * DM + i * 256); }
;                     for (int ks = 0; ks < 8; ++ks) { ga += *(const f32x4*)(pg + (size_t)ks * 256 * 4096 + gcol); gb += *(const f32x4*)(pg + (size_t)ks * 256 * 4096 + gcol + 128); }
;                     f32x4 o;
; #pragma unroll
;                     for (int j = 0; j < 4; ++j) o[j] = sigmoidf_(ga[j] * rg) * a1[j] + sigmoidf_(gb[j] * rg) * a2[j];
;                     u32x2 w; w.x = cvt_pk_bf16(o[0], o[1]); w.y = cvt_pk_bf16(o[2], o[3]);
;                     *(u32x2*)(T + (size_t)(RP + gw) * DM + i * 256 + lane * 4) = w;
;                 }
	v_pk_add_f32 v[58:59], v[58:59], 0 op_sel_hi:[1,0]
	v_pk_add_f32 v[54:55], v[54:55], v[62:63]
	v_pk_add_f32 v[58:59], v[58:59], v[66:67]
	v_pk_add_f32 v[54:55], v[54:55], v[70:71]
	v_pk_add_f32 v[58:59], v[58:59], v[74:75]
	v_pk_add_f32 v[54:55], v[54:55], v[78:79]
	v_pk_add_f32 v[58:59], v[58:59], v[82:83]
	v_pk_add_f32 v[54:55], v[54:55], v[86:87]
	v_pk_add_f32 v[58:59], v[58:59], v[90:91]
	v_pk_add_f32 v[54:55], v[54:55], v[94:95]
	v_pk_add_f32 v[58:59], v[58:59], v[98:99]
	v_pk_add_f32 v[54:55], v[54:55], v[102:103]
	v_pk_add_f32 v[58:59], v[58:59], v[106:107]
	v_pk_add_f32 v[54:55], v[54:55], v[110:111]
	v_pk_add_f32 v[58:59], v[58:59], v[114:115]
	v_mul_f32_e32 v53, v52, v54
	v_mul_f32_e32 v53, 0xbfb8aa3b, v53
	v_mul_f32_e32 v54, v52, v58
	v_exp_f32_e32 v53, v53
	v_mul_f32_e32 v54, 0xbfb8aa3b, v54
	v_exp_f32_e32 v54, v54
	v_pk_add_f32 v[60:61], v[60:61], 0 op_sel_hi:[1,0]
	v_add_f32_e32 v53, 1.0, v53
	v_rcp_f32_e32 v70, v53
	v_add_f32_e32 v53, 1.0, v54
	v_rcp_f32_e32 v71, v53
	v_mul_f32_e32 v53, v52, v55
	v_mul_f32_e32 v53, 0xbfb8aa3b, v53
	v_mul_f32_e32 v55, v52, v59
	v_exp_f32_e32 v53, v53
	v_mul_f32_e32 v55, 0xbfb8aa3b, v55
	v_exp_f32_e32 v59, v55
	v_pk_add_f32 v[60:61], v[60:61], v[68:69]
	v_pk_add_f32 v[56:57], v[56:57], v[64:65]
	v_pk_add_f32 v[60:61], v[60:61], v[76:77]
	v_pk_add_f32 v[64:65], v[118:119], 0 op_sel_hi:[1,0]
	v_pk_add_f32 v[68:69], v[122:123], 0 op_sel_hi:[1,0]
	v_add_f32_e32 v53, 1.0, v53
	v_pk_add_f32 v[60:61], v[60:61], v[84:85]
	v_pk_add_f32 v[64:65], v[64:65], v[126:127]
	v_pk_add_f32 v[68:69], v[68:69], v[130:131]
	v_rcp_f32_e32 v58, v53
	v_add_f32_e32 v53, 1.0, v59
	v_pk_add_f32 v[60:61], v[60:61], v[92:93]
	v_pk_add_f32 v[64:65], v[64:65], v[134:135]
	v_pk_add_f32 v[68:69], v[68:69], v[138:139]
	v_rcp_f32_e32 v59, v53
	v_pk_add_f32 v[60:61], v[60:61], v[100:101]
	v_pk_add_f32 v[64:65], v[64:65], v[142:143]
	v_pk_add_f32 v[68:69], v[68:69], v[146:147]
	v_pk_add_f32 v[56:57], v[56:57], v[72:73]
	v_pk_add_f32 v[60:61], v[60:61], v[108:109]
	v_mov_b32_e32 v54, v64
	v_mov_b32_e32 v55, v68
	v_pk_add_f32 v[56:57], v[56:57], v[80:81]
	v_pk_add_f32 v[60:61], v[60:61], v[116:117]
	v_pk_mul_f32 v[54:55], v[54:55], v[70:71]
	v_mov_b32_e32 v68, v65
	v_pk_add_f32 v[56:57], v[56:57], v[88:89]
	v_add_f32_e32 v53, v54, v55
	v_pk_mul_f32 v[54:55], v[68:69], v[58:59]
	v_mul_f32_e32 v58, v52, v60
	v_pk_add_f32 v[56:57], v[56:57], v[96:97]
	v_mul_f32_e32 v58, 0xbfb8aa3b, v58
	v_pk_add_f32 v[56:57], v[56:57], v[104:105]
	v_exp_f32_e32 v58, v58
	v_pk_add_f32 v[56:57], v[56:57], v[112:113]
	v_add_f32_e32 v60, v54, v55
	v_mul_f32_e32 v57, v52, v57
	v_mul_f32_e32 v56, v52, v56
	v_mul_f32_e32 v57, 0xbfb8aa3b, v57
	v_mul_f32_e32 v56, 0xbfb8aa3b, v56
	v_add_f32_e32 v55, 1.0, v58
	v_exp_f32_e32 v58, v57
	v_mul_f32_e32 v57, v52, v61
	v_exp_f32_e32 v56, v56
	v_mul_f32_e32 v57, 0xbfb8aa3b, v57
	v_exp_f32_e32 v59, v57
	v_pk_add_f32 v[62:63], v[120:121], 0 op_sel_hi:[1,0]
	v_pk_add_f32 v[66:67], v[124:125], 0 op_sel_hi:[1,0]
	v_add_f32_e32 v54, 1.0, v56
	v_pk_add_f32 v[62:63], v[62:63], v[128:129]
	v_pk_add_f32 v[66:67], v[66:67], v[132:133]
	v_rcp_f32_e32 v54, v54
	v_rcp_f32_e32 v55, v55
	v_add_f32_e32 v58, 1.0, v58
	v_add_f32_e32 v59, 1.0, v59
	v_pk_add_f32 v[62:63], v[62:63], v[136:137]
	v_pk_add_f32 v[66:67], v[66:67], v[140:141]
	v_rcp_f32_e32 v58, v58
	v_rcp_f32_e32 v59, v59
	v_pk_add_f32 v[62:63], v[62:63], v[144:145]
	v_pk_add_f32 v[66:67], v[66:67], v[148:149]
	v_mov_b32_e32 v56, v62
	v_mov_b32_e32 v57, v66
	v_pk_mul_f32 v[54:55], v[56:57], v[54:55]
	v_mov_b32_e32 v66, v63
	v_add_f32_e32 v56, v54, v55
	v_pk_mul_f32 v[54:55], v[66:67], v[58:59]
	s_nop 0
	v_add_f32_e32 v55, v54, v55
	v_cvt_pk_bf16_f32 v54, v53, v60
	v_cvt_pk_bf16_f32 v55, v56, v55
	global_store_dwordx2 v[0:1], v[54:55], off offset:1024
	global_load_dwordx4 v[54:57], v[50:51], off offset:2048
	s_nop 0
	global_load_dwordx4 v[58:61], v[50:51], off offset:2560
	global_load_dwordx4 v[62:65], v[22:23], off offset:2048
	global_load_dwordx4 v[66:69], v[22:23], off offset:2560
	global_load_dwordx4 v[70:73], v[26:27], off offset:2048
	global_load_dwordx4 v[74:77], v[26:27], off offset:2560
	global_load_dwordx4 v[78:81], v[24:25], off offset:2048
	global_load_dwordx4 v[82:85], v[24:25], off offset:2560
	global_load_dwordx4 v[86:89], v[28:29], off offset:2048
	global_load_dwordx4 v[90:93], v[28:29], off offset:2560
	global_load_dwordx4 v[94:97], v[30:31], off offset:2048
	global_load_dwordx4 v[98:101], v[30:31], off offset:2560
	global_load_dwordx4 v[102:105], v[32:33], off offset:2048
	global_load_dwordx4 v[106:109], v[32:33], off offset:2560
	global_load_dwordx4 v[110:113], v[34:35], off offset:2048
	global_load_dwordx4 v[22:25], v[34:35], off offset:2560
	global_load_dwordx4 v[26:29], v[18:19], off offset:3072
	s_nop 0
	global_load_dwordx4 v[30:33], v[36:37], off offset:3072
	s_nop 0
	global_load_dwordx4 v[34:37], v[38:39], off offset:3072
	s_nop 0
	global_load_dwordx4 v[38:41], v[40:41], off offset:3072
	s_nop 0
	global_load_dwordx4 v[114:117], v[42:43], off offset:3072
	s_nop 0
	global_load_dwordx4 v[42:45], v[44:45], off offset:3072
	s_nop 0
	global_load_dwordx4 v[118:121], v[46:47], off offset:3072
	s_nop 0
	global_load_dwordx4 v[46:49], v[48:49], off offset:3072
	s_waitcnt vmcnt(0)
; DI unsigned cvt_pk_bf16(float lo, float hi) { unsigned r; asm volatile("v_cvt_pk_bf16_f32 %0, %1, %2" : "=v"(r) : "v"(lo), "v"(hi)); return r; }
; DI float sigmoidf_(float x) { return __builtin_amdgcn_rcpf(1.0f + __builtin_amdgcn_exp2f(-x * LOG2E)); }
; __global__ void __launch_bounds__(512) mk_fwd(Params p) {
;     ...
;                 for (int i = 0; i < 8; ++i) {
;                     const int col = i * 256 + lane * 4, gcol = 256 * (col >> 7) + (col & 127);
;                     f32x4 a1 = {0.f, 0.f, 0.f, 0.f}, a2 = a1, ga = a1, gb = a1;
;                     for (int ks = 0; ks < 4; ++ks) { a1 += *(const f32x4*)(pa + (size_t)ks * 256 * DM + i * 256); a2 += *(const f32x4*)(pa + (size_t)(ks + 4) * 256 * DM + i * 256); }
;                     for (int ks = 0; ks < 8; ++ks) { ga += *(const f32x4*)(pg + (size_t)ks * 256 * 4096 + gcol); gb += *(const f32x4*)(pg + (size_t)ks * 256 * 4096 + gcol + 128); }
;                     f32x4 o;
; #pragma unroll
;                     for (int j = 0; j < 4; ++j) o[j] = sigmoidf_(ga[j] * rg) * a1[j] + sigmoidf_(gb[j] * rg) * a2[j];
;                     u32x2 w; w.x = cvt_pk_bf16(o[0], o[1]); w.y = cvt_pk_bf16(o[2], o[3]);
;                     *(u32x2*)(T + (size_t)(RP + gw) * DM + i * 256 + lane * 4) = w;
;                 }
	v_pk_add_f32 v[54:55], v[54:55], 0 op_sel_hi:[1,0]
	v_pk_add_f32 v[58:59], v[58:59], 0 op_sel_hi:[1,0]
	v_pk_add_f32 v[54:55], v[54:55], v[62:63]
	v_pk_add_f32 v[58:59], v[58:59], v[66:67]
	v_pk_add_f32 v[54:55], v[54:55], v[70:71]
	v_pk_add_f32 v[58:59], v[58:59], v[74:75]
	v_pk_add_f32 v[54:55], v[54:55], v[78:79]
	v_pk_add_f32 v[58:59], v[58:59], v[82:83]
	v_pk_add_f32 v[54:55], v[54:55], v[86:87]
	v_pk_add_f32 v[58:59], v[58:59], v[90:91]
	v_pk_add_f32 v[54:55], v[54:55], v[94:95]
	v_pk_add_f32 v[58:59], v[58:59], v[98:99]
	v_pk_add_f32 v[54:55], v[54:55], v[102:103]
	v_pk_add_f32 v[58:59], v[58:59], v[106:107]
	v_pk_add_f32 v[54:55], v[54:55], v[110:111]
	v_pk_add_f32 v[50:51], v[56:57], 0 op_sel_hi:[1,0]
	v_pk_add_f32 v[56:57], v[60:61], 0 op_sel_hi:[1,0]
	v_pk_add_f32 v[50:51], v[50:51], v[64:65]
	v_pk_add_f32 v[56:57], v[56:57], v[68:69]
	v_pk_add_f32 v[50:51], v[50:51], v[72:73]
	v_pk_add_f32 v[56:57], v[56:57], v[76:77]
	v_pk_add_f32 v[50:51], v[50:51], v[80:81]
	v_pk_add_f32 v[22:23], v[58:59], v[22:23]
	v_pk_add_f32 v[26:27], v[26:27], 0 op_sel_hi:[1,0]
	v_mul_f32_e32 v22, v52, v22
	v_mul_f32_e32 v22, 0xbfb8aa3b, v22
	v_exp_f32_e32 v22, v22
	v_pk_add_f32 v[26:27], v[26:27], v[34:35]
	v_mul_f32_e32 v34, v52, v54
	v_pk_add_f32 v[26:27], v[26:27], v[114:115]
	v_add_f32_e32 v22, 1.0, v22
	v_pk_add_f32 v[26:27], v[26:27], v[118:119]
	v_rcp_f32_e32 v35, v22
	v_mov_b32_e32 v22, v26
	v_mul_f32_e32 v26, v52, v55
	v_mul_f32_e32 v26, 0xbfb8aa3b, v26
	v_mul_f32_e32 v23, v52, v23
	v_pk_add_f32 v[28:29], v[28:29], 0 op_sel_hi:[1,0]
	v_mul_f32_e32 v34, 0xbfb8aa3b, v34
	v_exp_f32_e32 v26, v26
	v_mul_f32_e32 v23, 0xbfb8aa3b, v23
	v_pk_add_f32 v[28:29], v[28:29], v[36:37]
	v_exp_f32_e32 v34, v34
	v_exp_f32_e32 v37, v23
	v_pk_add_f32 v[50:51], v[50:51], v[88:89]
	v_add_f32_e32 v26, 1.0, v26
	v_pk_add_f32 v[50:51], v[50:51], v[96:97]
	v_pk_add_f32 v[30:31], v[30:31], 0 op_sel_hi:[1,0]
	v_pk_add_f32 v[50:51], v[50:51], v[104:105]
	v_add_f32_e32 v34, 1.0, v34
	v_pk_add_f32 v[50:51], v[50:51], v[112:113]
	v_rcp_f32_e32 v36, v26
	v_add_f32_e32 v26, 1.0, v37
	v_pk_add_f32 v[56:57], v[56:57], v[84:85]
	v_pk_add_f32 v[30:31], v[30:31], v[38:39]
	v_rcp_f32_e32 v34, v34
	v_rcp_f32_e32 v37, v26
	v_mul_f32_e32 v26, v52, v50
	v_pk_add_f32 v[56:57], v[56:57], v[92:93]
	v_pk_add_f32 v[30:31], v[30:31], v[42:43]
	v_mul_f32_e32 v26, 0xbfb8aa3b, v26
	v_pk_add_f32 v[56:57], v[56:57], v[100:101]
	v_pk_add_f32 v[30:31], v[30:31], v[46:47]
	v_exp_f32_e32 v26, v26
	v_pk_add_f32 v[56:57], v[56:57], v[108:109]
	v_mov_b32_e32 v23, v30
	v_pk_add_f32 v[24:25], v[56:57], v[24:25]
	v_pk_mul_f32 v[22:23], v[22:23], v[34:35]
	v_mov_b32_e32 v30, v27
	v_add_f32_e32 v34, v22, v23
	v_pk_mul_f32 v[22:23], v[30:31], v[36:37]
	v_mul_f32_e32 v24, v52, v24
	v_mul_f32_e32 v24, 0xbfb8aa3b, v24
	v_add_f32_e32 v30, v22, v23
	v_add_f32_e32 v22, 1.0, v26
	v_mul_f32_e32 v26, v52, v51
	v_mul_f32_e32 v25, v52, v25
	v_exp_f32_e32 v24, v24
	v_mul_f32_e32 v26, 0xbfb8aa3b, v26
	v_mul_f32_e32 v25, 0xbfb8aa3b, v25
	v_exp_f32_e32 v26, v26
	v_exp_f32_e32 v27, v25
	v_pk_add_f32 v[32:33], v[32:33], 0 op_sel_hi:[1,0]
	v_add_f32_e32 v23, 1.0, v24
	v_pk_add_f32 v[32:33], v[32:33], v[40:41]
	v_rcp_f32_e32 v22, v22
	v_rcp_f32_e32 v23, v23
	v_add_f32_e32 v26, 1.0, v26
	v_add_f32_e32 v27, 1.0, v27
	v_pk_add_f32 v[28:29], v[28:29], v[116:117]
	v_pk_add_f32 v[32:33], v[32:33], v[44:45]
	v_rcp_f32_e32 v26, v26
	v_rcp_f32_e32 v27, v27
	v_pk_add_f32 v[28:29], v[28:29], v[120:121]
	v_pk_add_f32 v[32:33], v[32:33], v[48:49]
	v_mov_b32_e32 v24, v28
	v_mov_b32_e32 v25, v32
	v_pk_mul_f32 v[22:23], v[24:25], v[22:23]
	v_mov_b32_e32 v32, v29
	v_add_f32_e32 v24, v22, v23
	v_pk_mul_f32 v[22:23], v[32:33], v[26:27]
	v_add_co_u32_e32 v36, vcc, s1, v16
	v_add_f32_e32 v23, v22, v23
	v_cvt_pk_bf16_f32 v22, v34, v30
	s_nop 0
	v_addc_co_u32_e32 v37, vcc, 0, v17, vcc
	s_mov_b32 s1, 0x403000
	v_cvt_pk_bf16_f32 v23, v24, v23
	global_store_dwordx2 v[0:1], v[22:23], off offset:1536
	v_add_co_u32_e32 v22, vcc, s1, v16
	s_mov_b32 s1, 0x802000
	s_nop 0
	v_addc_co_u32_e32 v23, vcc, 0, v17, vcc
	v_add_co_u32_e32 v38, vcc, s1, v16
	s_mov_b32 s1, 0x803000
	s_nop 0
	v_addc_co_u32_e32 v39, vcc, 0, v17, vcc
	v_add_co_u32_e32 v24, vcc, s1, v16
	s_mov_b32 s1, 0xc02000
	s_nop 0
	v_addc_co_u32_e32 v25, vcc, 0, v17, vcc
	v_add_co_u32_e32 v40, vcc, s1, v16
	s_mov_b32 s1, 0xc03000
	s_nop 0
	v_addc_co_u32_e32 v41, vcc, 0, v17, vcc
	v_add_co_u32_e32 v26, vcc, s1, v16
	s_mov_b32 s1, 0x1002000
	s_nop 0
	v_addc_co_u32_e32 v27, vcc, 0, v17, vcc
	v_add_co_u32_e32 v42, vcc, s1, v16
	s_mov_b32 s1, 0x1003000
	s_nop 0
	v_addc_co_u32_e32 v43, vcc, 0, v17, vcc
	v_add_co_u32_e32 v28, vcc, s1, v16
	s_mov_b32 s1, 0x1402000
	s_nop 0
	v_addc_co_u32_e32 v29, vcc, 0, v17, vcc
	v_add_co_u32_e32 v44, vcc, s1, v16
	s_mov_b32 s1, 0x1403000
	s_nop 0
	v_addc_co_u32_e32 v45, vcc, 0, v17, vcc
	v_add_co_u32_e32 v30, vcc, s1, v16
	global_load_dwordx4 v[54:57], v[20:21], off
	s_nop 0
	v_addc_co_u32_e32 v31, vcc, 0, v17, vcc
	s_mov_b32 s1, 0x1802000
	v_add_co_u32_e32 v46, vcc, s1, v16
	global_load_dwordx4 v[58:61], v[20:21], off offset:512
	global_load_dwordx4 v[62:65], v[22:23], off offset:-4096
	global_load_dwordx4 v[66:69], v[36:37], off offset:512
	v_addc_co_u32_e32 v47, vcc, 0, v17, vcc
	s_mov_b32 s1, 0x1803000
	v_add_co_u32_e32 v32, vcc, s1, v16
	global_load_dwordx4 v[70:73], v[24:25], off offset:-4096
	global_load_dwordx4 v[74:77], v[26:27], off offset:-4096
	global_load_dwordx4 v[78:81], v[38:39], off offset:512
	global_load_dwordx4 v[82:85], v[40:41], off offset:512
	v_addc_co_u32_e32 v33, vcc, 0, v17, vcc
	s_mov_b32 s1, 0x1c02000
	v_add_co_u32_e32 v48, vcc, s1, v16
	global_load_dwordx4 v[86:89], v[28:29], off offset:-4096
	global_load_dwordx4 v[90:93], v[30:31], off offset:-4096
	global_load_dwordx4 v[94:97], v[42:43], off offset:512
	global_load_dwordx4 v[98:101], v[44:45], off offset:512
	v_addc_co_u32_e32 v49, vcc, 0, v17, vcc
	s_mov_b32 s1, 0x1c03000
	v_add_co_u32_e32 v34, vcc, s1, v16
	s_waitcnt vmcnt(0)
; DI unsigned cvt_pk_bf16(float lo, float hi) { unsigned r; asm volatile("v_cvt_pk_bf16_f32 %0, %1, %2" : "=v"(r) : "v"(lo), "v"(hi)); return r; }
; DI float sigmoidf_(float x) { return __builtin_amdgcn_rcpf(1.0f + __builtin_amdgcn_exp2f(-x * LOG2E)); }
; __global__ void __launch_bounds__(512) mk_fwd(Params p) {
;     ...
;                 for (int i = 0; i < 8; ++i) {
;                     const int col = i * 256 + lane * 4, gcol = 256 * (col >> 7) + (col & 127);
;                     f32x4 a1 = {0.f, 0.f, 0.f, 0.f}, a2 = a1, ga = a1, gb = a1;
;                     for (int ks = 0; ks < 4; ++ks) { a1 += *(const f32x4*)(pa + (size_t)ks * 256 * DM + i * 256); a2 += *(const f32x4*)(pa + (size_t)(ks + 4) * 256 * DM + i * 256); }
;                     for (int ks = 0; ks < 8; ++ks) { ga += *(const f32x4*)(pg + (size_t)ks * 256 * 4096 + gcol); gb += *(const f32x4*)(pg + (size_t)ks * 256 * 4096 + gcol + 128); }
;                     f32x4 o;
; #pragma unroll
;                     for (int j = 0; j < 4; ++j) o[j] = sigmoidf_(ga[j] * rg) * a1[j] + sigmoidf_(gb[j] * rg) * a2[j];
;                     u32x2 w; w.x = cvt_pk_bf16(o[0], o[1]); w.y = cvt_pk_bf16(o[2], o[3]);
;                     *(u32x2*)(T + (size_t)(RP + gw) * DM + i * 256 + lane * 4) = w;
;                 }
	v_pk_add_f32 v[54:55], v[54:55], 0 op_sel_hi:[1,0]
	v_addc_co_u32_e32 v35, vcc, 0, v17, vcc
	global_load_dwordx4 v[102:105], v[32:33], off offset:-4096
	global_load_dwordx4 v[106:109], v[34:35], off offset:-4096
	global_load_dwordx4 v[110:113], v[46:47], off offset:512
	global_load_dwordx4 v[114:117], v[48:49], off offset:512
	v_add_co_u32_e32 v18, vcc, s0, v18
	v_pk_add_f32 v[58:59], v[58:59], 0 op_sel_hi:[1,0]
	s_nop 0
	v_addc_co_u32_e32 v19, vcc, 0, v19, vcc
	global_load_dwordx4 v[118:121], v[18:19], off
	global_load_dwordx4 v[122:125], v[2:3], off
	global_load_dwordx4 v[126:129], v[6:7], off
	global_load_dwordx4 v[130:133], v[4:5], off
	global_load_dwordx4 v[134:137], v[8:9], off
	global_load_dwordx4 v[138:141], v[10:11], off
	global_load_dwordx4 v[142:145], v[12:13], off
	global_load_dwordx4 v[146:149], v[14:15], off
	v_pk_add_f32 v[54:55], v[54:55], v[62:63]
	v_pk_add_f32 v[58:59], v[58:59], v[66:67]
	v_pk_add_f32 v[54:55], v[54:55], v[70:71]
	v_pk_add_f32 v[58:59], v[58:59], v[78:79]
	v_pk_add_f32 v[54:55], v[54:55], v[74:75]
	v_pk_add_f32 v[58:59], v[58:59], v[82:83]
	v_pk_add_f32 v[54:55], v[54:55], v[86:87]
	v_pk_add_f32 v[58:59], v[58:59], v[94:95]
	v_pk_add_f32 v[54:55], v[54:55], v[90:91]
	v_pk_add_f32 v[58:59], v[58:59], v[98:99]
	v_pk_add_f32 v[50:51], v[56:57], 0 op_sel_hi:[1,0]
	v_pk_add_f32 v[56:57], v[60:61], 0 op_sel_hi:[1,0]
	v_pk_add_f32 v[50:51], v[50:51], v[64:65]
	v_pk_add_f32 v[56:57], v[56:57], v[68:69]
	v_pk_add_f32 v[50:51], v[50:51], v[72:73]
	v_pk_add_f32 v[56:57], v[56:57], v[80:81]
	v_pk_add_f32 v[50:51], v[50:51], v[76:77]
	v_pk_add_f32 v[56:57], v[56:57], v[84:85]
	v_pk_add_f32 v[50:51], v[50:51], v[88:89]
	v_pk_add_f32 v[56:57], v[56:57], v[96:97]
	v_pk_add_f32 v[50:51], v[50:51], v[92:93]
	v_pk_add_f32 v[56:57], v[56:57], v[100:101]
	s_movk_i32 s0, 0x3000
	v_add_co_u32_e32 v16, vcc, s0, v16
	s_waitcnt vmcnt(0)
	v_pk_add_f32 v[54:55], v[54:55], v[102:103]
	s_nop 0
	v_pk_add_f32 v[54:55], v[54:55], v[106:107]
	v_pk_add_f32 v[58:59], v[58:59], v[110:111]
	v_mul_f32_e32 v53, v52, v54
	v_pk_add_f32 v[58:59], v[58:59], v[114:115]
	v_mul_f32_e32 v53, 0xbfb8aa3b, v53
	v_mul_f32_e32 v54, v52, v58
	v_exp_f32_e32 v53, v53
	v_mul_f32_e32 v54, 0xbfb8aa3b, v54
	v_exp_f32_e32 v54, v54
	v_pk_add_f32 v[50:51], v[50:51], v[104:105]
	v_add_f32_e32 v53, 1.0, v53
	v_rcp_f32_e32 v68, v53
	v_add_f32_e32 v53, 1.0, v54
	v_rcp_f32_e32 v69, v53
	v_mul_f32_e32 v53, v52, v55
	v_mul_f32_e32 v53, 0xbfb8aa3b, v53
	v_mul_f32_e32 v55, v52, v59
	v_exp_f32_e32 v53, v53
	v_mul_f32_e32 v55, 0xbfb8aa3b, v55
	v_exp_f32_e32 v59, v55
	v_pk_add_f32 v[56:57], v[56:57], v[112:113]
	v_pk_add_f32 v[50:51], v[50:51], v[108:109]
	v_pk_add_f32 v[56:57], v[56:57], v[116:117]
	v_pk_add_f32 v[62:63], v[118:119], 0 op_sel_hi:[1,0]
	v_pk_add_f32 v[66:67], v[122:123], 0 op_sel_hi:[1,0]
	v_add_f32_e32 v53, 1.0, v53
	v_mul_f32_e32 v50, v52, v50
	v_pk_add_f32 v[62:63], v[62:63], v[126:127]
	v_pk_add_f32 v[66:67], v[66:67], v[130:131]
	v_rcp_f32_e32 v58, v53
	v_add_f32_e32 v53, 1.0, v59
	v_mul_f32_e32 v50, 0xbfb8aa3b, v50
	v_mul_f32_e32 v56, v52, v56
	v_pk_add_f32 v[62:63], v[62:63], v[134:135]
	v_pk_add_f32 v[66:67], v[66:67], v[138:139]
	v_rcp_f32_e32 v59, v53
	v_exp_f32_e32 v50, v50
	v_mul_f32_e32 v56, 0xbfb8aa3b, v56
	v_pk_add_f32 v[62:63], v[62:63], v[142:143]
	v_pk_add_f32 v[66:67], v[66:67], v[146:147]
	v_exp_f32_e32 v56, v56
	v_mov_b32_e32 v54, v62
	v_mov_b32_e32 v55, v66
	v_pk_mul_f32 v[54:55], v[54:55], v[68:69]
	v_mov_b32_e32 v66, v63
	v_mul_f32_e32 v51, v52, v51
	v_add_f32_e32 v53, v54, v55
	v_pk_mul_f32 v[54:55], v[66:67], v[58:59]
	v_add_f32_e32 v50, 1.0, v50
	v_mul_f32_e32 v51, 0xbfb8aa3b, v51
	v_add_f32_e32 v58, v54, v55
	v_rcp_f32_e32 v54, v50
	v_add_f32_e32 v50, 1.0, v56
	v_exp_f32_e32 v56, v51
	v_mul_f32_e32 v51, v52, v57
	v_mul_f32_e32 v51, 0xbfb8aa3b, v51
	v_exp_f32_e32 v57, v51
	v_pk_add_f32 v[60:61], v[120:121], 0 op_sel_hi:[1,0]
	v_pk_add_f32 v[64:65], v[124:125], 0 op_sel_hi:[1,0]
	v_pk_add_f32 v[60:61], v[60:61], v[128:129]
	v_pk_add_f32 v[64:65], v[64:65], v[132:133]
	v_rcp_f32_e32 v55, v50
	v_add_f32_e32 v56, 1.0, v56
	v_add_f32_e32 v57, 1.0, v57
	v_pk_add_f32 v[60:61], v[60:61], v[136:137]
	v_pk_add_f32 v[64:65], v[64:65], v[140:141]
	v_rcp_f32_e32 v56, v56
	v_rcp_f32_e32 v57, v57
	v_pk_add_f32 v[60:61], v[60:61], v[144:145]
	v_pk_add_f32 v[64:65], v[64:65], v[148:149]
	v_mov_b32_e32 v50, v60
	v_mov_b32_e32 v51, v64
	v_pk_mul_f32 v[50:51], v[50:51], v[54:55]
	v_mov_b32_e32 v64, v61
	v_add_f32_e32 v54, v50, v51
	v_pk_mul_f32 v[50:51], v[64:65], v[56:57]
	v_addc_co_u32_e32 v17, vcc, 0, v17, vcc
	v_add_f32_e32 v51, v50, v51
	v_cvt_pk_bf16_f32 v50, v53, v58
	v_cvt_pk_bf16_f32 v51, v54, v51
	global_store_dwordx2 v[0:1], v[50:51], off offset:2048
	global_load_dwordx4 v[54:57], v[20:21], off offset:2048
	global_load_dwordx4 v[58:61], v[20:21], off offset:2560
	global_load_dwordx4 v[62:65], v[36:37], off offset:2048
	global_load_dwordx4 v[66:69], v[36:37], off offset:2560
	global_load_dwordx4 v[70:73], v[38:39], off offset:2048
	global_load_dwordx4 v[74:77], v[38:39], off offset:2560
	global_load_dwordx4 v[78:81], v[40:41], off offset:2048
	global_load_dwordx4 v[82:85], v[40:41], off offset:2560
	global_load_dwordx4 v[86:89], v[42:43], off offset:2048
	global_load_dwordx4 v[90:93], v[42:43], off offset:2560
	global_load_dwordx4 v[94:97], v[44:45], off offset:2048
	global_load_dwordx4 v[98:101], v[44:45], off offset:2560
	global_load_dwordx4 v[102:105], v[46:47], off offset:2048
	global_load_dwordx4 v[106:109], v[46:47], off offset:2560
	global_load_dwordx4 v[110:113], v[48:49], off offset:2048
	global_load_dwordx4 v[36:39], v[48:49], off offset:2560
	global_load_dwordx4 v[40:43], v[18:19], off offset:1024
	s_nop 0
	global_load_dwordx4 v[44:47], v[2:3], off offset:1024
	global_load_dwordx4 v[114:117], v[6:7], off offset:1024
	global_load_dwordx4 v[48:51], v[4:5], off offset:1024
	global_load_dwordx4 v[118:121], v[8:9], off offset:1024
	global_load_dwordx4 v[122:125], v[10:11], off offset:1024
	global_load_dwordx4 v[126:129], v[12:13], off offset:1024
	global_load_dwordx4 v[130:133], v[14:15], off offset:1024
	s_waitcnt vmcnt(0)
; DI unsigned cvt_pk_bf16(float lo, float hi) { unsigned r; asm volatile("v_cvt_pk_bf16_f32 %0, %1, %2" : "=v"(r) : "v"(lo), "v"(hi)); return r; }
; DI float sigmoidf_(float x) { return __builtin_amdgcn_rcpf(1.0f + __builtin_amdgcn_exp2f(-x * LOG2E)); }
; __global__ void __launch_bounds__(512) mk_fwd(Params p) {
;     ...
;                 for (int i = 0; i < 8; ++i) {
;                     const int col = i * 256 + lane * 4, gcol = 256 * (col >> 7) + (col & 127);
;                     f32x4 a1 = {0.f, 0.f, 0.f, 0.f}, a2 = a1, ga = a1, gb = a1;
;                     for (int ks = 0; ks < 4; ++ks) { a1 += *(const f32x4*)(pa + (size_t)ks * 256 * DM + i * 256); a2 += *(const f32x4*)(pa + (size_t)(ks + 4) * 256 * DM + i * 256); }
;                     for (int ks = 0; ks < 8; ++ks) { ga += *(const f32x4*)(pg + (size_t)ks * 256 * 4096 + gcol); gb += *(const f32x4*)(pg + (size_t)ks * 256 * 4096 + gcol + 128); }
;                     f32x4 o;
; #pragma unroll
;                     for (int j = 0; j < 4; ++j) o[j] = sigmoidf_(ga[j] * rg) * a1[j] + sigmoidf_(gb[j] * rg) * a2[j];
;                     u32x2 w; w.x = cvt_pk_bf16(o[0], o[1]); w.y = cvt_pk_bf16(o[2], o[3]);
;                     *(u32x2*)(T + (size_t)(RP + gw) * DM + i * 256 + lane * 4) = w;
;                 }
	v_pk_add_f32 v[54:55], v[54:55], 0 op_sel_hi:[1,0]
	v_pk_add_f32 v[58:59], v[58:59], 0 op_sel_hi:[1,0]
	v_pk_add_f32 v[54:55], v[54:55], v[62:63]
	v_pk_add_f32 v[58:59], v[58:59], v[66:67]
	v_pk_add_f32 v[54:55], v[54:55], v[70:71]
	v_pk_add_f32 v[58:59], v[58:59], v[74:75]
	v_pk_add_f32 v[54:55], v[54:55], v[78:79]
	v_pk_add_f32 v[58:59], v[58:59], v[82:83]
	v_pk_add_f32 v[54:55], v[54:55], v[86:87]
	v_pk_add_f32 v[58:59], v[58:59], v[90:91]
	v_pk_add_f32 v[54:55], v[54:55], v[94:95]
	v_pk_add_f32 v[58:59], v[58:59], v[98:99]
	v_pk_add_f32 v[20:21], v[56:57], 0 op_sel_hi:[1,0]
	v_pk_add_f32 v[58:59], v[58:59], v[106:107]
	v_pk_add_f32 v[54:55], v[54:55], v[102:103]
	v_pk_add_f32 v[56:57], v[60:61], 0 op_sel_hi:[1,0]
	v_pk_add_f32 v[20:21], v[20:21], v[64:65]
	v_pk_add_f32 v[54:55], v[54:55], v[110:111]
	v_pk_add_f32 v[56:57], v[56:57], v[68:69]
	v_pk_add_f32 v[20:21], v[20:21], v[72:73]
	v_pk_add_f32 v[56:57], v[56:57], v[76:77]
	v_pk_add_f32 v[20:21], v[20:21], v[80:81]
	v_pk_add_f32 v[36:37], v[58:59], v[36:37]
	v_pk_add_f32 v[40:41], v[40:41], 0 op_sel_hi:[1,0]
	v_mul_f32_e32 v36, v52, v36
	v_mul_f32_e32 v36, 0xbfb8aa3b, v36
	v_exp_f32_e32 v36, v36
	v_pk_add_f32 v[40:41], v[40:41], v[114:115]
	v_pk_add_f32 v[44:45], v[44:45], 0 op_sel_hi:[1,0]
	v_pk_add_f32 v[40:41], v[40:41], v[118:119]
	v_add_f32_e32 v36, 1.0, v36
	v_pk_add_f32 v[40:41], v[40:41], v[126:127]
	v_pk_add_f32 v[44:45], v[44:45], v[48:49]
	v_mul_f32_e32 v48, v52, v54
	v_rcp_f32_e32 v49, v36
	v_mov_b32_e32 v36, v40
	v_mul_f32_e32 v40, v52, v55
	v_mul_f32_e32 v48, 0xbfb8aa3b, v48
	v_mul_f32_e32 v40, 0xbfb8aa3b, v40
	v_mul_f32_e32 v37, v52, v37
	v_pk_add_f32 v[56:57], v[56:57], v[84:85]
	v_pk_add_f32 v[20:21], v[20:21], v[88:89]
	v_pk_add_f32 v[46:47], v[46:47], 0 op_sel_hi:[1,0]
	v_exp_f32_e32 v48, v48
	v_exp_f32_e32 v40, v40
	v_mul_f32_e32 v37, 0xbfb8aa3b, v37
	v_pk_add_f32 v[56:57], v[56:57], v[92:93]
	v_pk_add_f32 v[20:21], v[20:21], v[96:97]
	v_pk_add_f32 v[46:47], v[46:47], v[50:51]
	v_exp_f32_e32 v51, v37
	v_pk_add_f32 v[56:57], v[56:57], v[100:101]
	v_pk_add_f32 v[20:21], v[20:21], v[104:105]
	v_pk_add_f32 v[56:57], v[56:57], v[108:109]
	v_pk_add_f32 v[20:21], v[20:21], v[112:113]
	v_pk_add_f32 v[38:39], v[56:57], v[38:39]
	v_add_f32_e32 v48, 1.0, v48
	v_add_f32_e32 v40, 1.0, v40
	v_mul_f32_e32 v20, v52, v20
	v_rcp_f32_e32 v48, v48
	v_rcp_f32_e32 v50, v40
	v_add_f32_e32 v40, 1.0, v51
	v_mul_f32_e32 v20, 0xbfb8aa3b, v20
	v_mul_f32_e32 v38, v52, v38
	v_pk_add_f32 v[44:45], v[44:45], v[122:123]
	v_rcp_f32_e32 v51, v40
	v_exp_f32_e32 v20, v20
	v_mul_f32_e32 v38, 0xbfb8aa3b, v38
	v_pk_add_f32 v[44:45], v[44:45], v[130:131]
	v_exp_f32_e32 v38, v38
	v_mov_b32_e32 v37, v44
	v_pk_mul_f32 v[36:37], v[36:37], v[48:49]
	v_mov_b32_e32 v44, v41
	v_mul_f32_e32 v21, v52, v21
	v_add_f32_e32 v40, v36, v37
	v_pk_mul_f32 v[36:37], v[44:45], v[50:51]
	v_add_f32_e32 v20, 1.0, v20
	v_mul_f32_e32 v21, 0xbfb8aa3b, v21
	v_add_f32_e32 v41, v36, v37
	v_rcp_f32_e32 v36, v20
	v_add_f32_e32 v20, 1.0, v38
	v_exp_f32_e32 v38, v21
	v_mul_f32_e32 v21, v52, v39
	v_mul_f32_e32 v21, 0xbfb8aa3b, v21
	v_exp_f32_e32 v39, v21
	v_pk_add_f32 v[42:43], v[42:43], 0 op_sel_hi:[1,0]
	v_rcp_f32_e32 v37, v20
	v_pk_add_f32 v[42:43], v[42:43], v[116:117]
	v_add_f32_e32 v38, 1.0, v38
	v_add_f32_e32 v39, 1.0, v39
	v_pk_add_f32 v[42:43], v[42:43], v[120:121]
	v_pk_add_f32 v[46:47], v[46:47], v[124:125]
	v_rcp_f32_e32 v38, v38
	v_rcp_f32_e32 v39, v39
	v_pk_add_f32 v[42:43], v[42:43], v[128:129]
	v_pk_add_f32 v[46:47], v[46:47], v[132:133]
	v_mov_b32_e32 v20, v42
	v_mov_b32_e32 v21, v46
	v_pk_mul_f32 v[20:21], v[20:21], v[36:37]
	v_mov_b32_e32 v46, v43
	v_add_f32_e32 v36, v20, v21
	v_pk_mul_f32 v[20:21], v[46:47], v[38:39]
	s_nop 0
	v_add_f32_e32 v21, v20, v21
	v_cvt_pk_bf16_f32 v20, v40, v41
	v_cvt_pk_bf16_f32 v21, v36, v21
	global_store_dwordx2 v[0:1], v[20:21], off offset:2560
	global_load_dwordx4 v[36:39], v[16:17], off
	global_load_dwordx4 v[40:43], v[16:17], off offset:512
	global_load_dwordx4 v[44:47], v[22:23], off
	global_load_dwordx4 v[48:51], v[22:23], off offset:512
	global_load_dwordx4 v[54:57], v[24:25], off
	global_load_dwordx4 v[58:61], v[24:25], off offset:512
	global_load_dwordx4 v[62:65], v[26:27], off
	global_load_dwordx4 v[66:69], v[26:27], off offset:512
	global_load_dwordx4 v[70:73], v[28:29], off
	global_load_dwordx4 v[74:77], v[28:29], off offset:512
	global_load_dwordx4 v[78:81], v[30:31], off
	global_load_dwordx4 v[82:85], v[30:31], off offset:512
	global_load_dwordx4 v[86:89], v[32:33], off
	global_load_dwordx4 v[90:93], v[32:33], off offset:512
	global_load_dwordx4 v[94:97], v[34:35], off
	global_load_dwordx4 v[98:101], v[34:35], off offset:512
	global_load_dwordx4 v[102:105], v[18:19], off offset:2048
	global_load_dwordx4 v[106:109], v[2:3], off offset:2048
	global_load_dwordx4 v[110:113], v[6:7], off offset:2048
	global_load_dwordx4 v[114:117], v[4:5], off offset:2048
	global_load_dwordx4 v[118:121], v[8:9], off offset:2048
	global_load_dwordx4 v[122:125], v[10:11], off offset:2048
	global_load_dwordx4 v[126:129], v[12:13], off offset:2048
	global_load_dwordx4 v[130:133], v[14:15], off offset:2048
	s_waitcnt vmcnt(0)
; DI unsigned cvt_pk_bf16(float lo, float hi) { unsigned r; asm volatile("v_cvt_pk_bf16_f32 %0, %1, %2" : "=v"(r) : "v"(lo), "v"(hi)); return r; }
; DI float sigmoidf_(float x) { return __builtin_amdgcn_rcpf(1.0f + __builtin_amdgcn_exp2f(-x * LOG2E)); }
; __global__ void __launch_bounds__(512) mk_fwd(Params p) {
;     ...
;                 for (int i = 0; i < 8; ++i) {
;                     const int col = i * 256 + lane * 4, gcol = 256 * (col >> 7) + (col & 127);
;                     f32x4 a1 = {0.f, 0.f, 0.f, 0.f}, a2 = a1, ga = a1, gb = a1;
;                     for (int ks = 0; ks < 4; ++ks) { a1 += *(const f32x4*)(pa + (size_t)ks * 256 * DM + i * 256); a2 += *(const f32x4*)(pa + (size_t)(ks + 4) * 256 * DM + i * 256); }
;                     for (int ks = 0; ks < 8; ++ks) { ga += *(const f32x4*)(pg + (size_t)ks * 256 * 4096 + gcol); gb += *(const f32x4*)(pg + (size_t)ks * 256 * 4096 + gcol + 128); }
;                     f32x4 o;
; #pragma unroll
;                     for (int j = 0; j < 4; ++j) o[j] = sigmoidf_(ga[j] * rg) * a1[j] + sigmoidf_(gb[j] * rg) * a2[j];
;                     u32x2 w; w.x = cvt_pk_bf16(o[0], o[1]); w.y = cvt_pk_bf16(o[2], o[3]);
;                     *(u32x2*)(T + (size_t)(RP + gw) * DM + i * 256 + lane * 4) = w;
;                 }
	v_pk_add_f32 v[36:37], v[36:37], 0 op_sel_hi:[1,0]
	v_pk_add_f32 v[40:41], v[40:41], 0 op_sel_hi:[1,0]
	v_pk_add_f32 v[36:37], v[36:37], v[44:45]
	v_pk_add_f32 v[40:41], v[40:41], v[48:49]
	v_pk_add_f32 v[36:37], v[36:37], v[54:55]
	v_pk_add_f32 v[40:41], v[40:41], v[58:59]
	v_pk_add_f32 v[36:37], v[36:37], v[62:63]
	v_pk_add_f32 v[40:41], v[40:41], v[66:67]
	v_pk_add_f32 v[36:37], v[36:37], v[70:71]
	v_pk_add_f32 v[40:41], v[40:41], v[74:75]
	v_pk_add_f32 v[36:37], v[36:37], v[78:79]
	v_pk_add_f32 v[40:41], v[40:41], v[82:83]
	v_pk_add_f32 v[36:37], v[36:37], v[86:87]
	v_pk_add_f32 v[40:41], v[40:41], v[90:91]
	v_pk_add_f32 v[36:37], v[36:37], v[94:95]
	v_pk_add_f32 v[40:41], v[40:41], v[98:99]
	v_mul_f32_e32 v36, v52, v36
	v_mul_f32_e32 v36, 0xbfb8aa3b, v36
	v_mul_f32_e32 v40, v52, v40
	v_exp_f32_e32 v36, v36
	v_mul_f32_e32 v40, 0xbfb8aa3b, v40
	v_exp_f32_e32 v40, v40
	v_pk_add_f32 v[20:21], v[38:39], 0 op_sel_hi:[1,0]
	v_pk_add_f32 v[38:39], v[42:43], 0 op_sel_hi:[1,0]
	v_pk_add_f32 v[20:21], v[20:21], v[46:47]
	v_mul_f32_e32 v37, v52, v37
	v_pk_add_f32 v[38:39], v[38:39], v[50:51]
	v_pk_add_f32 v[20:21], v[20:21], v[56:57]
	v_add_f32_e32 v36, 1.0, v36
	v_mul_f32_e32 v37, 0xbfb8aa3b, v37
	v_pk_add_f32 v[38:39], v[38:39], v[60:61]
	v_pk_add_f32 v[20:21], v[20:21], v[64:65]
	v_rcp_f32_e32 v50, v36
	v_add_f32_e32 v36, 1.0, v40
	v_exp_f32_e32 v40, v37
	v_mul_f32_e32 v37, v52, v41
	v_pk_add_f32 v[38:39], v[38:39], v[68:69]
	v_pk_add_f32 v[20:21], v[20:21], v[72:73]
	v_mul_f32_e32 v37, 0xbfb8aa3b, v37
	v_pk_add_f32 v[38:39], v[38:39], v[76:77]
	v_pk_add_f32 v[20:21], v[20:21], v[80:81]
	v_exp_f32_e32 v41, v37
	v_pk_add_f32 v[38:39], v[38:39], v[84:85]
	v_pk_add_f32 v[20:21], v[20:21], v[88:89]
	v_pk_add_f32 v[38:39], v[38:39], v[92:93]
	v_pk_add_f32 v[20:21], v[20:21], v[96:97]
	v_pk_add_f32 v[38:39], v[38:39], v[100:101]
	v_pk_add_f32 v[44:45], v[102:103], 0 op_sel_hi:[1,0]
	v_pk_add_f32 v[48:49], v[106:107], 0 op_sel_hi:[1,0]
	v_mul_f32_e32 v20, v52, v20
	v_pk_add_f32 v[44:45], v[44:45], v[110:111]
	v_pk_add_f32 v[48:49], v[48:49], v[114:115]
	v_rcp_f32_e32 v51, v36
	v_add_f32_e32 v40, 1.0, v40
	v_add_f32_e32 v41, 1.0, v41
	v_mul_f32_e32 v20, 0xbfb8aa3b, v20
	v_mul_f32_e32 v38, v52, v38
	v_pk_add_f32 v[44:45], v[44:45], v[118:119]
	v_pk_add_f32 v[48:49], v[48:49], v[122:123]
	v_rcp_f32_e32 v40, v40
	v_rcp_f32_e32 v41, v41
	v_exp_f32_e32 v20, v20
	v_mul_f32_e32 v38, 0xbfb8aa3b, v38
	v_pk_add_f32 v[44:45], v[44:45], v[126:127]
	v_pk_add_f32 v[48:49], v[48:49], v[130:131]
	v_exp_f32_e32 v38, v38
	v_mov_b32_e32 v36, v44
	v_mov_b32_e32 v37, v48
	v_pk_mul_f32 v[36:37], v[36:37], v[50:51]
	v_mov_b32_e32 v48, v45
	v_mul_f32_e32 v21, v52, v21
	v_add_f32_e32 v44, v36, v37
	v_pk_mul_f32 v[36:37], v[48:49], v[40:41]
	v_add_f32_e32 v20, 1.0, v20
	v_mul_f32_e32 v21, 0xbfb8aa3b, v21
	v_add_f32_e32 v40, v36, v37
	v_rcp_f32_e32 v36, v20
	v_add_f32_e32 v20, 1.0, v38
	v_exp_f32_e32 v38, v21
	v_mul_f32_e32 v21, v52, v39
	v_mul_f32_e32 v21, 0xbfb8aa3b, v21
	v_exp_f32_e32 v39, v21
	v_pk_add_f32 v[42:43], v[104:105], 0 op_sel_hi:[1,0]
	v_pk_add_f32 v[46:47], v[108:109], 0 op_sel_hi:[1,0]
	v_pk_add_f32 v[42:43], v[42:43], v[112:113]
	v_pk_add_f32 v[46:47], v[46:47], v[116:117]
	v_rcp_f32_e32 v37, v20
	v_add_f32_e32 v38, 1.0, v38
	v_add_f32_e32 v39, 1.0, v39
	v_pk_add_f32 v[42:43], v[42:43], v[120:121]
	v_pk_add_f32 v[46:47], v[46:47], v[124:125]
	v_rcp_f32_e32 v38, v38
	v_rcp_f32_e32 v39, v39
	v_pk_add_f32 v[42:43], v[42:43], v[128:129]
	v_pk_add_f32 v[46:47], v[46:47], v[132:133]
	v_mov_b32_e32 v20, v42
	v_mov_b32_e32 v21, v46
	v_pk_mul_f32 v[20:21], v[20:21], v[36:37]
	v_mov_b32_e32 v46, v43
	v_add_f32_e32 v36, v20, v21
	v_pk_mul_f32 v[20:21], v[46:47], v[38:39]
	s_nop 0
	v_add_f32_e32 v21, v20, v21
	v_cvt_pk_bf16_f32 v20, v44, v40
	v_cvt_pk_bf16_f32 v21, v36, v21
	global_store_dwordx2 v[0:1], v[20:21], off offset:3072
	global_load_dwordx4 v[36:39], v[16:17], off offset:2048
	global_load_dwordx4 v[40:43], v[16:17], off offset:2560
	global_load_dwordx4 v[44:47], v[22:23], off offset:2048
	global_load_dwordx4 v[48:51], v[22:23], off offset:2560
	global_load_dwordx4 v[54:57], v[24:25], off offset:2048
	global_load_dwordx4 v[58:61], v[24:25], off offset:2560
	global_load_dwordx4 v[62:65], v[26:27], off offset:2048
	global_load_dwordx4 v[66:69], v[26:27], off offset:2560
	global_load_dwordx4 v[70:73], v[28:29], off offset:2048
	global_load_dwordx4 v[74:77], v[28:29], off offset:2560
	global_load_dwordx4 v[78:81], v[30:31], off offset:2048
	global_load_dwordx4 v[82:85], v[30:31], off offset:2560
	global_load_dwordx4 v[86:89], v[32:33], off offset:2048
	global_load_dwordx4 v[90:93], v[32:33], off offset:2560
	global_load_dwordx4 v[94:97], v[34:35], off offset:2048
	global_load_dwordx4 v[98:101], v[34:35], off offset:2560
	global_load_dwordx4 v[20:23], v[18:19], off offset:3072
	global_load_dwordx4 v[24:27], v[2:3], off offset:3072
	global_load_dwordx4 v[28:31], v[6:7], off offset:3072
	s_nop 0
	global_load_dwordx4 v[32:35], v[4:5], off offset:3072
	global_load_dwordx4 v[102:105], v[8:9], off offset:3072
	global_load_dwordx4 v[106:109], v[10:11], off offset:3072
	global_load_dwordx4 v[110:113], v[12:13], off offset:3072
	s_nop 0
	global_load_dwordx4 v[2:5], v[14:15], off offset:3072
	s_waitcnt vmcnt(0)
; DI unsigned cvt_pk_bf16(float lo, float hi) { unsigned r; asm volatile("v_cvt_pk_bf16_f32 %0, %1, %2" : "=v"(r) : "v"(lo), "v"(hi)); return r; }
; DI float sigmoidf_(float x) { return __builtin_amdgcn_rcpf(1.0f + __builtin_amdgcn_exp2f(-x * LOG2E)); }
; __global__ void __launch_bounds__(512) mk_fwd(Params p) {
;     ...
;                 for (int i = 0; i < 8; ++i) {
;                     const int col = i * 256 + lane * 4, gcol = 256 * (col >> 7) + (col & 127);
;                     f32x4 a1 = {0.f, 0.f, 0.f, 0.f}, a2 = a1, ga = a1, gb = a1;
;                     for (int ks = 0; ks < 4; ++ks) { a1 += *(const f32x4*)(pa + (size_t)ks * 256 * DM + i * 256); a2 += *(const f32x4*)(pa + (size_t)(ks + 4) * 256 * DM + i * 256); }
;                     for (int ks = 0; ks < 8; ++ks) { ga += *(const f32x4*)(pg + (size_t)ks * 256 * 4096 + gcol); gb += *(const f32x4*)(pg + (size_t)ks * 256 * 4096 + gcol + 128); }
;                     f32x4 o;
; #pragma unroll
;                     for (int j = 0; j < 4; ++j) o[j] = sigmoidf_(ga[j] * rg) * a1[j] + sigmoidf_(gb[j] * rg) * a2[j];
;                     u32x2 w; w.x = cvt_pk_bf16(o[0], o[1]); w.y = cvt_pk_bf16(o[2], o[3]);
;                     *(u32x2*)(T + (size_t)(RP + gw) * DM + i * 256 + lane * 4) = w;
;                 }
	v_pk_add_f32 v[8:9], v[36:37], 0 op_sel_hi:[1,0]
	v_pk_add_f32 v[12:13], v[40:41], 0 op_sel_hi:[1,0]
	v_pk_add_f32 v[8:9], v[8:9], v[44:45]
	v_pk_add_f32 v[12:13], v[12:13], v[48:49]
	v_pk_add_f32 v[8:9], v[8:9], v[54:55]
	v_pk_add_f32 v[12:13], v[12:13], v[58:59]
	v_pk_add_f32 v[8:9], v[8:9], v[62:63]
	v_pk_add_f32 v[12:13], v[12:13], v[66:67]
	v_pk_add_f32 v[8:9], v[8:9], v[70:71]
	v_pk_add_f32 v[12:13], v[12:13], v[74:75]
	v_pk_add_f32 v[8:9], v[8:9], v[78:79]
	v_pk_add_f32 v[12:13], v[12:13], v[82:83]
	v_pk_add_f32 v[8:9], v[8:9], v[86:87]
	v_pk_add_f32 v[12:13], v[12:13], v[90:91]
	v_pk_add_f32 v[8:9], v[8:9], v[94:95]
	v_pk_add_f32 v[12:13], v[12:13], v[98:99]
	v_mul_f32_e32 v8, v52, v8
	v_mul_f32_e32 v8, 0xbfb8aa3b, v8
	v_mul_f32_e32 v12, v52, v12
	v_exp_f32_e32 v8, v8
	v_mul_f32_e32 v12, 0xbfb8aa3b, v12
	v_exp_f32_e32 v12, v12
	v_pk_add_f32 v[10:11], v[42:43], 0 op_sel_hi:[1,0]
	v_mul_f32_e32 v9, v52, v9
	v_pk_add_f32 v[10:11], v[10:11], v[50:51]
	v_pk_add_f32 v[18:19], v[26:27], 0 op_sel_hi:[1,0]
	v_add_f32_e32 v8, 1.0, v8
	v_pk_add_f32 v[18:19], v[18:19], v[34:35]
	v_mul_f32_e32 v9, 0xbfb8aa3b, v9
	v_pk_add_f32 v[18:19], v[18:19], v[108:109]
	v_pk_add_f32 v[10:11], v[10:11], v[60:61]
	v_pk_add_f32 v[16:17], v[20:21], 0 op_sel_hi:[1,0]
	v_pk_add_f32 v[20:21], v[24:25], 0 op_sel_hi:[1,0]
	v_pk_add_f32 v[10:11], v[10:11], v[68:69]
	v_pk_add_f32 v[16:17], v[16:17], v[28:29]
	v_pk_add_f32 v[20:21], v[20:21], v[32:33]
	v_pk_add_f32 v[6:7], v[38:39], 0 op_sel_hi:[1,0]
	v_pk_add_f32 v[10:11], v[10:11], v[76:77]
	v_pk_add_f32 v[4:5], v[18:19], v[4:5]
	v_rcp_f32_e32 v18, v8
	v_add_f32_e32 v8, 1.0, v12
	v_exp_f32_e32 v12, v9
	v_mul_f32_e32 v9, v52, v13
	v_rcp_f32_e32 v19, v8
	v_mul_f32_e32 v9, 0xbfb8aa3b, v9
	v_pk_add_f32 v[16:17], v[16:17], v[102:103]
	v_pk_add_f32 v[20:21], v[20:21], v[106:107]
	v_exp_f32_e32 v13, v9
	v_pk_add_f32 v[6:7], v[6:7], v[46:47]
	v_pk_add_f32 v[10:11], v[10:11], v[84:85]
	v_pk_add_f32 v[16:17], v[16:17], v[110:111]
	v_pk_add_f32 v[2:3], v[20:21], v[2:3]
	v_pk_add_f32 v[6:7], v[6:7], v[56:57]
	v_pk_add_f32 v[10:11], v[10:11], v[92:93]
	v_mov_b32_e32 v8, v16
	v_mov_b32_e32 v9, v2
	v_pk_add_f32 v[6:7], v[6:7], v[64:65]
	v_pk_add_f32 v[10:11], v[10:11], v[100:101]
	v_add_f32_e32 v2, 1.0, v12
	v_pk_mul_f32 v[8:9], v[8:9], v[18:19]
	v_pk_add_f32 v[6:7], v[6:7], v[72:73]
	v_rcp_f32_e32 v12, v2
	v_add_f32_e32 v2, 1.0, v13
	v_add_f32_e32 v16, v8, v9
	v_mul_f32_e32 v8, v52, v10
	v_pk_add_f32 v[6:7], v[6:7], v[80:81]
	v_rcp_f32_e32 v13, v2
	v_mul_f32_e32 v8, 0xbfb8aa3b, v8
	v_pk_add_f32 v[6:7], v[6:7], v[88:89]
	v_exp_f32_e32 v8, v8
	v_pk_add_f32 v[6:7], v[6:7], v[96:97]
	v_mov_b32_e32 v2, v17
	v_mul_f32_e32 v7, v52, v7
	v_pk_mul_f32 v[2:3], v[2:3], v[12:13]
	v_mul_f32_e32 v6, v52, v6
	v_mul_f32_e32 v7, 0xbfb8aa3b, v7
	v_mul_f32_e32 v6, 0xbfb8aa3b, v6
	v_add_f32_e32 v10, v2, v3
	v_add_f32_e32 v3, 1.0, v8
	v_exp_f32_e32 v8, v7
	v_mul_f32_e32 v7, v52, v11
	v_exp_f32_e32 v6, v6
	v_mul_f32_e32 v7, 0xbfb8aa3b, v7
	v_exp_f32_e32 v9, v7
	v_pk_add_f32 v[14:15], v[22:23], 0 op_sel_hi:[1,0]
	v_add_f32_e32 v2, 1.0, v6
	v_mov_b32_e32 v7, v4
	v_add_f32_e32 v4, 1.0, v8
	v_pk_add_f32 v[14:15], v[14:15], v[30:31]
	v_rcp_f32_e32 v2, v2
	v_rcp_f32_e32 v3, v3
	v_rcp_f32_e32 v8, v4
	v_add_f32_e32 v4, 1.0, v9
	v_pk_add_f32 v[14:15], v[14:15], v[104:105]
	v_rcp_f32_e32 v9, v4
	v_pk_add_f32 v[14:15], v[14:15], v[112:113]
	s_nop 0
	v_mov_b32_e32 v6, v14
	v_pk_mul_f32 v[2:3], v[6:7], v[2:3]
	v_mov_b32_e32 v4, v15
	v_add_f32_e32 v6, v2, v3
	v_pk_mul_f32 v[2:3], v[4:5], v[8:9]
	s_nop 0
	v_add_f32_e32 v3, v2, v3
	v_cvt_pk_bf16_f32 v2, v16, v10
	v_cvt_pk_bf16_f32 v3, v6, v3
	global_store_dwordx2 v[0:1], v[2:3], off offset:3584
